# speedup vs baseline: 1.0295x; 1.0198x over previous
; DEV int TID() { int t = threadIdx.x; asm volatile("" : "+v"(t)); return t; }
; DEV void gemm_tile(const u16* __restrict__ A, size_t lda, const u16* __restrict__ Bt, size_t ldb, int K,
;                    u16* sA, u16* sB, f32x4 (&acc)[8][4]) {
;   const int tid = TID(), lane = tid & 63, wid = tid >> 6;
;   const int wr = wid >> 1, wc = wid & 1, fr = lane & 15, fq = lane >> 4;
; #pragma unroll
;   for (int mi = 0; mi < 8; ++mi)
; #pragma unroll
;     for (int ni = 0; ni < 4; ++ni) acc[mi][ni] = f32x4{0.f, 0.f, 0.f, 0.f};
;   const int lr = tid >> 2, lc = (tid & 3) * 8;
;   const u16* ap = A + (size_t)lr * lda + lc;
;   const u16* bp = Bt + (size_t)lr * ldb + lc;
;   u32x4 ra[4], rb[2];
;     ...
;   const int nk = K >> 5;
;   const int swz = ((fq ^ ((0 - (fr >> 2)) & 3)) << 3);
;   const u16* sAr = sA + (wr * 128 + fr) * 32 + swz;
;   const u16* sBr = sA + 256 * 32 + (wc * 64 + fr) * 32 + swz;
;   G_LOAD(0)
;   __syncthreads();
;   S_STORE(0)
;   if (nk > 1) G_LOAD(32)
;   __syncthreads();
.LBB0_121:
	s_lshl_b32 s4, s8, 8
	s_ashr_i32 s5, s4, 31
	v_mov_b32_e32 v11, v178
	s_lshl_b32 s14, s9, 7
	s_lshl_b64 s[8:9], s[4:5], 12
	s_add_u32 s6, s64, s8
	v_ashrrev_i32_e32 v36, 2, v11
	v_ashrrev_i32_e32 v37, 31, v36
	s_addc_u32 s7, s65, s9
	v_readlane_b32 s16, v249, 62
	v_lshlrev_b64 v[38:39], 12, v[36:37]
	v_lshlrev_b32_e32 v2, 4, v11
	v_readlane_b32 s17, v249, 63
	v_lshl_add_u64 v[0:1], s[6:7], 0, v[38:39]
	v_and_b32_e32 v156, 48, v2
	s_mov_b32 s5, s17
	v_lshl_add_u64 v[40:41], v[0:1], 0, v[156:157]
	s_mov_b32 s15, 0x40000
	s_add_i32 s16, s14, 0x1200
	v_writelane_b32 v249, s4, 62
	v_add_co_u32_e32 v42, vcc, s15, v40
	s_nop 0
	v_writelane_b32 v249, s5, 63
	s_lshl_b64 s[16:17], s[16:17], 12
	v_addc_co_u32_e32 v43, vcc, 0, v41, vcc
	s_mov_b32 s5, 0x80000
	s_add_u32 s16, s46, s16
	v_add_co_u32_e32 v44, vcc, s5, v40
	s_addc_u32 s17, s47, s17
	s_nop 0
	v_addc_co_u32_e32 v45, vcc, 0, v41, vcc
	s_mov_b32 s5, 0xc0000
	v_lshl_add_u64 v[0:1], s[16:17], 0, v[38:39]
	v_add_co_u32_e32 v46, vcc, s5, v40
	v_lshl_add_u64 v[152:153], v[0:1], 0, v[156:157]
	s_nop 0
	v_addc_co_u32_e32 v47, vcc, 0, v41, vcc
	v_add_co_u32_e32 v48, vcc, s15, v152
	v_addc_co_u32_e32 v49, vcc, 0, v153, vcc
	s_barrier
	v_lshrrev_b32_e32 v37, 4, v11
	v_lshrrev_b32_e32 v50, 2, v11
	v_sub_u32_e32 v50, 0, v50
	v_sub_u32_e32 v53, 0, v37
	v_lshlrev_b32_e32 v51, 6, v11
	v_and_b32_e32 v52, 3, v11
	v_xor_b32_e32 v37, v37, v50
	v_xor_b32_e32 v11, v11, v53
	v_lshlrev_b32_e32 v37, 4, v37
	v_lshlrev_b32_e32 v11, 4, v11
	v_lshl_add_u64 v[38:39], v[38:39], 0, s[8:9]
	v_and_b32_e32 v37, 48, v37
	v_and_b32_e32 v11, 48, v11
	s_movk_i32 s8, 0xe3c0
	v_mov_b32_e32 v0, 0
	v_lshl_or_b32 v38, v52, 4, v38
	v_and_or_b32 v156, v51, s8, v37
	v_lshl_or_b32 v159, v36, 6, v11
	s_movk_i32 s8, 0x13c0
	s_mov_b32 s5, 0
	s_mov_b64 s[6:7], 0
	v_mov_b32_e32 v1, v0
	v_mov_b32_e32 v2, v0
	v_mov_b32_e32 v3, v0
	v_mov_b32_e32 v4, v0
	v_mov_b32_e32 v5, v0
	v_mov_b32_e32 v6, v0
	v_mov_b32_e32 v7, v0
	v_mov_b32_e32 v8, v0
	v_mov_b32_e32 v9, v0
	v_mov_b32_e32 v10, v0
	v_and_or_b32 v158, v51, s8, v37
	v_lshl_add_u64 v[154:155], s[46:47], 0, v[38:39]
	v_mov_b32_e32 v11, v0
	v_mov_b32_e32 v36, v0
	v_mov_b32_e32 v37, v0
	v_mov_b32_e32 v38, v0
	v_mov_b32_e32 v39, v0
	v_mov_b32_e32 v40, v0
	v_mov_b32_e32 v41, v0
	v_mov_b32_e32 v12, v0
	v_mov_b32_e32 v13, v0
	v_mov_b32_e32 v14, v0
	v_mov_b32_e32 v15, v0
	v_mov_b32_e32 v16, v0
	v_mov_b32_e32 v17, v0
	v_mov_b32_e32 v18, v0
	v_mov_b32_e32 v19, v0
	v_mov_b32_e32 v20, v0
	v_mov_b32_e32 v21, v0
	v_mov_b32_e32 v22, v0
	v_mov_b32_e32 v23, v0
	v_mov_b32_e32 v24, v0
	v_mov_b32_e32 v25, v0
	v_mov_b32_e32 v26, v0
	v_mov_b32_e32 v27, v0
	v_mov_b32_e32 v28, v0
	v_mov_b32_e32 v29, v0
	v_mov_b32_e32 v30, v0
	v_mov_b32_e32 v31, v0
	v_mov_b32_e32 v32, v0
	v_mov_b32_e32 v33, v0
	v_mov_b32_e32 v34, v0
	v_mov_b32_e32 v35, v0
	v_mov_b32_e32 v42, v0
	v_mov_b32_e32 v43, v0
	v_mov_b32_e32 v44, v0
	v_mov_b32_e32 v45, v0
	v_mov_b32_e32 v46, v0
	v_mov_b32_e32 v47, v0
	v_mov_b32_e32 v48, v0
	v_mov_b32_e32 v49, v0
	v_mov_b32_e32 v50, v0
	v_mov_b32_e32 v51, v0
	v_mov_b32_e32 v52, v0
	v_mov_b32_e32 v53, v0
	v_mov_b32_e32 v54, v0
	v_mov_b32_e32 v55, v0
	v_mov_b32_e32 v56, v0
	v_mov_b32_e32 v57, v0
	v_mov_b32_e32 v58, v0
	v_mov_b32_e32 v59, v0
	v_mov_b32_e32 v60, v0
	v_mov_b32_e32 v61, v0
	v_mov_b32_e32 v62, v0
	v_mov_b32_e32 v63, v0
	v_mov_b32_e32 v64, v0
	v_mov_b32_e32 v65, v0
	v_mov_b32_e32 v66, v0
	v_mov_b32_e32 v67, v0
	v_mov_b32_e32 v68, v0
	v_mov_b32_e32 v69, v0
	v_mov_b32_e32 v70, v0
	v_mov_b32_e32 v71, v0
	v_mov_b32_e32 v72, v0
	v_mov_b32_e32 v73, v0
	v_mov_b32_e32 v74, v0
	v_mov_b32_e32 v75, v0
	v_mov_b32_e32 v76, v0
	v_mov_b32_e32 v77, v0
	v_mov_b32_e32 v78, v0
	v_mov_b32_e32 v79, v0
	v_mov_b32_e32 v80, v0
	v_mov_b32_e32 v81, v0
	v_mov_b32_e32 v82, v0
	v_mov_b32_e32 v83, v0
	v_mov_b32_e32 v84, v0
	v_mov_b32_e32 v85, v0
	v_mov_b32_e32 v86, v0
	v_mov_b32_e32 v87, v0
	v_mov_b32_e32 v88, v0
	v_mov_b32_e32 v89, v0
	v_mov_b32_e32 v90, v0
	v_mov_b32_e32 v91, v0
	v_mov_b32_e32 v96, v0
	v_mov_b32_e32 v97, v0
	v_mov_b32_e32 v98, v0
	v_mov_b32_e32 v99, v0
	v_mov_b32_e32 v120, v0
	v_mov_b32_e32 v121, v0
	v_mov_b32_e32 v122, v0
	v_mov_b32_e32 v123, v0
	v_mov_b32_e32 v124, v0
	v_mov_b32_e32 v125, v0
	v_mov_b32_e32 v126, v0
	v_mov_b32_e32 v127, v0
	v_mov_b32_e32 v128, v0
	v_mov_b32_e32 v129, v0
	v_mov_b32_e32 v130, v0
	v_mov_b32_e32 v131, v0
	v_mov_b32_e32 v132, v0
	v_mov_b32_e32 v133, v0
	v_mov_b32_e32 v134, v0
	v_mov_b32_e32 v135, v0
	v_mov_b32_e32 v136, v0
	v_mov_b32_e32 v137, v0
	v_mov_b32_e32 v138, v0
	v_mov_b32_e32 v139, v0
	v_mov_b32_e32 v140, v0
	v_mov_b32_e32 v141, v0
	v_mov_b32_e32 v142, v0
	v_mov_b32_e32 v143, v0
	v_mov_b32_e32 v144, v0
	v_mov_b32_e32 v145, v0
	v_mov_b32_e32 v146, v0
	v_mov_b32_e32 v147, v0
	v_mov_b32_e32 v148, v0
	v_mov_b32_e32 v149, v0
	v_mov_b32_e32 v150, v0
	v_mov_b32_e32 v151, v0
	s_mov_b32 s16, 0xa6d0000
	s_mov_b32 s17, 0xa710000
	s_waitcnt lgkmcnt(0)
	s_barrier
; DEV f32x4 mfma16(bf16x8 a, bf16x8 b, f32x4 c) { return __builtin_amdgcn_mfma_f32_16x16x32_bf16(a, b, c, 0, 0, 0); }
; DEV void gemm_tile(const u16* __restrict__ A, size_t lda, const u16* __restrict__ Bt, size_t ldb, int K,
;                    u16* sA, u16* sB, f32x4 (&acc)[8][4]) {
;     ...
;   G_LOAD(0)
;   __syncthreads();
;   S_STORE(0)
;   if (nk > 1) G_LOAD(32)
;   __syncthreads();
;   for (int kt = 0; kt < nk; ++kt) {
;     const int st = kt & 1;
;     if (kt + 1 < nk) S_STORE(st ^ 1)
;     if (kt + 2 < nk) G_LOAD((kt + 2) << 5)
;     {
;       const u16* pa = sAr + st * 12288;
;       const u16* pb = sBr + st * 12288;
;       bf16x8 b[4];
; #pragma unroll
;       for (int ni = 0; ni < 4; ++ni) b[ni] = *(const bf16x8*)(pb + ni * 16 * 32);
; #pragma unroll
;       for (int mh = 0; mh < 2; ++mh) {
;         bf16x8 a[4];
; #pragma unroll
;         for (int mi = 0; mi < 4; ++mi) a[mi] = *(const bf16x8*)(pa + (mh * 64 + mi * 16) * 32);
; #pragma unroll
;         for (int mi = 0; mi < 4; ++mi)
; #pragma unroll
;           for (int ni = 0; ni < 4; ++ni) acc[mh * 4 + mi][ni] = mfma16(a[mi], b[ni], acc[mh * 4 + mi][ni]);
;       }
;     }
;     __syncthreads();
;   }
	v_lshl_add_u64 v[108:109], v[154:155], 0, s[6:7]
	v_add_co_u32_e32 v112, vcc, s16, v108
	s_nop 1
	v_addc_co_u32_e32 v113, vcc, 0, v109, vcc
	v_add_co_u32_e32 v114, vcc, s17, v108
	s_nop 1
	v_addc_co_u32_e32 v115, vcc, 0, v109, vcc
	v_add_co_u32_e32 v172, vcc, s95, v108
	s_nop 1
	v_addc_co_u32_e32 v173, vcc, 0, v109, vcc
	v_add_co_u32_e32 v108, vcc, s74, v108
	v_lshl_add_u64 v[110:111], v[152:153], 0, s[6:7]
	s_nop 1
	v_addc_co_u32_e32 v109, vcc, 0, v109, vcc
	v_add_co_u32_e32 v174, vcc, s15, v110
	s_nop 1
	v_addc_co_u32_e32 v175, vcc, 0, v111, vcc
	v_lshrrev_b32_e32 v228, 4, v178
	v_sub_u32_e32 v228, 0, v228
	v_and_b32_e32 v228, 3, v228
	v_lshlrev_b32_e32 v228, 4, v228
	v_lshrrev_b32_e32 v229, 6, v178
	v_lshlrev_b32_e32 v229, 10, v229
	v_xor_b32_e32 v112, v112, v228
	v_xor_b32_e32 v114, v114, v228
	v_xor_b32_e32 v172, v172, v228
	v_xor_b32_e32 v108, v108, v228
	v_xor_b32_e32 v110, v110, v228
	v_xor_b32_e32 v174, v174, v228
	v_readfirstlane_b32 s5, v229
	s_nop 1
	s_add_i32 s9, s5, 0x6000
	s_add_i32 m0, s9, 0x0
	s_nop 0
	global_load_lds_dwordx4 v[112:113], off
	v_lshl_add_u64 v[112:113], v[112:113], 0, 64
	s_add_i32 m0, s9, 0x1000
	s_nop 0
	global_load_lds_dwordx4 v[114:115], off
	v_lshl_add_u64 v[114:115], v[114:115], 0, 64
	s_add_i32 m0, s9, 0x2000
	s_nop 0
	global_load_lds_dwordx4 v[172:173], off
	v_lshl_add_u64 v[172:173], v[172:173], 0, 64
	s_add_i32 m0, s9, 0x3000
	s_nop 0
	global_load_lds_dwordx4 v[108:109], off
	v_lshl_add_u64 v[108:109], v[108:109], 0, 64
	s_add_i32 m0, s9, 0x4000
	s_nop 0
	global_load_lds_dwordx4 v[110:111], off
	v_lshl_add_u64 v[110:111], v[110:111], 0, 64
	s_add_i32 m0, s9, 0x5000
	s_nop 0
	global_load_lds_dwordx4 v[174:175], off
	v_lshl_add_u64 v[174:175], v[174:175], 0, 64
	s_add_i32 s9, s5, 0xc000
	s_add_i32 m0, s9, 0x0
	s_nop 0
	global_load_lds_dwordx4 v[112:113], off
	v_lshl_add_u64 v[112:113], v[112:113], 0, 64
	s_add_i32 m0, s9, 0x1000
	s_nop 0
	global_load_lds_dwordx4 v[114:115], off
	v_lshl_add_u64 v[114:115], v[114:115], 0, 64
	s_add_i32 m0, s9, 0x2000
	s_nop 0
	global_load_lds_dwordx4 v[172:173], off
	v_lshl_add_u64 v[172:173], v[172:173], 0, 64
	s_add_i32 m0, s9, 0x3000
	s_nop 0
	global_load_lds_dwordx4 v[108:109], off
	v_lshl_add_u64 v[108:109], v[108:109], 0, 64
	s_add_i32 m0, s9, 0x4000
	s_nop 0
	global_load_lds_dwordx4 v[110:111], off
	v_lshl_add_u64 v[110:111], v[110:111], 0, 64
	s_add_i32 m0, s9, 0x5000
	s_nop 0
	global_load_lds_dwordx4 v[174:175], off
	v_lshl_add_u64 v[174:175], v[174:175], 0, 64
	v_and_b32_e32 v230, 63, v178
	v_lshlrev_b32_e32 v230, 4, v230
	s_mov_b32 s8, 0x6000
	s_mov_b32 s9, s5
	s_waitcnt vmcnt(6)
	s_barrier
.LBB0_122:
	v_add_u32_e32 v229, s8, v158
	v_add_u32_e32 v228, s8, v156
	ds_read_b128 v[92:95], v229 offset:16384
	ds_read_b128 v[160:163], v228
	ds_read_b128 v[100:103], v229 offset:17408
	ds_read_b128 v[116:119], v229 offset:18432
	ds_read_b128 v[104:107], v229 offset:19456
	ds_read_b128 v[164:167], v228 offset:1024
	ds_read_b128 v[168:171], v228 offset:2048
	ds_read_b128 v[232:235], v228 offset:3072
	s_waitcnt lgkmcnt(6)
	v_mfma_f32_16x16x32_bf16 v[148:151], v[160:163], v[92:95], v[148:151]
	s_add_i32 m0, s9, 0x0
	s_waitcnt lgkmcnt(5)
	v_mfma_f32_16x16x32_bf16 v[144:147], v[160:163], v[100:103], v[144:147]
	global_load_lds_dwordx4 v[112:113], off
	v_lshl_add_u64 v[112:113], v[112:113], 0, 64
	global_load_dwordx4 v[252:255], v[112:113], off
	v_lshl_add_u64 v[112:113], v[112:113], 0, 64
	s_waitcnt lgkmcnt(4)
	v_mfma_f32_16x16x32_bf16 v[140:143], v[160:163], v[116:119], v[140:143]
	s_add_i32 m0, s9, 0x1000
	s_waitcnt lgkmcnt(3)
	v_mfma_f32_16x16x32_bf16 v[136:139], v[160:163], v[104:107], v[136:139]
	ds_read_b128 v[236:239], v228 offset:4096
	ds_read_b128 v[240:243], v228 offset:5120
	s_waitcnt lgkmcnt(4)
	v_mfma_f32_16x16x32_bf16 v[132:135], v[164:167], v[92:95], v[132:135]
	global_load_lds_dwordx4 v[114:115], off
	v_lshl_add_u64 v[114:115], v[114:115], 0, 64
	global_load_dwordx4 v[208:211], v[114:115], off
	v_lshl_add_u64 v[114:115], v[114:115], 0, 64
	v_mfma_f32_16x16x32_bf16 v[128:131], v[164:167], v[100:103], v[128:131]
	s_add_i32 m0, s9, 0x2000
	v_mfma_f32_16x16x32_bf16 v[124:127], v[164:167], v[116:119], v[124:127]
	global_load_lds_dwordx4 v[172:173], off
	v_lshl_add_u64 v[172:173], v[172:173], 0, 64
	global_load_dwordx4 v[212:215], v[172:173], off
	v_lshl_add_u64 v[172:173], v[172:173], 0, 64
	v_mfma_f32_16x16x32_bf16 v[120:123], v[164:167], v[104:107], v[120:123]
	s_add_i32 m0, s9, 0x3000
	s_waitcnt lgkmcnt(3)
	v_mfma_f32_16x16x32_bf16 v[96:99], v[168:171], v[92:95], v[96:99]
	global_load_lds_dwordx4 v[108:109], off
	v_lshl_add_u64 v[108:109], v[108:109], 0, 64
	global_load_dwordx4 v[216:219], v[108:109], off
	v_lshl_add_u64 v[108:109], v[108:109], 0, 64
	v_mfma_f32_16x16x32_bf16 v[88:91], v[168:171], v[100:103], v[88:91]
	s_add_i32 m0, s9, 0x4000
	v_mfma_f32_16x16x32_bf16 v[84:87], v[168:171], v[116:119], v[84:87]
	global_load_lds_dwordx4 v[110:111], off
	v_lshl_add_u64 v[110:111], v[110:111], 0, 64
	global_load_dwordx4 v[220:223], v[110:111], off
	v_lshl_add_u64 v[110:111], v[110:111], 0, 64
	v_mfma_f32_16x16x32_bf16 v[80:83], v[168:171], v[104:107], v[80:83]
	ds_read_b128 v[244:247], v228 offset:6144
	ds_read_b128 v[160:163], v228 offset:7168
	s_waitcnt lgkmcnt(4)
	v_mfma_f32_16x16x32_bf16 v[76:79], v[232:235], v[92:95], v[76:79]
	s_add_i32 m0, s9, 0x5000
	v_mfma_f32_16x16x32_bf16 v[72:75], v[232:235], v[100:103], v[72:75]
	global_load_lds_dwordx4 v[174:175], off
	v_lshl_add_u64 v[174:175], v[174:175], 0, 64
	global_load_dwordx4 v[224:227], v[174:175], off
	v_lshl_add_u64 v[174:175], v[174:175], 0, 64
	v_mfma_f32_16x16x32_bf16 v[68:71], v[232:235], v[116:119], v[68:71]
	s_add_i32 s9, s8, s5
	s_add_i32 s8, s8, 0x6000
	v_mfma_f32_16x16x32_bf16 v[64:67], v[232:235], v[104:107], v[64:67]
	s_cmp_eq_u32 s8, 0x12000
	s_cselect_b32 s8, 0, s8
	s_waitcnt lgkmcnt(3)
	v_mfma_f32_16x16x32_bf16 v[60:63], v[236:239], v[92:95], v[60:63]
	s_add_u32 s6, s6, 64
	s_addc_u32 s7, s7, 0
	s_cmpk_lg_i32 s6, 0xf80
	v_mfma_f32_16x16x32_bf16 v[56:59], v[236:239], v[100:103], v[56:59]
	v_mfma_f32_16x16x32_bf16 v[52:55], v[236:239], v[116:119], v[52:55]
	v_mfma_f32_16x16x32_bf16 v[48:51], v[236:239], v[104:107], v[48:51]
	s_waitcnt lgkmcnt(2)
	v_mfma_f32_16x16x32_bf16 v[44:47], v[240:243], v[92:95], v[44:47]
	v_mfma_f32_16x16x32_bf16 v[40:43], v[240:243], v[100:103], v[40:43]
	v_mfma_f32_16x16x32_bf16 v[36:39], v[240:243], v[116:119], v[36:39]
	v_mfma_f32_16x16x32_bf16 v[32:35], v[240:243], v[104:107], v[32:35]
	s_waitcnt lgkmcnt(1)
	v_mfma_f32_16x16x32_bf16 v[28:31], v[244:247], v[92:95], v[28:31]
	v_mfma_f32_16x16x32_bf16 v[24:27], v[244:247], v[100:103], v[24:27]
	v_mfma_f32_16x16x32_bf16 v[20:23], v[244:247], v[116:119], v[20:23]
	v_mfma_f32_16x16x32_bf16 v[16:19], v[244:247], v[104:107], v[16:19]
	s_waitcnt lgkmcnt(0)
	s_waitcnt vmcnt(12)
	s_barrier
; DEV f32x4 mfma16(bf16x8 a, bf16x8 b, f32x4 c) { return __builtin_amdgcn_mfma_f32_16x16x32_bf16(a, b, c, 0, 0, 0); }
; DEV void gemm_tile(const u16* __restrict__ A, size_t lda, const u16* __restrict__ Bt, size_t ldb, int K,
;                    u16* sA, u16* sB, f32x4 (&acc)[8][4]) {
;     ...
;   for (int kt = 0; kt < nk; ++kt) {
;     const int st = kt & 1;
;     if (kt + 1 < nk) S_STORE(st ^ 1)
;     if (kt + 2 < nk) G_LOAD((kt + 2) << 5)
;     {
;       const u16* pa = sAr + st * 12288;
;       const u16* pb = sBr + st * 12288;
;       bf16x8 b[4];
; #pragma unroll
;       for (int ni = 0; ni < 4; ++ni) b[ni] = *(const bf16x8*)(pb + ni * 16 * 32);
; #pragma unroll
;       for (int mh = 0; mh < 2; ++mh) {
;         bf16x8 a[4];
; #pragma unroll
;         for (int mi = 0; mi < 4; ++mi) a[mi] = *(const bf16x8*)(pa + (mh * 64 + mi * 16) * 32);
; #pragma unroll
;         for (int mi = 0; mi < 4; ++mi)
; #pragma unroll
;           for (int ni = 0; ni < 4; ++ni) acc[mh * 4 + mi][ni] = mfma16(a[mi], b[ni], acc[mh * 4 + mi][ni]);
;       }
;     }
;     __syncthreads();
;   }
	v_mfma_f32_16x16x32_bf16 v[12:15], v[160:163], v[92:95], v[12:15]
	v_mfma_f32_16x16x32_bf16 v[8:11], v[160:163], v[100:103], v[8:11]
	v_mfma_f32_16x16x32_bf16 v[4:7], v[160:163], v[116:119], v[4:7]
	v_mfma_f32_16x16x32_bf16 v[0:3], v[160:163], v[104:107], v[0:3]
	v_add_u32_e32 v229, s8, v158
	v_add_u32_e32 v228, s8, v156
	ds_read_b128 v[92:95], v229 offset:16384
	ds_read_b128 v[160:163], v228
	ds_read_b128 v[100:103], v229 offset:17408
	ds_read_b128 v[116:119], v229 offset:18432
	ds_read_b128 v[104:107], v229 offset:19456
	ds_read_b128 v[164:167], v228 offset:1024
	ds_read_b128 v[168:171], v228 offset:2048
	ds_read_b128 v[232:235], v228 offset:3072
	s_waitcnt lgkmcnt(6)
	v_mfma_f32_16x16x32_bf16 v[148:151], v[160:163], v[92:95], v[148:151]
	s_waitcnt vmcnt(0)
	v_add_u32_e32 v231, s9, v230
	s_waitcnt lgkmcnt(5)
	v_mfma_f32_16x16x32_bf16 v[144:147], v[160:163], v[100:103], v[144:147]
	ds_write_b128 v231, v[252:255]
	s_waitcnt lgkmcnt(5)
	v_mfma_f32_16x16x32_bf16 v[140:143], v[160:163], v[116:119], v[140:143]
	ds_write_b128 v231, v[208:211] offset:4096
	s_waitcnt lgkmcnt(5)
	v_mfma_f32_16x16x32_bf16 v[136:139], v[160:163], v[104:107], v[136:139]
	ds_read_b128 v[236:239], v228 offset:4096
	ds_read_b128 v[240:243], v228 offset:5120
	s_waitcnt lgkmcnt(6)
	v_mfma_f32_16x16x32_bf16 v[132:135], v[164:167], v[92:95], v[132:135]
	ds_write_b128 v231, v[212:215] offset:8192
	v_mfma_f32_16x16x32_bf16 v[128:131], v[164:167], v[100:103], v[128:131]
	ds_write_b128 v231, v[216:219] offset:12288
	v_mfma_f32_16x16x32_bf16 v[124:127], v[164:167], v[116:119], v[124:127]
	ds_write_b128 v231, v[220:223] offset:16384
	v_mfma_f32_16x16x32_bf16 v[120:123], v[164:167], v[104:107], v[120:123]
	ds_write_b128 v231, v[224:227] offset:20480
	s_waitcnt lgkmcnt(9)
	v_mfma_f32_16x16x32_bf16 v[96:99], v[168:171], v[92:95], v[96:99]
	s_add_i32 s9, s8, s5
	s_add_i32 s8, s8, 0x6000
	v_mfma_f32_16x16x32_bf16 v[88:91], v[168:171], v[100:103], v[88:91]
	s_cmp_eq_u32 s8, 0x12000
	s_cselect_b32 s8, 0, s8
	v_mfma_f32_16x16x32_bf16 v[84:87], v[168:171], v[116:119], v[84:87]
	s_add_u32 s6, s6, 64
	s_addc_u32 s7, s7, 0
	s_cmpk_lg_i32 s6, 0xf80
	v_mfma_f32_16x16x32_bf16 v[80:83], v[168:171], v[104:107], v[80:83]
	ds_read_b128 v[244:247], v228 offset:6144
	ds_read_b128 v[160:163], v228 offset:7168
	s_waitcnt lgkmcnt(10)
	v_mfma_f32_16x16x32_bf16 v[76:79], v[232:235], v[92:95], v[76:79]
	v_mfma_f32_16x16x32_bf16 v[72:75], v[232:235], v[100:103], v[72:75]
	v_mfma_f32_16x16x32_bf16 v[68:71], v[232:235], v[116:119], v[68:71]
	v_mfma_f32_16x16x32_bf16 v[64:67], v[232:235], v[104:107], v[64:67]
	s_waitcnt lgkmcnt(7)
	v_mfma_f32_16x16x32_bf16 v[60:63], v[236:239], v[92:95], v[60:63]
	v_mfma_f32_16x16x32_bf16 v[56:59], v[236:239], v[100:103], v[56:59]
	v_mfma_f32_16x16x32_bf16 v[52:55], v[236:239], v[116:119], v[52:55]
	v_mfma_f32_16x16x32_bf16 v[48:51], v[236:239], v[104:107], v[48:51]
	s_waitcnt lgkmcnt(6)
	v_mfma_f32_16x16x32_bf16 v[44:47], v[240:243], v[92:95], v[44:47]
	v_mfma_f32_16x16x32_bf16 v[40:43], v[240:243], v[100:103], v[40:43]
	v_mfma_f32_16x16x32_bf16 v[36:39], v[240:243], v[116:119], v[36:39]
	v_mfma_f32_16x16x32_bf16 v[32:35], v[240:243], v[104:107], v[32:35]
	s_waitcnt lgkmcnt(1)
	v_mfma_f32_16x16x32_bf16 v[28:31], v[244:247], v[92:95], v[28:31]
	v_mfma_f32_16x16x32_bf16 v[24:27], v[244:247], v[100:103], v[24:27]
	v_mfma_f32_16x16x32_bf16 v[20:23], v[244:247], v[116:119], v[20:23]
	v_mfma_f32_16x16x32_bf16 v[16:19], v[244:247], v[104:107], v[16:19]
	s_waitcnt lgkmcnt(0)
	s_waitcnt lgkmcnt(0)
	s_barrier
	v_mfma_f32_16x16x32_bf16 v[12:15], v[160:163], v[92:95], v[12:15]
	v_mfma_f32_16x16x32_bf16 v[8:11], v[160:163], v[100:103], v[8:11]
	v_mfma_f32_16x16x32_bf16 v[4:7], v[160:163], v[116:119], v[4:7]
	v_mfma_f32_16x16x32_bf16 v[0:3], v[160:163], v[104:107], v[0:3]
	s_cbranch_scc1 .LBB0_122
	ds_read_b128 v[92:95], v158 offset:16384
	ds_read_b128 v[100:103], v158 offset:17408
	ds_read_b128 v[104:107], v158 offset:18432
	ds_read_b128 v[108:111], v158 offset:19456
	ds_read_b128 v[112:115], v156
	ds_read_b128 v[116:119], v156 offset:1024
	ds_read_b128 v[152:155], v156 offset:2048
	ds_read_b128 v[160:163], v156 offset:3072
	s_movk_i32 s5, 0xb49
	s_waitcnt lgkmcnt(3)
	v_mfma_f32_16x16x32_bf16 v[148:151], v[112:115], v[92:95], v[148:151]
	v_mfma_f32_16x16x32_bf16 v[144:147], v[112:115], v[100:103], v[144:147]
	v_mfma_f32_16x16x32_bf16 v[140:143], v[112:115], v[104:107], v[140:143]
	v_mfma_f32_16x16x32_bf16 v[112:115], v[112:115], v[108:111], v[136:139]
	s_waitcnt lgkmcnt(2)
	v_mfma_f32_16x16x32_bf16 v[132:135], v[116:119], v[92:95], v[132:135]
	v_mfma_f32_16x16x32_bf16 v[128:131], v[116:119], v[100:103], v[128:131]
	v_mfma_f32_16x16x32_bf16 v[136:139], v[116:119], v[104:107], v[124:127]
	v_mfma_f32_16x16x32_bf16 v[164:167], v[116:119], v[108:111], v[120:123]
	s_waitcnt lgkmcnt(1)
	v_mfma_f32_16x16x32_bf16 v[168:171], v[152:155], v[92:95], v[96:99]
	s_nop 2
	ds_read_b128 v[96:99], v156 offset:4096
	ds_read_b128 v[116:119], v156 offset:5120
	ds_read_b128 v[120:123], v156 offset:6144
	ds_read_b128 v[124:127], v156 offset:7168
	s_waitcnt lgkmcnt(0)
	s_waitcnt vmcnt(0)
	s_barrier
; DEV int TID() { int t = threadIdx.x; asm volatile("" : "+v"(t)); return t; }
; DEV f32x4 mfma16(bf16x8 a, bf16x8 b, f32x4 c) { return __builtin_amdgcn_mfma_f32_16x16x32_bf16(a, b, c, 0, 0, 0); }
; DEV void gemm_tile(const u16* __restrict__ A, size_t lda, const u16* __restrict__ Bt, size_t ldb, int K,
;                    u16* sA, u16* sB, f32x4 (&acc)[8][4]) {
;     ...
;       for (int ni = 0; ni < 4; ++ni) b[ni] = *(const bf16x8*)(pb + ni * 16 * 32);
; #pragma unroll
;       for (int mh = 0; mh < 2; ++mh) {
;         bf16x8 a[4];
; #pragma unroll
;         for (int mi = 0; mi < 4; ++mi) a[mi] = *(const bf16x8*)(pa + (mh * 64 + mi * 16) * 32);
; #pragma unroll
;         for (int mi = 0; mi < 4; ++mi)
; #pragma unroll
;           for (int ni = 0; ni < 4; ++ni) acc[mh * 4 + mi][ni] = mfma16(a[mi], b[ni], acc[mh * 4 + mi][ni]);
; DEV void store_tile_bf16(const f32x4 (&acc)[8][4], u16* __restrict__ OUT, size_t ld, int m0, int n0, int ncols,
;                          unsigned char* smem) {
;   const int tid = TID(), lane = tid & 63, wid = tid >> 6;
;   const int wr = wid >> 1, wc = wid & 1, fr = lane & 15, fq = lane >> 4;
;   u16* st = (u16*)(smem + wid * 9216);
; #pragma unroll
;   for (int mh = 0; mh < 2; ++mh) {
; #pragma unroll
;     for (int mi = 0; mi < 4; ++mi)
; #pragma unroll
;       for (int ni = 0; ni < 4; ++ni)
; #pragma unroll
;         for (int j = 0; j < 4; ++j) st[(mi * 16 + fq * 4 + j) * 72 + ni * 16 + fr] = f2bf(acc[mh * 4 + mi][ni][j]);
	v_mfma_f32_16x16x32_bf16 v[88:91], v[152:155], v[100:103], v[88:91]
	v_mfma_f32_16x16x32_bf16 v[84:87], v[152:155], v[104:107], v[84:87]
	v_mfma_f32_16x16x32_bf16 v[80:83], v[152:155], v[108:111], v[80:83]
	v_mfma_f32_16x16x32_bf16 v[76:79], v[160:163], v[92:95], v[76:79]
	v_mfma_f32_16x16x32_bf16 v[72:75], v[160:163], v[100:103], v[72:75]
	v_mfma_f32_16x16x32_bf16 v[68:71], v[160:163], v[104:107], v[68:71]
	v_mfma_f32_16x16x32_bf16 v[64:67], v[160:163], v[108:111], v[64:67]
	v_mfma_f32_16x16x32_bf16 v[60:63], v[96:99], v[92:95], v[60:63]
	v_mfma_f32_16x16x32_bf16 v[56:59], v[96:99], v[100:103], v[56:59]
	v_mfma_f32_16x16x32_bf16 v[52:55], v[96:99], v[104:107], v[52:55]
	v_mfma_f32_16x16x32_bf16 v[48:51], v[96:99], v[108:111], v[48:51]
	v_mfma_f32_16x16x32_bf16 v[44:47], v[116:119], v[92:95], v[44:47]
	v_mfma_f32_16x16x32_bf16 v[28:31], v[120:123], v[92:95], v[28:31]
	v_mfma_f32_16x16x32_bf16 v[12:15], v[124:127], v[92:95], v[12:15]
	ds_read_b128 v[152:155], v158 offset:40960
	ds_read_b128 v[160:163], v158 offset:41984
	ds_read_b128 v[172:175], v158 offset:43008
	ds_read_b128 v[192:195], v158 offset:44032
	ds_read_b128 v[92:95], v156 offset:24576
	ds_read_b128 v[96:99], v156 offset:25600
	ds_read_b128 v[196:199], v156 offset:26624
	ds_read_b128 v[200:203], v156 offset:27648
	v_mfma_f32_16x16x32_bf16 v[40:43], v[116:119], v[100:103], v[40:43]
	v_mfma_f32_16x16x32_bf16 v[36:39], v[116:119], v[104:107], v[36:39]
	v_mfma_f32_16x16x32_bf16 v[32:35], v[116:119], v[108:111], v[32:35]
	v_mfma_f32_16x16x32_bf16 v[24:27], v[120:123], v[100:103], v[24:27]
	v_mfma_f32_16x16x32_bf16 v[20:23], v[120:123], v[104:107], v[20:23]
	v_mfma_f32_16x16x32_bf16 v[16:19], v[120:123], v[108:111], v[16:19]
	v_mfma_f32_16x16x32_bf16 v[8:11], v[124:127], v[100:103], v[8:11]
	v_mfma_f32_16x16x32_bf16 v[4:7], v[124:127], v[104:107], v[4:7]
	v_mfma_f32_16x16x32_bf16 v[0:3], v[124:127], v[108:111], v[0:3]
	s_waitcnt lgkmcnt(3)
	v_mfma_f32_16x16x32_bf16 v[116:119], v[92:95], v[172:175], v[140:143]
	s_waitcnt lgkmcnt(2)
	v_mfma_f32_16x16x32_bf16 v[108:111], v[96:99], v[152:155], v[132:135]
	v_mfma_f32_16x16x32_bf16 v[104:107], v[96:99], v[160:163], v[128:131]
	v_mfma_f32_16x16x32_bf16 v[100:103], v[96:99], v[172:175], v[136:139]
	s_nop 1
	ds_read_b128 v[128:131], v156 offset:28672
	ds_read_b128 v[132:135], v156 offset:29696
	ds_read_b128 v[136:139], v156 offset:30720
	ds_read_b128 v[140:143], v156 offset:31744
	s_waitcnt lgkmcnt(0)
	s_barrier
	v_mfma_f32_16x16x32_bf16 v[60:63], v[128:131], v[152:155], v[60:63]
	v_mfma_f32_16x16x32_bf16 v[56:59], v[128:131], v[160:163], v[56:59]
	v_mfma_f32_16x16x32_bf16 v[52:55], v[128:131], v[172:175], v[52:55]
	v_mfma_f32_16x16x32_bf16 v[48:51], v[128:131], v[192:195], v[48:51]
	v_mov_b32_e32 v129, v178
	v_mfma_f32_16x16x32_bf16 v[124:127], v[92:95], v[152:155], v[148:151]
	v_lshrrev_b32_e32 v128, 6, v129
	v_mul_lo_u32 v131, v128, s75
	v_lshrrev_b32_e32 v128, 2, v129
	v_mfma_f32_16x16x32_bf16 v[44:47], v[132:135], v[152:155], v[44:47]
	v_and_b32_e32 v130, 15, v129
	v_lshl_or_b32 v130, v130, 1, v131
	v_mfma_f32_16x16x32_bf16 v[40:43], v[132:135], v[160:163], v[40:43]
	v_mfma_f32_16x16x32_bf16 v[36:39], v[132:135], v[172:175], v[36:39]
	v_mfma_f32_16x16x32_bf16 v[32:35], v[132:135], v[192:195], v[32:35]
	v_lshlrev_b32_e32 v133, 3, v129
	v_and_b32_e32 v132, 12, v128
	v_and_b32_e32 v128, 64, v129
	v_and_b32_e32 v133, 56, v133
	v_or3_b32 v128, v128, s14, v133
	v_lshl_or_b32 v131, v133, 1, v131
	v_bfe_u32 v133, v129, 3, 3
	v_and_b32_e32 v129, 0xffffff80, v129
	v_add_u32_e32 v134, s4, v129
	v_bfe_u32 v135, v124, 16, 1
	s_movk_i32 s4, 0x90
	v_add3_u32 v135, v124, v135, s71
	v_mad_u32_u24 v124, v132, s4, v130
	v_bfe_u32 v130, v125, 16, 1
	v_add3_u32 v125, v125, v130, s71
	v_mfma_f32_16x16x32_bf16 v[120:123], v[92:95], v[160:163], v[144:147]
	ds_write_b16_d16_hi v124, v125 offset:144
	v_bfe_u32 v125, v126, 16, 1
	v_add3_u32 v125, v126, v125, s71
	ds_write_b16_d16_hi v124, v125 offset:288
	v_bfe_u32 v125, v127, 16, 1
	v_add3_u32 v125, v127, v125, s71
	ds_write_b16_d16_hi v124, v125 offset:432
	s_nop 0
	v_bfe_u32 v125, v120, 16, 1
	v_add3_u32 v120, v120, v125, s71
	ds_write_b16_d16_hi v124, v120 offset:32
	v_bfe_u32 v120, v121, 16, 1
	v_add3_u32 v120, v121, v120, s71
	ds_write_b16_d16_hi v124, v120 offset:176
	v_bfe_u32 v120, v122, 16, 1
	v_add3_u32 v120, v122, v120, s71
	ds_write_b16_d16_hi v124, v120 offset:320
	v_bfe_u32 v120, v123, 16, 1
	v_add3_u32 v120, v123, v120, s71
	ds_write_b16_d16_hi v124, v120 offset:464
	v_bfe_u32 v120, v116, 16, 1
	v_add3_u32 v116, v116, v120, s71
	ds_write_b16_d16_hi v124, v116 offset:64
	v_bfe_u32 v116, v117, 16, 1
	v_add3_u32 v116, v117, v116, s71
	v_mfma_f32_16x16x32_bf16 v[112:115], v[92:95], v[192:195], v[112:115]
	ds_write_b16_d16_hi v124, v116 offset:208
	v_bfe_u32 v116, v118, 16, 1
	v_add3_u32 v116, v118, v116, s71
	ds_write_b16_d16_hi v124, v116 offset:352
	v_bfe_u32 v116, v119, 16, 1
	v_add3_u32 v116, v119, v116, s71
	ds_write_b16_d16_hi v124, v116 offset:496
	s_nop 0
	v_bfe_u32 v116, v112, 16, 1
	v_add3_u32 v112, v112, v116, s71
	ds_write_b16_d16_hi v124, v112 offset:96
	v_bfe_u32 v112, v113, 16, 1
	v_add3_u32 v112, v113, v112, s71
	ds_write_b16_d16_hi v124, v112 offset:240
	v_bfe_u32 v112, v114, 16, 1
	v_add3_u32 v112, v114, v112, s71
	ds_write_b16_d16_hi v124, v112 offset:384
	v_bfe_u32 v112, v115, 16, 1
	v_add3_u32 v112, v115, v112, s71
	ds_write_b16_d16_hi v124, v112 offset:528
	v_bfe_u32 v112, v108, 16, 1
	v_add3_u32 v108, v108, v112, s71
	ds_write_b16_d16_hi v124, v108 offset:2304
	v_bfe_u32 v108, v109, 16, 1
	v_add3_u32 v108, v109, v108, s71
	ds_write_b16_d16_hi v124, v108 offset:2448
; DEV void store_tile_bf16(const f32x4 (&acc)[8][4], u16* __restrict__ OUT, size_t ld, int m0, int n0, int ncols,
;                          unsigned char* smem) {
;     ...
; #pragma unroll
;   for (int mh = 0; mh < 2; ++mh) {
; #pragma unroll
;     for (int mi = 0; mi < 4; ++mi)
; #pragma unroll
;       for (int ni = 0; ni < 4; ++ni)
; #pragma unroll
;         for (int j = 0; j < 4; ++j) st[(mi * 16 + fq * 4 + j) * 72 + ni * 16 + fr] = f2bf(acc[mh * 4 + mi][ni][j]);
;     const int chunk = lane & 7;
;     const int c0 = n0 + wc * 64 + chunk * 8;
; #pragma unroll
;     for (int itr = 0; itr < 8; ++itr) {
;       const int rl = (lane >> 3) + 8 * itr;
;       const u32x4 v = *(const u32x4*)(st + rl * 72 + chunk * 8);
;       if (c0 + 8 <= ncols) *(u32x4*)(OUT + (size_t)(m0 + wr * 128 + mh * 64 + rl) * ld + c0) = v;
	v_bfe_u32 v108, v110, 16, 1
	v_add3_u32 v108, v110, v108, s71
	ds_write_b16_d16_hi v124, v108 offset:2592
	v_bfe_u32 v108, v111, 16, 1
	v_add3_u32 v108, v111, v108, s71
	ds_write_b16_d16_hi v124, v108 offset:2736
	v_bfe_u32 v108, v104, 16, 1
	v_add3_u32 v104, v104, v108, s71
	ds_write_b16_d16_hi v124, v104 offset:2336
	v_bfe_u32 v104, v105, 16, 1
	v_add3_u32 v104, v105, v104, s71
	ds_write_b16_d16_hi v124, v104 offset:2480
	v_bfe_u32 v104, v106, 16, 1
	v_add3_u32 v104, v106, v104, s71
	ds_write_b16_d16_hi v124, v104 offset:2624
	v_bfe_u32 v104, v107, 16, 1
	v_add3_u32 v104, v107, v104, s71
	ds_write_b16_d16_hi v124, v104 offset:2768
	v_bfe_u32 v104, v100, 16, 1
	v_add3_u32 v100, v100, v104, s71
	ds_write_b16_d16_hi v124, v100 offset:2368
	v_bfe_u32 v100, v101, 16, 1
	v_add3_u32 v100, v101, v100, s71
	v_mfma_f32_16x16x32_bf16 v[96:99], v[96:99], v[192:195], v[164:167]
	ds_write_b16_d16_hi v124, v100 offset:2512
	v_bfe_u32 v100, v102, 16, 1
	v_add3_u32 v100, v102, v100, s71
	ds_write_b16_d16_hi v124, v100 offset:2656
	v_bfe_u32 v100, v103, 16, 1
	v_add3_u32 v100, v103, v100, s71
	ds_write_b16_d16_hi v124, v100 offset:2800
	s_nop 0
	v_bfe_u32 v100, v96, 16, 1
	v_add3_u32 v96, v96, v100, s71
	ds_write_b16_d16_hi v124, v96 offset:2400
	v_bfe_u32 v96, v97, 16, 1
	v_add3_u32 v96, v97, v96, s71
	v_mfma_f32_16x16x32_bf16 v[92:95], v[196:199], v[152:155], v[168:171]
	ds_write_b16_d16_hi v124, v96 offset:2544
	v_bfe_u32 v96, v98, 16, 1
	v_add3_u32 v96, v98, v96, s71
	ds_write_b16_d16_hi v124, v96 offset:2688
	v_bfe_u32 v96, v99, 16, 1
	v_add3_u32 v96, v99, v96, s71
	ds_write_b16_d16_hi v124, v96 offset:2832
	s_nop 0
	v_bfe_u32 v96, v92, 16, 1
	v_add3_u32 v92, v92, v96, s71
	ds_write_b16_d16_hi v124, v92 offset:4608
	v_bfe_u32 v92, v93, 16, 1
	v_add3_u32 v92, v93, v92, s71
	v_mfma_f32_16x16x32_bf16 v[88:91], v[196:199], v[160:163], v[88:91]
	ds_write_b16_d16_hi v124, v92 offset:4752
	v_bfe_u32 v92, v94, 16, 1
	v_add3_u32 v92, v94, v92, s71
	ds_write_b16_d16_hi v124, v92 offset:4896
	v_bfe_u32 v92, v95, 16, 1
	v_add3_u32 v92, v95, v92, s71
	ds_write_b16_d16_hi v124, v92 offset:5040
	s_nop 0
	v_bfe_u32 v92, v88, 16, 1
	v_add3_u32 v88, v88, v92, s71
	ds_write_b16_d16_hi v124, v88 offset:4640
	v_bfe_u32 v88, v89, 16, 1
	v_add3_u32 v88, v89, v88, s71
	v_mfma_f32_16x16x32_bf16 v[84:87], v[196:199], v[172:175], v[84:87]
	ds_write_b16_d16_hi v124, v88 offset:4784
	v_bfe_u32 v88, v90, 16, 1
	v_add3_u32 v88, v90, v88, s71
	ds_write_b16_d16_hi v124, v88 offset:4928
	v_bfe_u32 v88, v91, 16, 1
	v_add3_u32 v88, v91, v88, s71
	ds_write_b16_d16_hi v124, v88 offset:5072
	s_nop 0
	v_bfe_u32 v88, v84, 16, 1
	v_add3_u32 v84, v84, v88, s71
	ds_write_b16_d16_hi v124, v84 offset:4672
	v_bfe_u32 v84, v85, 16, 1
	v_add3_u32 v84, v85, v84, s71
	v_mfma_f32_16x16x32_bf16 v[80:83], v[196:199], v[192:195], v[80:83]
	ds_write_b16_d16_hi v124, v84 offset:4816
	v_bfe_u32 v84, v86, 16, 1
	v_add3_u32 v84, v86, v84, s71
	ds_write_b16_d16_hi v124, v84 offset:4960
	v_bfe_u32 v84, v87, 16, 1
	v_add3_u32 v84, v87, v84, s71
	ds_write_b16_d16_hi v124, v84 offset:5104
	s_nop 0
	v_bfe_u32 v84, v80, 16, 1
	v_add3_u32 v80, v80, v84, s71
	ds_write_b16_d16_hi v124, v80 offset:4704
	v_bfe_u32 v80, v81, 16, 1
	v_add3_u32 v80, v81, v80, s71
	v_mfma_f32_16x16x32_bf16 v[76:79], v[200:203], v[152:155], v[76:79]
	ds_write_b16_d16_hi v124, v80 offset:4848
	v_bfe_u32 v80, v82, 16, 1
	v_add3_u32 v80, v82, v80, s71
	ds_write_b16_d16_hi v124, v80 offset:4992
	v_bfe_u32 v80, v83, 16, 1
	v_add3_u32 v80, v83, v80, s71
	ds_write_b16_d16_hi v124, v80 offset:5136
	s_nop 0
	v_bfe_u32 v80, v76, 16, 1
	v_add3_u32 v76, v76, v80, s71
	ds_write_b16_d16_hi v124, v76 offset:6912
	v_bfe_u32 v76, v77, 16, 1
	v_add3_u32 v76, v77, v76, s71
	v_mfma_f32_16x16x32_bf16 v[72:75], v[200:203], v[160:163], v[72:75]
	ds_write_b16_d16_hi v124, v76 offset:7056
	v_bfe_u32 v76, v78, 16, 1
	v_add3_u32 v76, v78, v76, s71
	ds_write_b16_d16_hi v124, v76 offset:7200
	v_bfe_u32 v76, v79, 16, 1
	v_add3_u32 v76, v79, v76, s71
	ds_write_b16_d16_hi v124, v76 offset:7344
	s_nop 0
	v_bfe_u32 v76, v72, 16, 1
	v_add3_u32 v72, v72, v76, s71
	ds_write_b16_d16_hi v124, v72 offset:6944
	v_bfe_u32 v72, v73, 16, 1
	v_add3_u32 v72, v73, v72, s71
	v_mfma_f32_16x16x32_bf16 v[68:71], v[200:203], v[172:175], v[68:71]
	ds_write_b16_d16_hi v124, v72 offset:7088
	v_bfe_u32 v72, v74, 16, 1
	v_add3_u32 v72, v74, v72, s71
	ds_write_b16_d16_hi v124, v72 offset:7232
	v_bfe_u32 v72, v75, 16, 1
	v_add3_u32 v72, v75, v72, s71
	ds_write_b16_d16_hi v124, v72 offset:7376
	s_nop 0
	v_bfe_u32 v72, v68, 16, 1
	v_add3_u32 v68, v68, v72, s71
	ds_write_b16_d16_hi v124, v68 offset:6976
	v_bfe_u32 v68, v69, 16, 1
	v_add3_u32 v68, v69, v68, s71
	v_mfma_f32_16x16x32_bf16 v[64:67], v[200:203], v[192:195], v[64:67]
	ds_write_b16_d16_hi v124, v68 offset:7120
	v_bfe_u32 v68, v70, 16, 1
	v_add3_u32 v68, v70, v68, s71
	ds_write_b16_d16_hi v124, v68 offset:7264
	v_bfe_u32 v68, v71, 16, 1
	v_add3_u32 v68, v71, v68, s71
	ds_write_b16_d16_hi v124, v68 offset:7408
	s_nop 0
	v_bfe_u32 v68, v64, 16, 1
	v_add3_u32 v64, v64, v68, s71
	ds_write_b16_d16_hi v124, v64 offset:7008
	v_bfe_u32 v64, v65, 16, 1
	v_add3_u32 v64, v65, v64, s71
	ds_write_b16_d16_hi v124, v64 offset:7152
	v_bfe_u32 v64, v66, 16, 1
	v_mfma_f32_16x16x32_bf16 v[28:31], v[136:139], v[152:155], v[28:31]
	v_add3_u32 v64, v66, v64, s71
	ds_write_b16_d16_hi v124, v64 offset:7296
	v_bfe_u32 v64, v67, 16, 1
	v_mfma_f32_16x16x32_bf16 v[24:27], v[136:139], v[160:163], v[24:27]
	v_ashrrev_i32_e32 v129, 31, v128
	v_add3_u32 v64, v67, v64, s71
	v_cmp_gt_i32_e32 vcc, s5, v128
	v_mfma_f32_16x16x32_bf16 v[20:23], v[136:139], v[172:175], v[20:23]
	v_lshl_add_u64 v[128:129], v[128:129], 1, s[68:69]
	ds_write_b16_d16_hi v124, v64 offset:7440
	v_mad_u32_u24 v65, v133, s4, v131
	v_mfma_f32_16x16x32_bf16 v[16:19], v[136:139], v[192:195], v[16:19]
	v_or_b32_e32 v64, v134, v133
	ds_write_b16_d16_hi v124, v135
	v_mfma_f32_16x16x32_bf16 v[12:15], v[140:143], v[152:155], v[12:15]
	v_mfma_f32_16x16x32_bf16 v[8:11], v[140:143], v[160:163], v[8:11]
	v_mfma_f32_16x16x32_bf16 v[4:7], v[140:143], v[172:175], v[4:7]
	v_mfma_f32_16x16x32_bf16 v[0:3], v[140:143], v[192:195], v[0:3]
	s_and_saveexec_b64 s[4:5], vcc
	s_cbranch_execz .LBB0_125
; DEV void store_tile_bf16(const f32x4 (&acc)[8][4], u16* __restrict__ OUT, size_t ld, int m0, int n0, int ncols,
;                          unsigned char* smem) {
;     ...
;     const int chunk = lane & 7;
;     const int c0 = n0 + wc * 64 + chunk * 8;
; #pragma unroll
;     for (int itr = 0; itr < 8; ++itr) {
;       const int rl = (lane >> 3) + 8 * itr;
;       const u32x4 v = *(const u32x4*)(st + rl * 72 + chunk * 8);
;       if (c0 + 8 <= ncols) *(u32x4*)(OUT + (size_t)(m0 + wr * 128 + mh * 64 + rl) * ld + c0) = v;
	ds_read_b128 v[66:69], v65
	v_mad_i64_i32 v[70:71], s[6:7], v64, s80, v[128:129]
	s_waitcnt lgkmcnt(0)
	global_store_dwordx4 v[70:71], v[66:69], off
	ds_read_b128 v[66:69], v65 offset:1152
	v_or_b32_e32 v70, 8, v64
	v_mad_i64_i32 v[70:71], s[6:7], v70, s80, v[128:129]
	s_waitcnt lgkmcnt(0)
	global_store_dwordx4 v[70:71], v[66:69], off
	ds_read_b128 v[66:69], v65 offset:2304
	v_or_b32_e32 v70, 16, v64
	v_mad_i64_i32 v[70:71], s[6:7], v70, s80, v[128:129]
	s_waitcnt lgkmcnt(0)
	global_store_dwordx4 v[70:71], v[66:69], off
	ds_read_b128 v[66:69], v65 offset:3456
	v_or_b32_e32 v70, 24, v64
	v_mad_i64_i32 v[70:71], s[6:7], v70, s80, v[128:129]
	s_waitcnt lgkmcnt(0)
	global_store_dwordx4 v[70:71], v[66:69], off
	ds_read_b128 v[66:69], v65 offset:4608
	v_or_b32_e32 v70, 32, v64
	v_mad_i64_i32 v[70:71], s[6:7], v70, s80, v[128:129]
	s_waitcnt lgkmcnt(0)
	global_store_dwordx4 v[70:71], v[66:69], off
	ds_read_b128 v[66:69], v65 offset:5760
	v_or_b32_e32 v70, 40, v64
	v_mad_i64_i32 v[70:71], s[6:7], v70, s80, v[128:129]
	s_waitcnt lgkmcnt(0)
	global_store_dwordx4 v[70:71], v[66:69], off
	ds_read_b128 v[66:69], v65 offset:6912
	v_or_b32_e32 v70, 48, v64
	v_mad_i64_i32 v[70:71], s[6:7], v70, s80, v[128:129]
	s_waitcnt lgkmcnt(0)
	global_store_dwordx4 v[70:71], v[66:69], off
	ds_read_b128 v[66:69], v65 offset:8064
	v_or_b32_e32 v70, 56, v64
	v_mad_i64_i32 v[70:71], s[6:7], v70, s80, v[128:129]
	s_waitcnt lgkmcnt(0)
	global_store_dwordx4 v[70:71], v[66:69], off

; DEV int TID() { int t = threadIdx.x; asm volatile("" : "+v"(t)); return t; }
; DEV void gemm_tile(const u16* __restrict__ A, size_t lda, const u16* __restrict__ Bt, size_t ldb, int K,
;                    u16* sA, u16* sB, f32x4 (&acc)[8][4]) {
;   const int tid = TID(), lane = tid & 63, wid = tid >> 6;
;   const int wr = wid >> 1, wc = wid & 1, fr = lane & 15, fq = lane >> 4;
; #pragma unroll
;   for (int mi = 0; mi < 8; ++mi)
; #pragma unroll
;     for (int ni = 0; ni < 4; ++ni) acc[mi][ni] = f32x4{0.f, 0.f, 0.f, 0.f};
;   const int lr = tid >> 2, lc = (tid & 3) * 8;
;   const u16* ap = A + (size_t)lr * lda + lc;
;   const u16* bp = Bt + (size_t)lr * ldb + lc;
;   u32x4 ra[4], rb[2];
;     ...
;   const int nk = K >> 5;
;   const int swz = ((fq ^ ((0 - (fr >> 2)) & 3)) << 3);
;   const u16* sAr = sA + (wr * 128 + fr) * 32 + swz;
;   const u16* sBr = sA + 256 * 32 + (wc * 64 + fr) * 32 + swz;
;   G_LOAD(0)
;   __syncthreads();
;   S_STORE(0)
;   if (nk > 1) G_LOAD(32)
;   __syncthreads();
.LBB0_161:
	s_lshl_b32 s4, s9, 8
	s_ashr_i32 s5, s4, 31
	s_lshl_b32 s6, s8, 7
	s_lshl_b64 s[10:11], s[4:5], 12
	s_add_u32 s8, s64, s10
	v_mov_b32_e32 v11, v178
	s_addc_u32 s9, s65, s11
	s_ashr_i32 s7, s6, 31
	s_lshl_b64 s[16:17], s[6:7], 12
	v_ashrrev_i32_e32 v36, 2, v11
	v_ashrrev_i32_e32 v37, 31, v36
	s_add_u32 s16, s46, s16
	v_lshlrev_b64 v[38:39], 12, v[36:37]
	v_lshlrev_b32_e32 v2, 4, v11
	s_addc_u32 s17, s47, s17
	v_lshl_add_u64 v[0:1], s[8:9], 0, v[38:39]
	v_and_b32_e32 v156, 48, v2
	v_lshl_add_u64 v[40:41], v[0:1], 0, v[156:157]
	v_lshl_add_u64 v[0:1], s[16:17], 0, v[38:39]
	s_mov_b32 s16, 0x40000
	v_add_co_u32_e32 v42, vcc, s16, v40
	s_mov_b32 s5, 0x80000
	s_nop 0
	v_addc_co_u32_e32 v43, vcc, 0, v41, vcc
	v_add_co_u32_e32 v44, vcc, s5, v40
	s_mov_b32 s5, 0xc0000
	s_nop 0
	v_addc_co_u32_e32 v45, vcc, 0, v41, vcc
	v_add_co_u32_e32 v46, vcc, s5, v40
	v_lshl_add_u64 v[152:153], v[0:1], 0, v[156:157]
	s_nop 0
	v_addc_co_u32_e32 v47, vcc, 0, v41, vcc
	v_add_co_u32_e32 v48, vcc, s16, v152
	v_addc_co_u32_e32 v49, vcc, 0, v153, vcc
	s_barrier
	v_lshrrev_b32_e32 v37, 4, v11
	v_lshrrev_b32_e32 v50, 2, v11
	v_sub_u32_e32 v50, 0, v50
	v_sub_u32_e32 v53, 0, v37
	v_lshlrev_b32_e32 v51, 6, v11
	v_and_b32_e32 v52, 3, v11
	v_xor_b32_e32 v37, v37, v50
	v_xor_b32_e32 v11, v11, v53
	v_lshlrev_b32_e32 v37, 4, v37
	v_lshlrev_b32_e32 v11, 4, v11
	v_lshl_add_u64 v[38:39], v[38:39], 0, s[10:11]
	v_and_b32_e32 v37, 48, v37
	v_and_b32_e32 v11, 48, v11
	s_movk_i32 s7, 0xe3c0
	v_mov_b32_e32 v0, 0
	v_lshl_or_b32 v38, v52, 4, v38
	v_and_or_b32 v156, v51, s7, v37
	v_lshl_or_b32 v159, v36, 6, v11
	s_movk_i32 s7, 0x13c0
	s_mov_b32 s5, 0
	s_mov_b64 s[8:9], 0
	v_mov_b32_e32 v1, v0
	v_mov_b32_e32 v2, v0
	v_mov_b32_e32 v3, v0
	v_mov_b32_e32 v4, v0
	v_mov_b32_e32 v5, v0
	v_mov_b32_e32 v6, v0
	v_mov_b32_e32 v7, v0
	v_mov_b32_e32 v8, v0
	v_mov_b32_e32 v9, v0
	v_mov_b32_e32 v10, v0
	v_and_or_b32 v158, v51, s7, v37
	v_lshl_add_u64 v[154:155], s[46:47], 0, v[38:39]
	v_mov_b32_e32 v11, v0
	v_mov_b32_e32 v36, v0
	v_mov_b32_e32 v37, v0
	v_mov_b32_e32 v38, v0
	v_mov_b32_e32 v39, v0
	v_mov_b32_e32 v40, v0
	v_mov_b32_e32 v41, v0
	v_mov_b32_e32 v42, v0
	v_mov_b32_e32 v43, v0
	v_mov_b32_e32 v44, v0
	v_mov_b32_e32 v45, v0
	v_mov_b32_e32 v46, v0
	v_mov_b32_e32 v47, v0
	v_mov_b32_e32 v48, v0
	v_mov_b32_e32 v12, v0
	v_mov_b32_e32 v13, v0
	v_mov_b32_e32 v14, v0
	v_mov_b32_e32 v15, v0
	v_mov_b32_e32 v16, v0
	v_mov_b32_e32 v17, v0
	v_mov_b32_e32 v18, v0
	v_mov_b32_e32 v19, v0
	v_mov_b32_e32 v20, v0
	v_mov_b32_e32 v21, v0
	v_mov_b32_e32 v22, v0
	v_mov_b32_e32 v23, v0
	v_mov_b32_e32 v24, v0
	v_mov_b32_e32 v25, v0
	v_mov_b32_e32 v26, v0
	v_mov_b32_e32 v27, v0
	v_mov_b32_e32 v28, v0
	v_mov_b32_e32 v29, v0
	v_mov_b32_e32 v30, v0
	v_mov_b32_e32 v31, v0
	v_mov_b32_e32 v32, v0
	v_mov_b32_e32 v33, v0
	v_mov_b32_e32 v34, v0
	v_mov_b32_e32 v35, v0
	v_mov_b32_e32 v49, v0
	v_mov_b32_e32 v50, v0
	v_mov_b32_e32 v51, v0
	v_mov_b32_e32 v52, v0
	v_mov_b32_e32 v53, v0
	v_mov_b32_e32 v54, v0
	v_mov_b32_e32 v55, v0
	v_mov_b32_e32 v56, v0
	v_mov_b32_e32 v57, v0
	v_mov_b32_e32 v58, v0
	v_mov_b32_e32 v59, v0
	v_mov_b32_e32 v60, v0
	v_mov_b32_e32 v61, v0
	v_mov_b32_e32 v62, v0
	v_mov_b32_e32 v63, v0
	v_mov_b32_e32 v64, v0
	v_mov_b32_e32 v65, v0
	v_mov_b32_e32 v66, v0
	v_mov_b32_e32 v67, v0
	v_mov_b32_e32 v68, v0
	v_mov_b32_e32 v69, v0
	v_mov_b32_e32 v70, v0
	v_mov_b32_e32 v71, v0
	v_mov_b32_e32 v72, v0
	v_mov_b32_e32 v73, v0
	v_mov_b32_e32 v74, v0
	v_mov_b32_e32 v75, v0
	v_mov_b32_e32 v76, v0
	v_mov_b32_e32 v77, v0
	v_mov_b32_e32 v78, v0
	v_mov_b32_e32 v79, v0
	v_mov_b32_e32 v80, v0
	v_mov_b32_e32 v81, v0
	v_mov_b32_e32 v82, v0
	v_mov_b32_e32 v83, v0
	v_mov_b32_e32 v84, v0
	v_mov_b32_e32 v85, v0
	v_mov_b32_e32 v86, v0
	v_mov_b32_e32 v87, v0
	v_mov_b32_e32 v88, v0
	v_mov_b32_e32 v89, v0
	v_mov_b32_e32 v90, v0
	v_mov_b32_e32 v91, v0
	v_mov_b32_e32 v96, v0
	v_mov_b32_e32 v97, v0
	v_mov_b32_e32 v98, v0
	v_mov_b32_e32 v99, v0
	v_mov_b32_e32 v120, v0
	v_mov_b32_e32 v121, v0
	v_mov_b32_e32 v122, v0
	v_mov_b32_e32 v123, v0
	v_mov_b32_e32 v124, v0
	v_mov_b32_e32 v125, v0
	v_mov_b32_e32 v126, v0
	v_mov_b32_e32 v127, v0
	v_mov_b32_e32 v128, v0
	v_mov_b32_e32 v129, v0
	v_mov_b32_e32 v130, v0
	v_mov_b32_e32 v131, v0
	v_mov_b32_e32 v132, v0
	v_mov_b32_e32 v133, v0
	v_mov_b32_e32 v134, v0
	v_mov_b32_e32 v135, v0
	v_mov_b32_e32 v136, v0
	v_mov_b32_e32 v137, v0
	v_mov_b32_e32 v138, v0
	v_mov_b32_e32 v139, v0
	v_mov_b32_e32 v140, v0
	v_mov_b32_e32 v141, v0
	v_mov_b32_e32 v142, v0
	v_mov_b32_e32 v143, v0
	v_mov_b32_e32 v144, v0
	v_mov_b32_e32 v145, v0
	v_mov_b32_e32 v146, v0
	v_mov_b32_e32 v147, v0
	v_mov_b32_e32 v148, v0
	v_mov_b32_e32 v149, v0
	v_mov_b32_e32 v150, v0
	v_mov_b32_e32 v151, v0
	s_mov_b32 s11, 0xa6d0000
	s_mov_b32 s17, 0xa710000
	s_waitcnt lgkmcnt(0)
	s_barrier
; DEV f32x4 mfma16(bf16x8 a, bf16x8 b, f32x4 c) { return __builtin_amdgcn_mfma_f32_16x16x32_bf16(a, b, c, 0, 0, 0); }
; DEV void gemm_tile(const u16* __restrict__ A, size_t lda, const u16* __restrict__ Bt, size_t ldb, int K,
;                    u16* sA, u16* sB, f32x4 (&acc)[8][4]) {
;     ...
;   G_LOAD(0)
;   __syncthreads();
;   S_STORE(0)
;   if (nk > 1) G_LOAD(32)
;   __syncthreads();
;   for (int kt = 0; kt < nk; ++kt) {
;     const int st = kt & 1;
;     if (kt + 1 < nk) S_STORE(st ^ 1)
;     if (kt + 2 < nk) G_LOAD((kt + 2) << 5)
;     {
;       const u16* pa = sAr + st * 12288;
;       const u16* pb = sBr + st * 12288;
;       bf16x8 b[4];
; #pragma unroll
;       for (int ni = 0; ni < 4; ++ni) b[ni] = *(const bf16x8*)(pb + ni * 16 * 32);
; #pragma unroll
;       for (int mh = 0; mh < 2; ++mh) {
;         bf16x8 a[4];
; #pragma unroll
;         for (int mi = 0; mi < 4; ++mi) a[mi] = *(const bf16x8*)(pa + (mh * 64 + mi * 16) * 32);
; #pragma unroll
;         for (int mi = 0; mi < 4; ++mi)
; #pragma unroll
;           for (int ni = 0; ni < 4; ++ni) acc[mh * 4 + mi][ni] = mfma16(a[mi], b[ni], acc[mh * 4 + mi][ni]);
;       }
;     }
;     __syncthreads();
;   }
	v_lshl_add_u64 v[108:109], v[154:155], 0, s[8:9]
	v_add_co_u32_e32 v112, vcc, s11, v108
	s_nop 1
	v_addc_co_u32_e32 v113, vcc, 0, v109, vcc
	v_add_co_u32_e32 v114, vcc, s17, v108
	s_nop 1
	v_addc_co_u32_e32 v115, vcc, 0, v109, vcc
	v_add_co_u32_e32 v172, vcc, s95, v108
	s_nop 1
	v_addc_co_u32_e32 v173, vcc, 0, v109, vcc
	v_add_co_u32_e32 v108, vcc, s74, v108
	v_lshl_add_u64 v[110:111], v[152:153], 0, s[8:9]
	s_nop 1
	v_addc_co_u32_e32 v109, vcc, 0, v109, vcc
	v_add_co_u32_e32 v174, vcc, s16, v110
	s_nop 1
	v_addc_co_u32_e32 v175, vcc, 0, v111, vcc
	v_lshrrev_b32_e32 v228, 4, v178
	v_sub_u32_e32 v228, 0, v228
	v_and_b32_e32 v228, 3, v228
	v_lshlrev_b32_e32 v228, 4, v228
	v_lshrrev_b32_e32 v229, 6, v178
	v_lshlrev_b32_e32 v229, 10, v229
	v_xor_b32_e32 v112, v112, v228
	v_xor_b32_e32 v114, v114, v228
	v_xor_b32_e32 v172, v172, v228
	v_xor_b32_e32 v108, v108, v228
	v_xor_b32_e32 v110, v110, v228
	v_xor_b32_e32 v174, v174, v228
	v_readfirstlane_b32 s5, v229
	s_nop 1
	s_add_i32 s10, s5, 0x6000
	s_add_i32 m0, s10, 0x0
	s_nop 0
	global_load_lds_dwordx4 v[112:113], off
	v_lshl_add_u64 v[112:113], v[112:113], 0, 64
	s_add_i32 m0, s10, 0x1000
	s_nop 0
	global_load_lds_dwordx4 v[114:115], off
	v_lshl_add_u64 v[114:115], v[114:115], 0, 64
	s_add_i32 m0, s10, 0x2000
	s_nop 0
	global_load_lds_dwordx4 v[172:173], off
	v_lshl_add_u64 v[172:173], v[172:173], 0, 64
	s_add_i32 m0, s10, 0x3000
	s_nop 0
	global_load_lds_dwordx4 v[108:109], off
	v_lshl_add_u64 v[108:109], v[108:109], 0, 64
	s_add_i32 m0, s10, 0x4000
	s_nop 0
	global_load_lds_dwordx4 v[110:111], off
	v_lshl_add_u64 v[110:111], v[110:111], 0, 64
	s_add_i32 m0, s10, 0x5000
	s_nop 0
	global_load_lds_dwordx4 v[174:175], off
	v_lshl_add_u64 v[174:175], v[174:175], 0, 64
	s_add_i32 s10, s5, 0xc000
	s_add_i32 m0, s10, 0x0
	s_nop 0
	global_load_lds_dwordx4 v[112:113], off
	v_lshl_add_u64 v[112:113], v[112:113], 0, 64
	s_add_i32 m0, s10, 0x1000
	s_nop 0
	global_load_lds_dwordx4 v[114:115], off
	v_lshl_add_u64 v[114:115], v[114:115], 0, 64
	s_add_i32 m0, s10, 0x2000
	s_nop 0
	global_load_lds_dwordx4 v[172:173], off
	v_lshl_add_u64 v[172:173], v[172:173], 0, 64
	s_add_i32 m0, s10, 0x3000
	s_nop 0
	global_load_lds_dwordx4 v[108:109], off
	v_lshl_add_u64 v[108:109], v[108:109], 0, 64
	s_add_i32 m0, s10, 0x4000
	s_nop 0
	global_load_lds_dwordx4 v[110:111], off
	v_lshl_add_u64 v[110:111], v[110:111], 0, 64
	s_add_i32 m0, s10, 0x5000
	s_nop 0
	global_load_lds_dwordx4 v[174:175], off
	v_lshl_add_u64 v[174:175], v[174:175], 0, 64
	v_and_b32_e32 v230, 63, v178
	v_lshlrev_b32_e32 v230, 4, v230
	s_mov_b32 s7, 0x6000
	s_mov_b32 s10, s5
	s_waitcnt vmcnt(6)
	s_barrier
.LBB0_162:
	v_add_u32_e32 v229, s7, v158
	v_add_u32_e32 v228, s7, v156
	ds_read_b128 v[92:95], v229 offset:16384
	ds_read_b128 v[160:163], v228
	ds_read_b128 v[100:103], v229 offset:17408
	ds_read_b128 v[116:119], v229 offset:18432
	ds_read_b128 v[104:107], v229 offset:19456
	ds_read_b128 v[164:167], v228 offset:1024
	ds_read_b128 v[168:171], v228 offset:2048
	ds_read_b128 v[232:235], v228 offset:3072
	s_waitcnt lgkmcnt(6)
	v_mfma_f32_16x16x32_bf16 v[148:151], v[160:163], v[92:95], v[148:151]
	s_add_i32 m0, s10, 0x0
	s_waitcnt lgkmcnt(5)
	v_mfma_f32_16x16x32_bf16 v[144:147], v[160:163], v[100:103], v[144:147]
	global_load_lds_dwordx4 v[112:113], off
	v_lshl_add_u64 v[112:113], v[112:113], 0, 64
	global_load_dwordx4 v[252:255], v[112:113], off
	v_lshl_add_u64 v[112:113], v[112:113], 0, 64
	s_waitcnt lgkmcnt(4)
	v_mfma_f32_16x16x32_bf16 v[140:143], v[160:163], v[116:119], v[140:143]
	s_add_i32 m0, s10, 0x1000
	s_waitcnt lgkmcnt(3)
	v_mfma_f32_16x16x32_bf16 v[136:139], v[160:163], v[104:107], v[136:139]
	ds_read_b128 v[236:239], v228 offset:4096
	ds_read_b128 v[240:243], v228 offset:5120
	s_waitcnt lgkmcnt(4)
	v_mfma_f32_16x16x32_bf16 v[132:135], v[164:167], v[92:95], v[132:135]
	global_load_lds_dwordx4 v[114:115], off
	v_lshl_add_u64 v[114:115], v[114:115], 0, 64
	global_load_dwordx4 v[208:211], v[114:115], off
	v_lshl_add_u64 v[114:115], v[114:115], 0, 64
	v_mfma_f32_16x16x32_bf16 v[128:131], v[164:167], v[100:103], v[128:131]
	s_add_i32 m0, s10, 0x2000
	v_mfma_f32_16x16x32_bf16 v[124:127], v[164:167], v[116:119], v[124:127]
	global_load_lds_dwordx4 v[172:173], off
	v_lshl_add_u64 v[172:173], v[172:173], 0, 64
	global_load_dwordx4 v[212:215], v[172:173], off
	v_lshl_add_u64 v[172:173], v[172:173], 0, 64
	v_mfma_f32_16x16x32_bf16 v[120:123], v[164:167], v[104:107], v[120:123]
	s_add_i32 m0, s10, 0x3000
	s_waitcnt lgkmcnt(3)
	v_mfma_f32_16x16x32_bf16 v[96:99], v[168:171], v[92:95], v[96:99]
	global_load_lds_dwordx4 v[108:109], off
	v_lshl_add_u64 v[108:109], v[108:109], 0, 64
	global_load_dwordx4 v[216:219], v[108:109], off
	v_lshl_add_u64 v[108:109], v[108:109], 0, 64
	v_mfma_f32_16x16x32_bf16 v[88:91], v[168:171], v[100:103], v[88:91]
	s_add_i32 m0, s10, 0x4000
	v_mfma_f32_16x16x32_bf16 v[84:87], v[168:171], v[116:119], v[84:87]
	global_load_lds_dwordx4 v[110:111], off
	v_lshl_add_u64 v[110:111], v[110:111], 0, 64
	global_load_dwordx4 v[220:223], v[110:111], off
	v_lshl_add_u64 v[110:111], v[110:111], 0, 64
	v_mfma_f32_16x16x32_bf16 v[80:83], v[168:171], v[104:107], v[80:83]
	ds_read_b128 v[244:247], v228 offset:6144
	ds_read_b128 v[160:163], v228 offset:7168
	s_waitcnt lgkmcnt(4)
	v_mfma_f32_16x16x32_bf16 v[76:79], v[232:235], v[92:95], v[76:79]
	s_add_i32 m0, s10, 0x5000
	v_mfma_f32_16x16x32_bf16 v[72:75], v[232:235], v[100:103], v[72:75]
	global_load_lds_dwordx4 v[174:175], off
	v_lshl_add_u64 v[174:175], v[174:175], 0, 64
	global_load_dwordx4 v[224:227], v[174:175], off
	v_lshl_add_u64 v[174:175], v[174:175], 0, 64
	v_mfma_f32_16x16x32_bf16 v[68:71], v[232:235], v[116:119], v[68:71]
	s_add_i32 s10, s7, s5
	s_add_i32 s7, s7, 0x6000
	v_mfma_f32_16x16x32_bf16 v[64:67], v[232:235], v[104:107], v[64:67]
	s_cmp_eq_u32 s7, 0x12000
	s_cselect_b32 s7, 0, s7
	s_waitcnt lgkmcnt(3)
	v_mfma_f32_16x16x32_bf16 v[60:63], v[236:239], v[92:95], v[60:63]
	s_add_u32 s8, s8, 64
	s_addc_u32 s9, s9, 0
	s_cmpk_lg_i32 s8, 0xf80
	v_mfma_f32_16x16x32_bf16 v[56:59], v[236:239], v[100:103], v[56:59]
	v_mfma_f32_16x16x32_bf16 v[52:55], v[236:239], v[116:119], v[52:55]
	v_mfma_f32_16x16x32_bf16 v[48:51], v[236:239], v[104:107], v[48:51]
	s_waitcnt lgkmcnt(2)
	v_mfma_f32_16x16x32_bf16 v[44:47], v[240:243], v[92:95], v[44:47]
	v_mfma_f32_16x16x32_bf16 v[40:43], v[240:243], v[100:103], v[40:43]
	v_mfma_f32_16x16x32_bf16 v[36:39], v[240:243], v[116:119], v[36:39]
	v_mfma_f32_16x16x32_bf16 v[32:35], v[240:243], v[104:107], v[32:35]
	s_waitcnt lgkmcnt(1)
	v_mfma_f32_16x16x32_bf16 v[28:31], v[244:247], v[92:95], v[28:31]
	v_mfma_f32_16x16x32_bf16 v[24:27], v[244:247], v[100:103], v[24:27]
	v_mfma_f32_16x16x32_bf16 v[20:23], v[244:247], v[116:119], v[20:23]
	v_mfma_f32_16x16x32_bf16 v[16:19], v[244:247], v[104:107], v[16:19]
	s_waitcnt lgkmcnt(0)
	s_waitcnt vmcnt(12)
	s_barrier
; DEV f32x4 mfma16(bf16x8 a, bf16x8 b, f32x4 c) { return __builtin_amdgcn_mfma_f32_16x16x32_bf16(a, b, c, 0, 0, 0); }
; DEV void gemm_tile(const u16* __restrict__ A, size_t lda, const u16* __restrict__ Bt, size_t ldb, int K,
;                    u16* sA, u16* sB, f32x4 (&acc)[8][4]) {
;     ...
;   for (int kt = 0; kt < nk; ++kt) {
;     const int st = kt & 1;
;     if (kt + 1 < nk) S_STORE(st ^ 1)
;     if (kt + 2 < nk) G_LOAD((kt + 2) << 5)
;     {
;       const u16* pa = sAr + st * 12288;
;       const u16* pb = sBr + st * 12288;
;       bf16x8 b[4];
; #pragma unroll
;       for (int ni = 0; ni < 4; ++ni) b[ni] = *(const bf16x8*)(pb + ni * 16 * 32);
; #pragma unroll
;       for (int mh = 0; mh < 2; ++mh) {
;         bf16x8 a[4];
; #pragma unroll
;         for (int mi = 0; mi < 4; ++mi) a[mi] = *(const bf16x8*)(pa + (mh * 64 + mi * 16) * 32);
; #pragma unroll
;         for (int mi = 0; mi < 4; ++mi)
; #pragma unroll
;           for (int ni = 0; ni < 4; ++ni) acc[mh * 4 + mi][ni] = mfma16(a[mi], b[ni], acc[mh * 4 + mi][ni]);
;       }
;     }
;     __syncthreads();
;   }
	v_mfma_f32_16x16x32_bf16 v[12:15], v[160:163], v[92:95], v[12:15]
	v_mfma_f32_16x16x32_bf16 v[8:11], v[160:163], v[100:103], v[8:11]
	v_mfma_f32_16x16x32_bf16 v[4:7], v[160:163], v[116:119], v[4:7]
	v_mfma_f32_16x16x32_bf16 v[0:3], v[160:163], v[104:107], v[0:3]
	v_add_u32_e32 v229, s7, v158
	v_add_u32_e32 v228, s7, v156
	ds_read_b128 v[92:95], v229 offset:16384
	ds_read_b128 v[160:163], v228
	ds_read_b128 v[100:103], v229 offset:17408
	ds_read_b128 v[116:119], v229 offset:18432
	ds_read_b128 v[104:107], v229 offset:19456
	ds_read_b128 v[164:167], v228 offset:1024
	ds_read_b128 v[168:171], v228 offset:2048
	ds_read_b128 v[232:235], v228 offset:3072
	s_waitcnt lgkmcnt(6)
	v_mfma_f32_16x16x32_bf16 v[148:151], v[160:163], v[92:95], v[148:151]
	s_waitcnt vmcnt(0)
	v_add_u32_e32 v231, s10, v230
	s_waitcnt lgkmcnt(5)
	v_mfma_f32_16x16x32_bf16 v[144:147], v[160:163], v[100:103], v[144:147]
	ds_write_b128 v231, v[252:255]
	s_waitcnt lgkmcnt(5)
	v_mfma_f32_16x16x32_bf16 v[140:143], v[160:163], v[116:119], v[140:143]
	ds_write_b128 v231, v[208:211] offset:4096
	s_waitcnt lgkmcnt(5)
	v_mfma_f32_16x16x32_bf16 v[136:139], v[160:163], v[104:107], v[136:139]
	ds_read_b128 v[236:239], v228 offset:4096
	ds_read_b128 v[240:243], v228 offset:5120
	s_waitcnt lgkmcnt(6)
	v_mfma_f32_16x16x32_bf16 v[132:135], v[164:167], v[92:95], v[132:135]
	ds_write_b128 v231, v[212:215] offset:8192
	v_mfma_f32_16x16x32_bf16 v[128:131], v[164:167], v[100:103], v[128:131]
	ds_write_b128 v231, v[216:219] offset:12288
	v_mfma_f32_16x16x32_bf16 v[124:127], v[164:167], v[116:119], v[124:127]
	ds_write_b128 v231, v[220:223] offset:16384
	v_mfma_f32_16x16x32_bf16 v[120:123], v[164:167], v[104:107], v[120:123]
	ds_write_b128 v231, v[224:227] offset:20480
	s_waitcnt lgkmcnt(9)
	v_mfma_f32_16x16x32_bf16 v[96:99], v[168:171], v[92:95], v[96:99]
	s_add_i32 s10, s7, s5
	s_add_i32 s7, s7, 0x6000
	v_mfma_f32_16x16x32_bf16 v[88:91], v[168:171], v[100:103], v[88:91]
	s_cmp_eq_u32 s7, 0x12000
	s_cselect_b32 s7, 0, s7
	v_mfma_f32_16x16x32_bf16 v[84:87], v[168:171], v[116:119], v[84:87]
	s_add_u32 s8, s8, 64
	s_addc_u32 s9, s9, 0
	s_cmpk_lg_i32 s8, 0xf80
	v_mfma_f32_16x16x32_bf16 v[80:83], v[168:171], v[104:107], v[80:83]
	ds_read_b128 v[244:247], v228 offset:6144
	ds_read_b128 v[160:163], v228 offset:7168
	s_waitcnt lgkmcnt(10)
	v_mfma_f32_16x16x32_bf16 v[76:79], v[232:235], v[92:95], v[76:79]
	v_mfma_f32_16x16x32_bf16 v[72:75], v[232:235], v[100:103], v[72:75]
	v_mfma_f32_16x16x32_bf16 v[68:71], v[232:235], v[116:119], v[68:71]
	v_mfma_f32_16x16x32_bf16 v[64:67], v[232:235], v[104:107], v[64:67]
	s_waitcnt lgkmcnt(7)
	v_mfma_f32_16x16x32_bf16 v[60:63], v[236:239], v[92:95], v[60:63]
	v_mfma_f32_16x16x32_bf16 v[56:59], v[236:239], v[100:103], v[56:59]
	v_mfma_f32_16x16x32_bf16 v[52:55], v[236:239], v[116:119], v[52:55]
	v_mfma_f32_16x16x32_bf16 v[48:51], v[236:239], v[104:107], v[48:51]
	s_waitcnt lgkmcnt(6)
	v_mfma_f32_16x16x32_bf16 v[44:47], v[240:243], v[92:95], v[44:47]
	v_mfma_f32_16x16x32_bf16 v[40:43], v[240:243], v[100:103], v[40:43]
	v_mfma_f32_16x16x32_bf16 v[36:39], v[240:243], v[116:119], v[36:39]
	v_mfma_f32_16x16x32_bf16 v[32:35], v[240:243], v[104:107], v[32:35]
	s_waitcnt lgkmcnt(1)
	v_mfma_f32_16x16x32_bf16 v[28:31], v[244:247], v[92:95], v[28:31]
	v_mfma_f32_16x16x32_bf16 v[24:27], v[244:247], v[100:103], v[24:27]
	v_mfma_f32_16x16x32_bf16 v[20:23], v[244:247], v[116:119], v[20:23]
	v_mfma_f32_16x16x32_bf16 v[16:19], v[244:247], v[104:107], v[16:19]
	s_waitcnt lgkmcnt(0)
	s_waitcnt lgkmcnt(0)
	s_barrier
	v_mfma_f32_16x16x32_bf16 v[12:15], v[160:163], v[92:95], v[12:15]
	v_mfma_f32_16x16x32_bf16 v[8:11], v[160:163], v[100:103], v[8:11]
	v_mfma_f32_16x16x32_bf16 v[4:7], v[160:163], v[116:119], v[4:7]
	v_mfma_f32_16x16x32_bf16 v[0:3], v[160:163], v[104:107], v[0:3]
	s_cbranch_scc1 .LBB0_162
	ds_read_b128 v[92:95], v158 offset:16384
	ds_read_b128 v[100:103], v158 offset:17408
	ds_read_b128 v[104:107], v158 offset:18432
	ds_read_b128 v[108:111], v158 offset:19456
	ds_read_b128 v[112:115], v156
	ds_read_b128 v[116:119], v156 offset:1024
	ds_read_b128 v[152:155], v156 offset:2048
	ds_read_b128 v[160:163], v156 offset:3072
	s_movk_i32 s5, 0x11f9
	s_waitcnt lgkmcnt(3)
	v_mfma_f32_16x16x32_bf16 v[148:151], v[112:115], v[92:95], v[148:151]
	v_mfma_f32_16x16x32_bf16 v[144:147], v[112:115], v[100:103], v[144:147]
	v_mfma_f32_16x16x32_bf16 v[140:143], v[112:115], v[104:107], v[140:143]
	v_mfma_f32_16x16x32_bf16 v[112:115], v[112:115], v[108:111], v[136:139]
	s_waitcnt lgkmcnt(2)
	v_mfma_f32_16x16x32_bf16 v[132:135], v[116:119], v[92:95], v[132:135]
	v_mfma_f32_16x16x32_bf16 v[128:131], v[116:119], v[100:103], v[128:131]
	v_mfma_f32_16x16x32_bf16 v[136:139], v[116:119], v[104:107], v[124:127]
	v_mfma_f32_16x16x32_bf16 v[164:167], v[116:119], v[108:111], v[120:123]
	s_waitcnt lgkmcnt(1)
	v_mfma_f32_16x16x32_bf16 v[168:171], v[152:155], v[92:95], v[96:99]
	s_nop 2
	ds_read_b128 v[96:99], v156 offset:4096
	ds_read_b128 v[116:119], v156 offset:5120
	ds_read_b128 v[120:123], v156 offset:6144
	ds_read_b128 v[124:127], v156 offset:7168
	s_waitcnt lgkmcnt(0)
	s_waitcnt vmcnt(0)
	s_barrier
; DEV int TID() { int t = threadIdx.x; asm volatile("" : "+v"(t)); return t; }
; DEV f32x4 mfma16(bf16x8 a, bf16x8 b, f32x4 c) { return __builtin_amdgcn_mfma_f32_16x16x32_bf16(a, b, c, 0, 0, 0); }
; DEV void gemm_tile(const u16* __restrict__ A, size_t lda, const u16* __restrict__ Bt, size_t ldb, int K,
;                    u16* sA, u16* sB, f32x4 (&acc)[8][4]) {
;     ...
;       for (int ni = 0; ni < 4; ++ni) b[ni] = *(const bf16x8*)(pb + ni * 16 * 32);
; #pragma unroll
;       for (int mh = 0; mh < 2; ++mh) {
;         bf16x8 a[4];
; #pragma unroll
;         for (int mi = 0; mi < 4; ++mi) a[mi] = *(const bf16x8*)(pa + (mh * 64 + mi * 16) * 32);
; #pragma unroll
;         for (int mi = 0; mi < 4; ++mi)
; #pragma unroll
;           for (int ni = 0; ni < 4; ++ni) acc[mh * 4 + mi][ni] = mfma16(a[mi], b[ni], acc[mh * 4 + mi][ni]);
; DEV void store_tile_bf16(const f32x4 (&acc)[8][4], u16* __restrict__ OUT, size_t ld, int m0, int n0, int ncols,
;                          unsigned char* smem) {
;   const int tid = TID(), lane = tid & 63, wid = tid >> 6;
;   const int wr = wid >> 1, wc = wid & 1, fr = lane & 15, fq = lane >> 4;
;   u16* st = (u16*)(smem + wid * 9216);
; #pragma unroll
;   for (int mh = 0; mh < 2; ++mh) {
; #pragma unroll
;     for (int mi = 0; mi < 4; ++mi)
; #pragma unroll
;       for (int ni = 0; ni < 4; ++ni)
; #pragma unroll
;         for (int j = 0; j < 4; ++j) st[(mi * 16 + fq * 4 + j) * 72 + ni * 16 + fr] = f2bf(acc[mh * 4 + mi][ni][j]);
	v_mfma_f32_16x16x32_bf16 v[88:91], v[152:155], v[100:103], v[88:91]
	v_mfma_f32_16x16x32_bf16 v[84:87], v[152:155], v[104:107], v[84:87]
	v_mfma_f32_16x16x32_bf16 v[80:83], v[152:155], v[108:111], v[80:83]
	v_mfma_f32_16x16x32_bf16 v[76:79], v[160:163], v[92:95], v[76:79]
	v_mfma_f32_16x16x32_bf16 v[72:75], v[160:163], v[100:103], v[72:75]
	v_mfma_f32_16x16x32_bf16 v[68:71], v[160:163], v[104:107], v[68:71]
	v_mfma_f32_16x16x32_bf16 v[64:67], v[160:163], v[108:111], v[64:67]
	v_mfma_f32_16x16x32_bf16 v[60:63], v[96:99], v[92:95], v[60:63]
	v_mfma_f32_16x16x32_bf16 v[56:59], v[96:99], v[100:103], v[56:59]
	v_mfma_f32_16x16x32_bf16 v[52:55], v[96:99], v[104:107], v[52:55]
	v_mfma_f32_16x16x32_bf16 v[48:51], v[96:99], v[108:111], v[48:51]
	v_mfma_f32_16x16x32_bf16 v[44:47], v[116:119], v[92:95], v[44:47]
	v_mfma_f32_16x16x32_bf16 v[28:31], v[120:123], v[92:95], v[28:31]
	v_mfma_f32_16x16x32_bf16 v[12:15], v[124:127], v[92:95], v[12:15]
	ds_read_b128 v[152:155], v158 offset:40960
	ds_read_b128 v[160:163], v158 offset:41984
	ds_read_b128 v[172:175], v158 offset:43008
	ds_read_b128 v[192:195], v158 offset:44032
	ds_read_b128 v[92:95], v156 offset:24576
	ds_read_b128 v[96:99], v156 offset:25600
	ds_read_b128 v[196:199], v156 offset:26624
	ds_read_b128 v[200:203], v156 offset:27648
	v_mfma_f32_16x16x32_bf16 v[40:43], v[116:119], v[100:103], v[40:43]
	v_mfma_f32_16x16x32_bf16 v[36:39], v[116:119], v[104:107], v[36:39]
	v_mfma_f32_16x16x32_bf16 v[32:35], v[116:119], v[108:111], v[32:35]
	v_mfma_f32_16x16x32_bf16 v[24:27], v[120:123], v[100:103], v[24:27]
	v_mfma_f32_16x16x32_bf16 v[20:23], v[120:123], v[104:107], v[20:23]
	v_mfma_f32_16x16x32_bf16 v[16:19], v[120:123], v[108:111], v[16:19]
	v_mfma_f32_16x16x32_bf16 v[8:11], v[124:127], v[100:103], v[8:11]
	v_mfma_f32_16x16x32_bf16 v[4:7], v[124:127], v[104:107], v[4:7]
	v_mfma_f32_16x16x32_bf16 v[0:3], v[124:127], v[108:111], v[0:3]
	s_waitcnt lgkmcnt(3)
	v_mfma_f32_16x16x32_bf16 v[116:119], v[92:95], v[172:175], v[140:143]
	s_waitcnt lgkmcnt(2)
	v_mfma_f32_16x16x32_bf16 v[108:111], v[96:99], v[152:155], v[132:135]
	v_mfma_f32_16x16x32_bf16 v[104:107], v[96:99], v[160:163], v[128:131]
	v_mfma_f32_16x16x32_bf16 v[100:103], v[96:99], v[172:175], v[136:139]
	s_nop 1
	ds_read_b128 v[128:131], v156 offset:28672
	ds_read_b128 v[132:135], v156 offset:29696
	ds_read_b128 v[136:139], v156 offset:30720
	ds_read_b128 v[140:143], v156 offset:31744
	s_waitcnt lgkmcnt(0)
	s_barrier
	v_mfma_f32_16x16x32_bf16 v[60:63], v[128:131], v[152:155], v[60:63]
	v_mfma_f32_16x16x32_bf16 v[56:59], v[128:131], v[160:163], v[56:59]
	v_mfma_f32_16x16x32_bf16 v[52:55], v[128:131], v[172:175], v[52:55]
	v_mfma_f32_16x16x32_bf16 v[48:51], v[128:131], v[192:195], v[48:51]
	v_mov_b32_e32 v129, v178
	v_mfma_f32_16x16x32_bf16 v[124:127], v[92:95], v[152:155], v[148:151]
	v_lshrrev_b32_e32 v128, 6, v129
	v_mul_lo_u32 v131, v128, s75
	v_lshrrev_b32_e32 v128, 2, v129
	v_mfma_f32_16x16x32_bf16 v[44:47], v[132:135], v[152:155], v[44:47]
	v_and_b32_e32 v130, 15, v129
	v_lshl_or_b32 v130, v130, 1, v131
	v_mfma_f32_16x16x32_bf16 v[40:43], v[132:135], v[160:163], v[40:43]
	v_mfma_f32_16x16x32_bf16 v[36:39], v[132:135], v[172:175], v[36:39]
	v_mfma_f32_16x16x32_bf16 v[32:35], v[132:135], v[192:195], v[32:35]
	v_lshlrev_b32_e32 v133, 3, v129
	v_and_b32_e32 v132, 12, v128
	v_and_b32_e32 v128, 64, v129
	v_and_b32_e32 v133, 56, v133
	v_or3_b32 v128, v128, s6, v133
	v_lshl_or_b32 v131, v133, 1, v131
	v_bfe_u32 v133, v129, 3, 3
	v_and_b32_e32 v129, 0xffffff80, v129
	v_add_u32_e32 v134, s4, v129
	v_bfe_u32 v135, v124, 16, 1
	s_movk_i32 s4, 0x90
	v_add3_u32 v135, v124, v135, s71
	v_mad_u32_u24 v124, v132, s4, v130
	v_bfe_u32 v130, v125, 16, 1
	v_add3_u32 v125, v125, v130, s71
	v_mfma_f32_16x16x32_bf16 v[120:123], v[92:95], v[160:163], v[144:147]
	ds_write_b16_d16_hi v124, v125 offset:144
	v_bfe_u32 v125, v126, 16, 1
	v_add3_u32 v125, v126, v125, s71
	ds_write_b16_d16_hi v124, v125 offset:288
	v_bfe_u32 v125, v127, 16, 1
	v_add3_u32 v125, v127, v125, s71
	ds_write_b16_d16_hi v124, v125 offset:432
	s_nop 0
	v_bfe_u32 v125, v120, 16, 1
	v_add3_u32 v120, v120, v125, s71
	ds_write_b16_d16_hi v124, v120 offset:32
	v_bfe_u32 v120, v121, 16, 1
	v_add3_u32 v120, v121, v120, s71
	ds_write_b16_d16_hi v124, v120 offset:176
	v_bfe_u32 v120, v122, 16, 1
	v_add3_u32 v120, v122, v120, s71
	ds_write_b16_d16_hi v124, v120 offset:320
	v_bfe_u32 v120, v123, 16, 1
	v_add3_u32 v120, v123, v120, s71
	ds_write_b16_d16_hi v124, v120 offset:464
	v_bfe_u32 v120, v116, 16, 1
	v_add3_u32 v116, v116, v120, s71
	ds_write_b16_d16_hi v124, v116 offset:64
	v_bfe_u32 v116, v117, 16, 1
	v_add3_u32 v116, v117, v116, s71
	v_mfma_f32_16x16x32_bf16 v[112:115], v[92:95], v[192:195], v[112:115]
	ds_write_b16_d16_hi v124, v116 offset:208
	v_bfe_u32 v116, v118, 16, 1
	v_add3_u32 v116, v118, v116, s71
	ds_write_b16_d16_hi v124, v116 offset:352
	v_bfe_u32 v116, v119, 16, 1
	v_add3_u32 v116, v119, v116, s71
	ds_write_b16_d16_hi v124, v116 offset:496
	s_nop 0
	v_bfe_u32 v116, v112, 16, 1
	v_add3_u32 v112, v112, v116, s71
	ds_write_b16_d16_hi v124, v112 offset:96
	v_bfe_u32 v112, v113, 16, 1
	v_add3_u32 v112, v113, v112, s71
	ds_write_b16_d16_hi v124, v112 offset:240
	v_bfe_u32 v112, v114, 16, 1
	v_add3_u32 v112, v114, v112, s71
	ds_write_b16_d16_hi v124, v112 offset:384
	v_bfe_u32 v112, v115, 16, 1
	v_add3_u32 v112, v115, v112, s71
	ds_write_b16_d16_hi v124, v112 offset:528
	v_bfe_u32 v112, v108, 16, 1
	v_add3_u32 v108, v108, v112, s71
	ds_write_b16_d16_hi v124, v108 offset:2304
	v_bfe_u32 v108, v109, 16, 1
	v_add3_u32 v108, v109, v108, s71
	ds_write_b16_d16_hi v124, v108 offset:2448
; DEV void store_tile_bf16(const f32x4 (&acc)[8][4], u16* __restrict__ OUT, size_t ld, int m0, int n0, int ncols,
;                          unsigned char* smem) {
;     ...
; #pragma unroll
;   for (int mh = 0; mh < 2; ++mh) {
; #pragma unroll
;     for (int mi = 0; mi < 4; ++mi)
; #pragma unroll
;       for (int ni = 0; ni < 4; ++ni)
; #pragma unroll
;         for (int j = 0; j < 4; ++j) st[(mi * 16 + fq * 4 + j) * 72 + ni * 16 + fr] = f2bf(acc[mh * 4 + mi][ni][j]);
;     const int chunk = lane & 7;
;     const int c0 = n0 + wc * 64 + chunk * 8;
; #pragma unroll
;     for (int itr = 0; itr < 8; ++itr) {
;       const int rl = (lane >> 3) + 8 * itr;
;       const u32x4 v = *(const u32x4*)(st + rl * 72 + chunk * 8);
;       if (c0 + 8 <= ncols) *(u32x4*)(OUT + (size_t)(m0 + wr * 128 + mh * 64 + rl) * ld + c0) = v;
	v_bfe_u32 v108, v110, 16, 1
	v_add3_u32 v108, v110, v108, s71
	ds_write_b16_d16_hi v124, v108 offset:2592
	v_bfe_u32 v108, v111, 16, 1
	v_add3_u32 v108, v111, v108, s71
	ds_write_b16_d16_hi v124, v108 offset:2736
	v_bfe_u32 v108, v104, 16, 1
	v_add3_u32 v104, v104, v108, s71
	ds_write_b16_d16_hi v124, v104 offset:2336
	v_bfe_u32 v104, v105, 16, 1
	v_add3_u32 v104, v105, v104, s71
	ds_write_b16_d16_hi v124, v104 offset:2480
	v_bfe_u32 v104, v106, 16, 1
	v_add3_u32 v104, v106, v104, s71
	ds_write_b16_d16_hi v124, v104 offset:2624
	v_bfe_u32 v104, v107, 16, 1
	v_add3_u32 v104, v107, v104, s71
	ds_write_b16_d16_hi v124, v104 offset:2768
	v_bfe_u32 v104, v100, 16, 1
	v_add3_u32 v100, v100, v104, s71
	ds_write_b16_d16_hi v124, v100 offset:2368
	v_bfe_u32 v100, v101, 16, 1
	v_add3_u32 v100, v101, v100, s71
	v_mfma_f32_16x16x32_bf16 v[96:99], v[96:99], v[192:195], v[164:167]
	ds_write_b16_d16_hi v124, v100 offset:2512
	v_bfe_u32 v100, v102, 16, 1
	v_add3_u32 v100, v102, v100, s71
	ds_write_b16_d16_hi v124, v100 offset:2656
	v_bfe_u32 v100, v103, 16, 1
	v_add3_u32 v100, v103, v100, s71
	ds_write_b16_d16_hi v124, v100 offset:2800
	s_nop 0
	v_bfe_u32 v100, v96, 16, 1
	v_add3_u32 v96, v96, v100, s71
	ds_write_b16_d16_hi v124, v96 offset:2400
	v_bfe_u32 v96, v97, 16, 1
	v_add3_u32 v96, v97, v96, s71
	v_mfma_f32_16x16x32_bf16 v[92:95], v[196:199], v[152:155], v[168:171]
	ds_write_b16_d16_hi v124, v96 offset:2544
	v_bfe_u32 v96, v98, 16, 1
	v_add3_u32 v96, v98, v96, s71
	ds_write_b16_d16_hi v124, v96 offset:2688
	v_bfe_u32 v96, v99, 16, 1
	v_add3_u32 v96, v99, v96, s71
	ds_write_b16_d16_hi v124, v96 offset:2832
	s_nop 0
	v_bfe_u32 v96, v92, 16, 1
	v_add3_u32 v92, v92, v96, s71
	ds_write_b16_d16_hi v124, v92 offset:4608
	v_bfe_u32 v92, v93, 16, 1
	v_add3_u32 v92, v93, v92, s71
	v_mfma_f32_16x16x32_bf16 v[88:91], v[196:199], v[160:163], v[88:91]
	ds_write_b16_d16_hi v124, v92 offset:4752
	v_bfe_u32 v92, v94, 16, 1
	v_add3_u32 v92, v94, v92, s71
	ds_write_b16_d16_hi v124, v92 offset:4896
	v_bfe_u32 v92, v95, 16, 1
	v_add3_u32 v92, v95, v92, s71
	ds_write_b16_d16_hi v124, v92 offset:5040
	s_nop 0
	v_bfe_u32 v92, v88, 16, 1
	v_add3_u32 v88, v88, v92, s71
	ds_write_b16_d16_hi v124, v88 offset:4640
	v_bfe_u32 v88, v89, 16, 1
	v_add3_u32 v88, v89, v88, s71
	v_mfma_f32_16x16x32_bf16 v[84:87], v[196:199], v[172:175], v[84:87]
	ds_write_b16_d16_hi v124, v88 offset:4784
	v_bfe_u32 v88, v90, 16, 1
	v_add3_u32 v88, v90, v88, s71
	ds_write_b16_d16_hi v124, v88 offset:4928
	v_bfe_u32 v88, v91, 16, 1
	v_add3_u32 v88, v91, v88, s71
	ds_write_b16_d16_hi v124, v88 offset:5072
	s_nop 0
	v_bfe_u32 v88, v84, 16, 1
	v_add3_u32 v84, v84, v88, s71
	ds_write_b16_d16_hi v124, v84 offset:4672
	v_bfe_u32 v84, v85, 16, 1
	v_add3_u32 v84, v85, v84, s71
	v_mfma_f32_16x16x32_bf16 v[80:83], v[196:199], v[192:195], v[80:83]
	ds_write_b16_d16_hi v124, v84 offset:4816
	v_bfe_u32 v84, v86, 16, 1
	v_add3_u32 v84, v86, v84, s71
	ds_write_b16_d16_hi v124, v84 offset:4960
	v_bfe_u32 v84, v87, 16, 1
	v_add3_u32 v84, v87, v84, s71
	ds_write_b16_d16_hi v124, v84 offset:5104
	s_nop 0
	v_bfe_u32 v84, v80, 16, 1
	v_add3_u32 v80, v80, v84, s71
	ds_write_b16_d16_hi v124, v80 offset:4704
	v_bfe_u32 v80, v81, 16, 1
	v_add3_u32 v80, v81, v80, s71
	v_mfma_f32_16x16x32_bf16 v[76:79], v[200:203], v[152:155], v[76:79]
	ds_write_b16_d16_hi v124, v80 offset:4848
	v_bfe_u32 v80, v82, 16, 1
	v_add3_u32 v80, v82, v80, s71
	ds_write_b16_d16_hi v124, v80 offset:4992
	v_bfe_u32 v80, v83, 16, 1
	v_add3_u32 v80, v83, v80, s71
	ds_write_b16_d16_hi v124, v80 offset:5136
	s_nop 0
	v_bfe_u32 v80, v76, 16, 1
	v_add3_u32 v76, v76, v80, s71
	ds_write_b16_d16_hi v124, v76 offset:6912
	v_bfe_u32 v76, v77, 16, 1
	v_add3_u32 v76, v77, v76, s71
	v_mfma_f32_16x16x32_bf16 v[72:75], v[200:203], v[160:163], v[72:75]
	ds_write_b16_d16_hi v124, v76 offset:7056
	v_bfe_u32 v76, v78, 16, 1
	v_add3_u32 v76, v78, v76, s71
	ds_write_b16_d16_hi v124, v76 offset:7200
	v_bfe_u32 v76, v79, 16, 1
	v_add3_u32 v76, v79, v76, s71
	ds_write_b16_d16_hi v124, v76 offset:7344
	s_nop 0
	v_bfe_u32 v76, v72, 16, 1
	v_add3_u32 v72, v72, v76, s71
	ds_write_b16_d16_hi v124, v72 offset:6944
	v_bfe_u32 v72, v73, 16, 1
	v_add3_u32 v72, v73, v72, s71
	v_mfma_f32_16x16x32_bf16 v[68:71], v[200:203], v[172:175], v[68:71]
	ds_write_b16_d16_hi v124, v72 offset:7088
	v_bfe_u32 v72, v74, 16, 1
	v_add3_u32 v72, v74, v72, s71
	ds_write_b16_d16_hi v124, v72 offset:7232
	v_bfe_u32 v72, v75, 16, 1
	v_add3_u32 v72, v75, v72, s71
	ds_write_b16_d16_hi v124, v72 offset:7376
	s_nop 0
	v_bfe_u32 v72, v68, 16, 1
	v_add3_u32 v68, v68, v72, s71
	ds_write_b16_d16_hi v124, v68 offset:6976
	v_bfe_u32 v68, v69, 16, 1
	v_add3_u32 v68, v69, v68, s71
	v_mfma_f32_16x16x32_bf16 v[64:67], v[200:203], v[192:195], v[64:67]
	ds_write_b16_d16_hi v124, v68 offset:7120
	v_bfe_u32 v68, v70, 16, 1
	v_add3_u32 v68, v70, v68, s71
	ds_write_b16_d16_hi v124, v68 offset:7264
	v_bfe_u32 v68, v71, 16, 1
	v_add3_u32 v68, v71, v68, s71
	ds_write_b16_d16_hi v124, v68 offset:7408
	s_nop 0
	v_bfe_u32 v68, v64, 16, 1
	v_add3_u32 v64, v64, v68, s71
	ds_write_b16_d16_hi v124, v64 offset:7008
	v_bfe_u32 v64, v65, 16, 1
	v_add3_u32 v64, v65, v64, s71
	ds_write_b16_d16_hi v124, v64 offset:7152
	v_bfe_u32 v64, v66, 16, 1
	v_mfma_f32_16x16x32_bf16 v[28:31], v[136:139], v[152:155], v[28:31]
	v_add3_u32 v64, v66, v64, s71
	ds_write_b16_d16_hi v124, v64 offset:7296
	v_bfe_u32 v64, v67, 16, 1
	v_mfma_f32_16x16x32_bf16 v[24:27], v[136:139], v[160:163], v[24:27]
	v_ashrrev_i32_e32 v129, 31, v128
	v_add3_u32 v64, v67, v64, s71
	v_cmp_gt_i32_e32 vcc, s5, v128
	v_mfma_f32_16x16x32_bf16 v[20:23], v[136:139], v[172:175], v[20:23]
	v_lshl_add_u64 v[128:129], v[128:129], 1, s[68:69]
	ds_write_b16_d16_hi v124, v64 offset:7440
	v_mad_u32_u24 v65, v133, s4, v131
	v_mfma_f32_16x16x32_bf16 v[16:19], v[136:139], v[192:195], v[16:19]
	v_or_b32_e32 v64, v134, v133
	ds_write_b16_d16_hi v124, v135
	v_mfma_f32_16x16x32_bf16 v[12:15], v[140:143], v[152:155], v[12:15]
	v_mfma_f32_16x16x32_bf16 v[8:11], v[140:143], v[160:163], v[8:11]
	v_mfma_f32_16x16x32_bf16 v[4:7], v[140:143], v[172:175], v[4:7]
	v_mfma_f32_16x16x32_bf16 v[0:3], v[140:143], v[192:195], v[0:3]
	s_and_saveexec_b64 s[4:5], vcc
	s_cbranch_execz .LBB0_165
; DEV void store_tile_bf16(const f32x4 (&acc)[8][4], u16* __restrict__ OUT, size_t ld, int m0, int n0, int ncols,
;                          unsigned char* smem) {
;     ...
;     const int chunk = lane & 7;
;     const int c0 = n0 + wc * 64 + chunk * 8;
; #pragma unroll
;     for (int itr = 0; itr < 8; ++itr) {
;       const int rl = (lane >> 3) + 8 * itr;
;       const u32x4 v = *(const u32x4*)(st + rl * 72 + chunk * 8);
;       if (c0 + 8 <= ncols) *(u32x4*)(OUT + (size_t)(m0 + wr * 128 + mh * 64 + rl) * ld + c0) = v;
	ds_read_b128 v[66:69], v65
	v_mad_i64_i32 v[70:71], s[6:7], v64, s75, v[128:129]
	s_waitcnt lgkmcnt(0)
	global_store_dwordx4 v[70:71], v[66:69], off
	ds_read_b128 v[66:69], v65 offset:1152
	v_or_b32_e32 v70, 8, v64
	v_mad_i64_i32 v[70:71], s[6:7], v70, s75, v[128:129]
	s_waitcnt lgkmcnt(0)
	global_store_dwordx4 v[70:71], v[66:69], off
	ds_read_b128 v[66:69], v65 offset:2304
	v_or_b32_e32 v70, 16, v64
	v_mad_i64_i32 v[70:71], s[6:7], v70, s75, v[128:129]
	s_waitcnt lgkmcnt(0)
	global_store_dwordx4 v[70:71], v[66:69], off
	ds_read_b128 v[66:69], v65 offset:3456
	v_or_b32_e32 v70, 24, v64
	v_mad_i64_i32 v[70:71], s[6:7], v70, s75, v[128:129]
	s_waitcnt lgkmcnt(0)
	global_store_dwordx4 v[70:71], v[66:69], off
	ds_read_b128 v[66:69], v65 offset:4608
	v_or_b32_e32 v70, 32, v64
	v_mad_i64_i32 v[70:71], s[6:7], v70, s75, v[128:129]
	s_waitcnt lgkmcnt(0)
	global_store_dwordx4 v[70:71], v[66:69], off
	ds_read_b128 v[66:69], v65 offset:5760
	v_or_b32_e32 v70, 40, v64
	v_mad_i64_i32 v[70:71], s[6:7], v70, s75, v[128:129]
	s_waitcnt lgkmcnt(0)
	global_store_dwordx4 v[70:71], v[66:69], off
	ds_read_b128 v[66:69], v65 offset:6912
	v_or_b32_e32 v70, 48, v64
	v_mad_i64_i32 v[70:71], s[6:7], v70, s75, v[128:129]
	s_waitcnt lgkmcnt(0)
	global_store_dwordx4 v[70:71], v[66:69], off
	ds_read_b128 v[66:69], v65 offset:8064
	v_or_b32_e32 v70, 56, v64
	v_mad_i64_i32 v[70:71], s[6:7], v70, s75, v[128:129]
	s_waitcnt lgkmcnt(0)
	global_store_dwordx4 v[70:71], v[66:69], off

; DEV int TID() { int t = threadIdx.x; asm volatile("" : "+v"(t)); return t; }
; DEV void gemm_tile(const u16* __restrict__ A, size_t lda, const u16* __restrict__ Bt, size_t ldb, int K,
;                    u16* sA, u16* sB, f32x4 (&acc)[8][4]) {
;   const int tid = TID(), lane = tid & 63, wid = tid >> 6;
;   const int wr = wid >> 1, wc = wid & 1, fr = lane & 15, fq = lane >> 4;
; #pragma unroll
;   for (int mi = 0; mi < 8; ++mi)
; #pragma unroll
;     for (int ni = 0; ni < 4; ++ni) acc[mi][ni] = f32x4{0.f, 0.f, 0.f, 0.f};
;   const int lr = tid >> 2, lc = (tid & 3) * 8;
;   const u16* ap = A + (size_t)lr * lda + lc;
;   const u16* bp = Bt + (size_t)lr * ldb + lc;
;   u32x4 ra[4], rb[2];
;     ...
;   const int nk = K >> 5;
;   const int swz = ((fq ^ ((0 - (fr >> 2)) & 3)) << 3);
;   const u16* sAr = sA + (wr * 128 + fr) * 32 + swz;
;   const u16* sBr = sA + 256 * 32 + (wc * 64 + fr) * 32 + swz;
;   G_LOAD(0)
;   __syncthreads();
;   S_STORE(0)
;   if (nk > 1) G_LOAD(32)
;   __syncthreads();
.LBB0_197:
	s_lshl_b32 s4, s7, 8
	s_ashr_i32 s5, s4, 31
	v_mov_b32_e32 v46, v178
	s_lshl_b32 s2, s6, 7
	s_lshl_b64 s[8:9], s[4:5], 12
	v_readlane_b32 s10, v249, 56
	v_readlane_b32 s11, v249, 57
	v_ashrrev_i32_e32 v28, 2, v46
	s_add_u32 s16, s10, s8
	v_ashrrev_i32_e32 v29, 31, v28
	s_addc_u32 s17, s11, s9
	v_lshlrev_b64 v[30:31], 12, v[28:29]
	v_lshlrev_b32_e32 v4, 4, v46
	v_lshl_add_u64 v[2:3], s[16:17], 0, v[30:31]
	v_and_b32_e32 v156, 48, v4
	v_lshl_add_u64 v[32:33], v[2:3], 0, v[156:157]
	s_mov_b32 s3, 0x40000
	s_mul_i32 s10, s6, 0x180000
	s_mul_hi_i32 s11, s2, 0x3000
	v_add_co_u32_e32 v34, vcc, s3, v32
	v_lshl_add_u64 v[0:1], v[158:159], 0, s[10:11]
	s_movk_i32 s16, 0x3000
	v_addc_co_u32_e32 v35, vcc, 0, v33, vcc
	s_mov_b32 s3, 0x80000
	v_mad_i64_i32 v[0:1], s[6:7], v28, s16, v[0:1]
	v_add_co_u32_e32 v36, vcc, s3, v32
	v_lshl_add_u64 v[38:39], v[0:1], 0, v[156:157]
	s_nop 0
	v_addc_co_u32_e32 v37, vcc, 0, v33, vcc
	s_mov_b32 s3, 0xc0000
	v_add_co_u32_e32 v40, vcc, s3, v38
	v_addc_co_u32_e32 v41, vcc, 0, v39, vcc
	v_add_co_u32_e32 v42, vcc, s3, v32
	v_addc_co_u32_e32 v43, vcc, 0, v33, vcc
	s_barrier
	v_lshrrev_b32_e32 v3, 4, v46
	v_lshrrev_b32_e32 v29, 2, v46
	v_sub_u32_e32 v29, 0, v29
	v_sub_u32_e32 v48, 0, v3
	v_xor_b32_e32 v3, v3, v29
	v_xor_b32_e32 v29, v46, v48
	v_mov_b64_e32 v[44:45], s[10:11]
	v_lshlrev_b32_e32 v3, 4, v3
	v_lshlrev_b32_e32 v29, 4, v29
	v_lshlrev_b32_e32 v47, 6, v46
	v_mad_i64_i32 v[44:45], s[10:11], v28, s16, v[44:45]
	v_lshl_add_u64 v[30:31], v[30:31], 0, s[8:9]
	v_and_b32_e32 v3, 48, v3
	v_and_b32_e32 v29, 48, v29
	s_movk_i32 s8, 0xe3c0
	v_mov_b32_e32 v0, 0
	v_or_b32_e32 v44, v44, v156
	v_or_b32_e32 v30, v30, v156
	v_and_or_b32 v156, v47, s8, v3
	v_lshl_or_b32 v167, v28, 6, v29
	s_movk_i32 s8, 0x13c0
	s_mov_b32 s5, 0
	s_mov_b64 s[6:7], 0
	v_mov_b32_e32 v1, v0
	v_mov_b32_e32 v2, v0
	s_ashr_i32 s3, s2, 31
	v_lshl_add_u64 v[162:163], v[160:161], 0, v[44:45]
	v_and_or_b32 v166, v47, s8, v3
	v_lshl_add_u64 v[164:165], s[46:47], 0, v[30:31]
	v_mov_b32_e32 v3, v0
	v_mov_b32_e32 v28, v0
	v_mov_b32_e32 v29, v0
	v_mov_b32_e32 v30, v0
	v_mov_b32_e32 v31, v0
	v_mov_b32_e32 v32, v0
	v_mov_b32_e32 v33, v0
	v_mov_b32_e32 v34, v0
	v_mov_b32_e32 v35, v0
	v_mov_b32_e32 v36, v0
	v_mov_b32_e32 v37, v0
	v_mov_b32_e32 v38, v0
	v_mov_b32_e32 v39, v0
	v_mov_b32_e32 v40, v0
	v_mov_b32_e32 v4, v0
	v_mov_b32_e32 v5, v0
	v_mov_b32_e32 v6, v0
	v_mov_b32_e32 v7, v0
	v_mov_b32_e32 v8, v0
	v_mov_b32_e32 v9, v0
	v_mov_b32_e32 v10, v0
	v_mov_b32_e32 v11, v0
	v_mov_b32_e32 v12, v0
	v_mov_b32_e32 v13, v0
	v_mov_b32_e32 v14, v0
	v_mov_b32_e32 v15, v0
	v_mov_b32_e32 v16, v0
	v_mov_b32_e32 v17, v0
	v_mov_b32_e32 v18, v0
	v_mov_b32_e32 v19, v0
	v_mov_b32_e32 v20, v0
	v_mov_b32_e32 v21, v0
	v_mov_b32_e32 v22, v0
	v_mov_b32_e32 v23, v0
	v_mov_b32_e32 v24, v0
	v_mov_b32_e32 v25, v0
	v_mov_b32_e32 v26, v0
	v_mov_b32_e32 v27, v0
	v_mov_b32_e32 v41, v0
	v_mov_b32_e32 v42, v0
	v_mov_b32_e32 v43, v0
	v_mov_b32_e32 v44, v0
	v_mov_b32_e32 v45, v0
	v_mov_b32_e32 v46, v0
	v_mov_b32_e32 v47, v0
	v_mov_b32_e32 v48, v0
	v_mov_b32_e32 v49, v0
	v_mov_b32_e32 v50, v0
	v_mov_b32_e32 v51, v0
	v_mov_b32_e32 v52, v0
	v_mov_b32_e32 v53, v0
	v_mov_b32_e32 v54, v0
	v_mov_b32_e32 v55, v0
	v_mov_b32_e32 v56, v0
	v_mov_b32_e32 v57, v0
	v_mov_b32_e32 v58, v0
	v_mov_b32_e32 v59, v0
	v_mov_b32_e32 v60, v0
	v_mov_b32_e32 v61, v0
	v_mov_b32_e32 v62, v0
	v_mov_b32_e32 v63, v0
	v_mov_b32_e32 v64, v0
	v_mov_b32_e32 v65, v0
	v_mov_b32_e32 v66, v0
	v_mov_b32_e32 v67, v0
	v_mov_b32_e32 v68, v0
	v_mov_b32_e32 v69, v0
	v_mov_b32_e32 v70, v0
	v_mov_b32_e32 v71, v0
	v_mov_b32_e32 v72, v0
	v_mov_b32_e32 v73, v0
	v_mov_b32_e32 v74, v0
	v_mov_b32_e32 v75, v0
	v_mov_b32_e32 v76, v0
	v_mov_b32_e32 v77, v0
	v_mov_b32_e32 v78, v0
	v_mov_b32_e32 v79, v0
	v_mov_b32_e32 v80, v0
	v_mov_b32_e32 v81, v0
	v_mov_b32_e32 v82, v0
	v_mov_b32_e32 v83, v0
	v_mov_b32_e32 v84, v0
	v_mov_b32_e32 v85, v0
	v_mov_b32_e32 v86, v0
	v_mov_b32_e32 v87, v0
	v_mov_b32_e32 v88, v0
	v_mov_b32_e32 v89, v0
	v_mov_b32_e32 v90, v0
	v_mov_b32_e32 v91, v0
	v_mov_b32_e32 v92, v0
	v_mov_b32_e32 v93, v0
	v_mov_b32_e32 v94, v0
	v_mov_b32_e32 v95, v0
	v_mov_b32_e32 v96, v0
	v_mov_b32_e32 v97, v0
	v_mov_b32_e32 v98, v0
	v_mov_b32_e32 v99, v0
	v_mov_b32_e32 v100, v0
	v_mov_b32_e32 v101, v0
	v_mov_b32_e32 v102, v0
	v_mov_b32_e32 v103, v0
	v_mov_b32_e32 v104, v0
	v_mov_b32_e32 v105, v0
	v_mov_b32_e32 v106, v0
	v_mov_b32_e32 v107, v0
	v_mov_b32_e32 v108, v0
	v_mov_b32_e32 v109, v0
	v_mov_b32_e32 v110, v0
	v_mov_b32_e32 v111, v0
	v_mov_b32_e32 v112, v0
	v_mov_b32_e32 v113, v0
	v_mov_b32_e32 v114, v0
	v_mov_b32_e32 v115, v0
	v_mov_b32_e32 v124, v0
	v_mov_b32_e32 v125, v0
	v_mov_b32_e32 v126, v0
	v_mov_b32_e32 v127, v0
	v_mov_b32_e32 v144, v0
	v_mov_b32_e32 v145, v0
	v_mov_b32_e32 v146, v0
	v_mov_b32_e32 v147, v0
	v_mov_b32_e32 v148, v0
	v_mov_b32_e32 v149, v0
	v_mov_b32_e32 v150, v0
	v_mov_b32_e32 v151, v0
	s_mov_b32 s10, 0x29450000
	s_waitcnt lgkmcnt(0)
	s_barrier
; DEV f32x4 mfma16(bf16x8 a, bf16x8 b, f32x4 c) { return __builtin_amdgcn_mfma_f32_16x16x32_bf16(a, b, c, 0, 0, 0); }
; DEV void gemm_tile(const u16* __restrict__ A, size_t lda, const u16* __restrict__ Bt, size_t ldb, int K,
;                    u16* sA, u16* sB, f32x4 (&acc)[8][4]) {
;     ...
;   G_LOAD(0)
;   __syncthreads();
;   S_STORE(0)
;   if (nk > 1) G_LOAD(32)
;   __syncthreads();
;   for (int kt = 0; kt < nk; ++kt) {
;     const int st = kt & 1;
;     if (kt + 1 < nk) S_STORE(st ^ 1)
;     if (kt + 2 < nk) G_LOAD((kt + 2) << 5)
;     {
;       const u16* pa = sAr + st * 12288;
;       const u16* pb = sBr + st * 12288;
;       bf16x8 b[4];
; #pragma unroll
;       for (int ni = 0; ni < 4; ++ni) b[ni] = *(const bf16x8*)(pb + ni * 16 * 32);
; #pragma unroll
;       for (int mh = 0; mh < 2; ++mh) {
;         bf16x8 a[4];
; #pragma unroll
;         for (int mi = 0; mi < 4; ++mi) a[mi] = *(const bf16x8*)(pa + (mh * 64 + mi * 16) * 32);
; #pragma unroll
;         for (int mi = 0; mi < 4; ++mi)
; #pragma unroll
;           for (int ni = 0; ni < 4; ++ni) acc[mh * 4 + mi][ni] = mfma16(a[mi], b[ni], acc[mh * 4 + mi][ni]);
;       }
;     }
;     __syncthreads();
;   }
	v_lshl_add_u64 v[132:133], v[164:165], 0, s[6:7]
	v_add_co_u32_e32 v136, vcc, s10, v132
	s_nop 1
	v_addc_co_u32_e32 v137, vcc, 0, v133, vcc
	s_mov_b32 s8, 0x29490000
	v_add_co_u32_e32 v138, vcc, s8, v132
	s_mov_b32 s8, 0x294d0000
	s_nop 1
	v_addc_co_u32_e32 v139, vcc, 0, v133, vcc
	v_add_co_u32_e32 v176, vcc, s8, v132
	s_nop 1
	v_addc_co_u32_e32 v177, vcc, 0, v133, vcc
	s_mov_b32 s8, 0x29510000
	v_add_co_u32_e32 v186, vcc, s8, v132
	v_lshl_add_u64 v[134:135], v[162:163], 0, s[6:7]
	s_nop 1
	v_addc_co_u32_e32 v187, vcc, 0, v133, vcc
	s_mov_b32 s8, 0x8dd0000
	v_add_co_u32_e32 v188, vcc, s8, v134
	s_nop 1
	v_addc_co_u32_e32 v189, vcc, 0, v135, vcc
	s_mov_b32 s8, 0x8e90000
	v_add_co_u32_e32 v192, vcc, s8, v134
	s_nop 1
	v_addc_co_u32_e32 v193, vcc, 0, v135, vcc
	v_lshrrev_b32_e32 v228, 4, v178
	v_sub_u32_e32 v228, 0, v228
	v_and_b32_e32 v228, 3, v228
	v_lshlrev_b32_e32 v228, 4, v228
	v_lshrrev_b32_e32 v229, 6, v178
	v_lshlrev_b32_e32 v229, 10, v229
	v_xor_b32_e32 v136, v136, v228
	v_xor_b32_e32 v138, v138, v228
	v_xor_b32_e32 v176, v176, v228
	v_xor_b32_e32 v186, v186, v228
	v_xor_b32_e32 v188, v188, v228
	v_xor_b32_e32 v192, v192, v228
	v_readfirstlane_b32 s5, v229
	s_nop 1
	s_add_i32 s9, s5, 0x6000
	s_add_i32 m0, s9, 0x0
	s_nop 0
	global_load_lds_dwordx4 v[136:137], off
	v_lshl_add_u64 v[136:137], v[136:137], 0, 64
	s_add_i32 m0, s9, 0x1000
	s_nop 0
	global_load_lds_dwordx4 v[138:139], off
	v_lshl_add_u64 v[138:139], v[138:139], 0, 64
	s_add_i32 m0, s9, 0x2000
	s_nop 0
	global_load_lds_dwordx4 v[176:177], off
	v_lshl_add_u64 v[176:177], v[176:177], 0, 64
	s_add_i32 m0, s9, 0x3000
	s_nop 0
	global_load_lds_dwordx4 v[186:187], off
	v_lshl_add_u64 v[186:187], v[186:187], 0, 64
	s_add_i32 m0, s9, 0x4000
	s_nop 0
	global_load_lds_dwordx4 v[188:189], off
	v_lshl_add_u64 v[188:189], v[188:189], 0, 64
	s_add_i32 m0, s9, 0x5000
	s_nop 0
	global_load_lds_dwordx4 v[192:193], off
	v_lshl_add_u64 v[192:193], v[192:193], 0, 64
	s_add_i32 s9, s5, 0xc000
	s_add_i32 m0, s9, 0x0
	s_nop 0
	global_load_lds_dwordx4 v[136:137], off
	v_lshl_add_u64 v[136:137], v[136:137], 0, 64
	s_add_i32 m0, s9, 0x1000
	s_nop 0
	global_load_lds_dwordx4 v[138:139], off
	v_lshl_add_u64 v[138:139], v[138:139], 0, 64
	s_add_i32 m0, s9, 0x2000
	s_nop 0
	global_load_lds_dwordx4 v[176:177], off
	v_lshl_add_u64 v[176:177], v[176:177], 0, 64
	s_add_i32 m0, s9, 0x3000
	s_nop 0
	global_load_lds_dwordx4 v[186:187], off
	v_lshl_add_u64 v[186:187], v[186:187], 0, 64
	s_add_i32 m0, s9, 0x4000
	s_nop 0
	global_load_lds_dwordx4 v[188:189], off
	v_lshl_add_u64 v[188:189], v[188:189], 0, 64
	s_add_i32 m0, s9, 0x5000
	s_nop 0
	global_load_lds_dwordx4 v[192:193], off
	v_lshl_add_u64 v[192:193], v[192:193], 0, 64
	v_and_b32_e32 v230, 63, v178
	v_lshlrev_b32_e32 v230, 4, v230
	s_mov_b32 s8, 0x6000
	s_mov_b32 s9, s5
	s_waitcnt vmcnt(6)
	s_barrier
.LBB0_198:
	v_add_u32_e32 v229, s8, v166
	v_add_u32_e32 v228, s8, v156
	ds_read_b128 v[116:119], v229 offset:16384
	ds_read_b128 v[168:171], v228
	ds_read_b128 v[128:131], v229 offset:17408
	ds_read_b128 v[140:143], v229 offset:18432
	ds_read_b128 v[120:123], v229 offset:19456
	ds_read_b128 v[152:155], v228 offset:1024
	ds_read_b128 v[172:175], v228 offset:2048
	ds_read_b128 v[132:135], v228 offset:3072
	s_waitcnt lgkmcnt(6)
	v_mfma_f32_16x16x32_bf16 v[148:151], v[168:171], v[116:119], v[148:151]
	s_add_i32 m0, s9, 0x0
	s_waitcnt lgkmcnt(5)
	v_mfma_f32_16x16x32_bf16 v[144:147], v[168:171], v[128:131], v[144:147]
	global_load_lds_dwordx4 v[136:137], off
	v_lshl_add_u64 v[136:137], v[136:137], 0, 64
	global_load_dwordx4 v[244:247], v[136:137], off
	v_lshl_add_u64 v[136:137], v[136:137], 0, 64
	s_waitcnt lgkmcnt(4)
	v_mfma_f32_16x16x32_bf16 v[124:127], v[168:171], v[140:143], v[124:127]
	s_add_i32 m0, s9, 0x1000
	s_waitcnt lgkmcnt(3)
	v_mfma_f32_16x16x32_bf16 v[112:115], v[168:171], v[120:123], v[112:115]
	ds_read_b128 v[232:235], v228 offset:4096
	ds_read_b128 v[236:239], v228 offset:5120
	s_waitcnt lgkmcnt(4)
	v_mfma_f32_16x16x32_bf16 v[108:111], v[152:155], v[116:119], v[108:111]
	global_load_lds_dwordx4 v[138:139], off
	v_lshl_add_u64 v[138:139], v[138:139], 0, 64
	global_load_dwordx4 v[252:255], v[138:139], off
	v_lshl_add_u64 v[138:139], v[138:139], 0, 64
	v_mfma_f32_16x16x32_bf16 v[104:107], v[152:155], v[128:131], v[104:107]
	s_add_i32 m0, s9, 0x2000
	v_mfma_f32_16x16x32_bf16 v[100:103], v[152:155], v[140:143], v[100:103]
	global_load_lds_dwordx4 v[176:177], off
	v_lshl_add_u64 v[176:177], v[176:177], 0, 64
	global_load_dwordx4 v[208:211], v[176:177], off
	v_lshl_add_u64 v[176:177], v[176:177], 0, 64
	v_mfma_f32_16x16x32_bf16 v[96:99], v[152:155], v[120:123], v[96:99]
	s_add_i32 m0, s9, 0x3000
	s_waitcnt lgkmcnt(3)
	v_mfma_f32_16x16x32_bf16 v[92:95], v[172:175], v[116:119], v[92:95]
	global_load_lds_dwordx4 v[186:187], off
	v_lshl_add_u64 v[186:187], v[186:187], 0, 64
	global_load_dwordx4 v[212:215], v[186:187], off
	v_lshl_add_u64 v[186:187], v[186:187], 0, 64
	v_mfma_f32_16x16x32_bf16 v[88:91], v[172:175], v[128:131], v[88:91]
	s_add_i32 m0, s9, 0x4000
	v_mfma_f32_16x16x32_bf16 v[84:87], v[172:175], v[140:143], v[84:87]
	global_load_lds_dwordx4 v[188:189], off
	v_lshl_add_u64 v[188:189], v[188:189], 0, 64
	global_load_dwordx4 v[216:219], v[188:189], off
	v_lshl_add_u64 v[188:189], v[188:189], 0, 64
	v_mfma_f32_16x16x32_bf16 v[80:83], v[172:175], v[120:123], v[80:83]
	ds_read_b128 v[240:243], v228 offset:6144
	ds_read_b128 v[168:171], v228 offset:7168
	s_waitcnt lgkmcnt(4)
; DEV f32x4 mfma16(bf16x8 a, bf16x8 b, f32x4 c) { return __builtin_amdgcn_mfma_f32_16x16x32_bf16(a, b, c, 0, 0, 0); }
; DEV void gemm_tile(const u16* __restrict__ A, size_t lda, const u16* __restrict__ Bt, size_t ldb, int K,
;                    u16* sA, u16* sB, f32x4 (&acc)[8][4]) {
;     ...
;   for (int kt = 0; kt < nk; ++kt) {
;     const int st = kt & 1;
;     if (kt + 1 < nk) S_STORE(st ^ 1)
;     if (kt + 2 < nk) G_LOAD((kt + 2) << 5)
;     {
;       const u16* pa = sAr + st * 12288;
;       const u16* pb = sBr + st * 12288;
;       bf16x8 b[4];
; #pragma unroll
;       for (int ni = 0; ni < 4; ++ni) b[ni] = *(const bf16x8*)(pb + ni * 16 * 32);
; #pragma unroll
;       for (int mh = 0; mh < 2; ++mh) {
;         bf16x8 a[4];
; #pragma unroll
;         for (int mi = 0; mi < 4; ++mi) a[mi] = *(const bf16x8*)(pa + (mh * 64 + mi * 16) * 32);
; #pragma unroll
;         for (int mi = 0; mi < 4; ++mi)
; #pragma unroll
;           for (int ni = 0; ni < 4; ++ni) acc[mh * 4 + mi][ni] = mfma16(a[mi], b[ni], acc[mh * 4 + mi][ni]);
;       }
;     }
;     __syncthreads();
;   }
	v_mfma_f32_16x16x32_bf16 v[76:79], v[132:135], v[116:119], v[76:79]
	s_add_i32 m0, s9, 0x5000
	v_mfma_f32_16x16x32_bf16 v[72:75], v[132:135], v[128:131], v[72:75]
	global_load_lds_dwordx4 v[192:193], off
	v_lshl_add_u64 v[192:193], v[192:193], 0, 64
	global_load_dwordx4 v[220:223], v[192:193], off
	v_lshl_add_u64 v[192:193], v[192:193], 0, 64
	v_mfma_f32_16x16x32_bf16 v[68:71], v[132:135], v[140:143], v[68:71]
	s_add_i32 s9, s8, s5
	s_add_i32 s8, s8, 0x6000
	v_mfma_f32_16x16x32_bf16 v[64:67], v[132:135], v[120:123], v[64:67]
	s_cmp_eq_u32 s8, 0x12000
	s_cselect_b32 s8, 0, s8
	s_waitcnt lgkmcnt(3)
	v_mfma_f32_16x16x32_bf16 v[60:63], v[232:235], v[116:119], v[60:63]
	s_add_u32 s6, s6, 64
	s_addc_u32 s7, s7, 0
	s_cmpk_lg_i32 s6, 0xf80
	v_mfma_f32_16x16x32_bf16 v[56:59], v[232:235], v[128:131], v[56:59]
	v_mfma_f32_16x16x32_bf16 v[52:55], v[232:235], v[140:143], v[52:55]
	v_mfma_f32_16x16x32_bf16 v[48:51], v[232:235], v[120:123], v[48:51]
	s_waitcnt lgkmcnt(2)
	v_mfma_f32_16x16x32_bf16 v[44:47], v[236:239], v[116:119], v[44:47]
	v_mfma_f32_16x16x32_bf16 v[40:43], v[236:239], v[128:131], v[40:43]
	v_mfma_f32_16x16x32_bf16 v[36:39], v[236:239], v[140:143], v[36:39]
	v_mfma_f32_16x16x32_bf16 v[32:35], v[236:239], v[120:123], v[32:35]
	s_waitcnt lgkmcnt(1)
	v_mfma_f32_16x16x32_bf16 v[28:31], v[240:243], v[116:119], v[28:31]
	v_mfma_f32_16x16x32_bf16 v[24:27], v[240:243], v[128:131], v[24:27]
	v_mfma_f32_16x16x32_bf16 v[20:23], v[240:243], v[140:143], v[20:23]
	v_mfma_f32_16x16x32_bf16 v[16:19], v[240:243], v[120:123], v[16:19]
	s_waitcnt lgkmcnt(0)
	s_waitcnt vmcnt(12)
	s_barrier
	v_mfma_f32_16x16x32_bf16 v[12:15], v[168:171], v[116:119], v[12:15]
	v_mfma_f32_16x16x32_bf16 v[8:11], v[168:171], v[128:131], v[8:11]
	v_mfma_f32_16x16x32_bf16 v[4:7], v[168:171], v[140:143], v[4:7]
	v_mfma_f32_16x16x32_bf16 v[0:3], v[168:171], v[120:123], v[0:3]
	v_add_u32_e32 v229, s8, v166
	v_add_u32_e32 v228, s8, v156
	ds_read_b128 v[116:119], v229 offset:16384
	ds_read_b128 v[168:171], v228
	ds_read_b128 v[128:131], v229 offset:17408
	ds_read_b128 v[140:143], v229 offset:18432
	ds_read_b128 v[120:123], v229 offset:19456
	ds_read_b128 v[152:155], v228 offset:1024
	ds_read_b128 v[172:175], v228 offset:2048
	ds_read_b128 v[132:135], v228 offset:3072
	s_waitcnt lgkmcnt(6)
	v_mfma_f32_16x16x32_bf16 v[148:151], v[168:171], v[116:119], v[148:151]
	s_waitcnt vmcnt(0)
	v_add_u32_e32 v231, s9, v230
	s_waitcnt lgkmcnt(5)
	v_mfma_f32_16x16x32_bf16 v[144:147], v[168:171], v[128:131], v[144:147]
	ds_write_b128 v231, v[244:247]
	s_waitcnt lgkmcnt(5)
	v_mfma_f32_16x16x32_bf16 v[124:127], v[168:171], v[140:143], v[124:127]
	ds_write_b128 v231, v[252:255] offset:4096
	s_waitcnt lgkmcnt(5)
	v_mfma_f32_16x16x32_bf16 v[112:115], v[168:171], v[120:123], v[112:115]
	ds_read_b128 v[232:235], v228 offset:4096
	ds_read_b128 v[236:239], v228 offset:5120
	s_waitcnt lgkmcnt(6)
	v_mfma_f32_16x16x32_bf16 v[108:111], v[152:155], v[116:119], v[108:111]
	ds_write_b128 v231, v[208:211] offset:8192
	v_mfma_f32_16x16x32_bf16 v[104:107], v[152:155], v[128:131], v[104:107]
	ds_write_b128 v231, v[212:215] offset:12288
	v_mfma_f32_16x16x32_bf16 v[100:103], v[152:155], v[140:143], v[100:103]
	ds_write_b128 v231, v[216:219] offset:16384
	v_mfma_f32_16x16x32_bf16 v[96:99], v[152:155], v[120:123], v[96:99]
	ds_write_b128 v231, v[220:223] offset:20480
	s_waitcnt lgkmcnt(9)
	v_mfma_f32_16x16x32_bf16 v[92:95], v[172:175], v[116:119], v[92:95]
	s_add_i32 s9, s8, s5
	s_add_i32 s8, s8, 0x6000
	v_mfma_f32_16x16x32_bf16 v[88:91], v[172:175], v[128:131], v[88:91]
	s_cmp_eq_u32 s8, 0x12000
	s_cselect_b32 s8, 0, s8
	v_mfma_f32_16x16x32_bf16 v[84:87], v[172:175], v[140:143], v[84:87]
	s_add_u32 s6, s6, 64
	s_addc_u32 s7, s7, 0
	s_cmpk_lg_i32 s6, 0xf80
	v_mfma_f32_16x16x32_bf16 v[80:83], v[172:175], v[120:123], v[80:83]
	ds_read_b128 v[240:243], v228 offset:6144
	ds_read_b128 v[168:171], v228 offset:7168
	s_waitcnt lgkmcnt(10)
	v_mfma_f32_16x16x32_bf16 v[76:79], v[132:135], v[116:119], v[76:79]
	v_mfma_f32_16x16x32_bf16 v[72:75], v[132:135], v[128:131], v[72:75]
	v_mfma_f32_16x16x32_bf16 v[68:71], v[132:135], v[140:143], v[68:71]
	v_mfma_f32_16x16x32_bf16 v[64:67], v[132:135], v[120:123], v[64:67]
	s_waitcnt lgkmcnt(7)
	v_mfma_f32_16x16x32_bf16 v[60:63], v[232:235], v[116:119], v[60:63]
	v_mfma_f32_16x16x32_bf16 v[56:59], v[232:235], v[128:131], v[56:59]
	v_mfma_f32_16x16x32_bf16 v[52:55], v[232:235], v[140:143], v[52:55]
	v_mfma_f32_16x16x32_bf16 v[48:51], v[232:235], v[120:123], v[48:51]
	s_waitcnt lgkmcnt(6)
	v_mfma_f32_16x16x32_bf16 v[44:47], v[236:239], v[116:119], v[44:47]
	v_mfma_f32_16x16x32_bf16 v[40:43], v[236:239], v[128:131], v[40:43]
	v_mfma_f32_16x16x32_bf16 v[36:39], v[236:239], v[140:143], v[36:39]
	v_mfma_f32_16x16x32_bf16 v[32:35], v[236:239], v[120:123], v[32:35]
	s_waitcnt lgkmcnt(1)
	v_mfma_f32_16x16x32_bf16 v[28:31], v[240:243], v[116:119], v[28:31]
	v_mfma_f32_16x16x32_bf16 v[24:27], v[240:243], v[128:131], v[24:27]
	v_mfma_f32_16x16x32_bf16 v[20:23], v[240:243], v[140:143], v[20:23]
	v_mfma_f32_16x16x32_bf16 v[16:19], v[240:243], v[120:123], v[16:19]
	s_waitcnt lgkmcnt(0)
	s_waitcnt lgkmcnt(0)
	s_barrier
	v_mfma_f32_16x16x32_bf16 v[12:15], v[168:171], v[116:119], v[12:15]
	v_mfma_f32_16x16x32_bf16 v[8:11], v[168:171], v[128:131], v[8:11]
	v_mfma_f32_16x16x32_bf16 v[4:7], v[168:171], v[140:143], v[4:7]
	v_mfma_f32_16x16x32_bf16 v[0:3], v[168:171], v[120:123], v[0:3]
	s_cbranch_scc1 .LBB0_198
; DEV f32x4 mfma16(bf16x8 a, bf16x8 b, f32x4 c) { return __builtin_amdgcn_mfma_f32_16x16x32_bf16(a, b, c, 0, 0, 0); }
; DEV void gemm_tile(const u16* __restrict__ A, size_t lda, const u16* __restrict__ Bt, size_t ldb, int K,
;                    u16* sA, u16* sB, f32x4 (&acc)[8][4]) {
;     ...
;   for (int kt = 0; kt < nk; ++kt) {
;     const int st = kt & 1;
;     if (kt + 1 < nk) S_STORE(st ^ 1)
;     if (kt + 2 < nk) G_LOAD((kt + 2) << 5)
;     {
;       const u16* pa = sAr + st * 12288;
;       const u16* pb = sBr + st * 12288;
;       bf16x8 b[4];
; #pragma unroll
;       for (int ni = 0; ni < 4; ++ni) b[ni] = *(const bf16x8*)(pb + ni * 16 * 32);
; #pragma unroll
;       for (int mh = 0; mh < 2; ++mh) {
;         bf16x8 a[4];
; #pragma unroll
;         for (int mi = 0; mi < 4; ++mi) a[mi] = *(const bf16x8*)(pa + (mh * 64 + mi * 16) * 32);
; #pragma unroll
;         for (int mi = 0; mi < 4; ++mi)
; #pragma unroll
;           for (int ni = 0; ni < 4; ++ni) acc[mh * 4 + mi][ni] = mfma16(a[mi], b[ni], acc[mh * 4 + mi][ni]);
;       }
;     }
;     __syncthreads();
;   }
	ds_read_b128 v[116:119], v166 offset:16384
	ds_read_b128 v[120:123], v166 offset:17408
	ds_read_b128 v[128:131], v166 offset:18432
	ds_read_b128 v[132:135], v166 offset:19456
	ds_read_b128 v[136:139], v156
	ds_read_b128 v[140:143], v156 offset:1024
	ds_read_b128 v[152:155], v156 offset:2048
	ds_read_b128 v[162:165], v156 offset:3072
	s_movk_i32 s5, 0x2200
	s_waitcnt lgkmcnt(3)
	v_mfma_f32_16x16x32_bf16 v[148:151], v[136:139], v[116:119], v[148:151]
	s_movk_i32 s8, 0x110
	v_mfma_f32_16x16x32_bf16 v[144:147], v[136:139], v[120:123], v[144:147]
	v_mfma_f32_16x16x32_bf16 v[124:127], v[136:139], v[128:131], v[124:127]
	v_mfma_f32_16x16x32_bf16 v[112:115], v[136:139], v[132:135], v[112:115]
	s_waitcnt lgkmcnt(2)
	v_mfma_f32_16x16x32_bf16 v[108:111], v[140:143], v[116:119], v[108:111]
	v_mfma_f32_16x16x32_bf16 v[104:107], v[140:143], v[120:123], v[104:107]
	v_mfma_f32_16x16x32_bf16 v[100:103], v[140:143], v[128:131], v[100:103]
	v_mfma_f32_16x16x32_bf16 v[96:99], v[140:143], v[132:135], v[96:99]
	s_waitcnt lgkmcnt(1)
	v_mfma_f32_16x16x32_bf16 v[92:95], v[152:155], v[116:119], v[92:95]
	v_mfma_f32_16x16x32_bf16 v[88:91], v[152:155], v[120:123], v[88:91]
	v_mfma_f32_16x16x32_bf16 v[84:87], v[152:155], v[128:131], v[84:87]
	v_mfma_f32_16x16x32_bf16 v[80:83], v[152:155], v[132:135], v[80:83]
	s_waitcnt lgkmcnt(0)
	v_mfma_f32_16x16x32_bf16 v[76:79], v[162:165], v[116:119], v[76:79]
	v_mfma_f32_16x16x32_bf16 v[72:75], v[162:165], v[120:123], v[72:75]
	v_mfma_f32_16x16x32_bf16 v[68:71], v[162:165], v[128:131], v[68:71]
	v_mfma_f32_16x16x32_bf16 v[64:67], v[162:165], v[132:135], v[64:67]
	ds_read_b128 v[136:139], v156 offset:4096
	ds_read_b128 v[140:143], v156 offset:5120
	ds_read_b128 v[152:155], v156 offset:6144
	ds_read_b128 v[162:165], v156 offset:7168
	s_waitcnt lgkmcnt(0)
	s_waitcnt vmcnt(0)
	s_barrier
	v_mfma_f32_16x16x32_bf16 v[60:63], v[136:139], v[116:119], v[60:63]
	v_mfma_f32_16x16x32_bf16 v[56:59], v[136:139], v[120:123], v[56:59]
	v_mfma_f32_16x16x32_bf16 v[52:55], v[136:139], v[128:131], v[52:55]
	v_mfma_f32_16x16x32_bf16 v[48:51], v[136:139], v[132:135], v[48:51]
	v_mfma_f32_16x16x32_bf16 v[44:47], v[140:143], v[116:119], v[44:47]
	v_mfma_f32_16x16x32_bf16 v[40:43], v[140:143], v[120:123], v[40:43]
	v_mfma_f32_16x16x32_bf16 v[36:39], v[140:143], v[128:131], v[36:39]
	v_mfma_f32_16x16x32_bf16 v[32:35], v[140:143], v[132:135], v[32:35]
	v_mfma_f32_16x16x32_bf16 v[28:31], v[152:155], v[116:119], v[28:31]
	v_mfma_f32_16x16x32_bf16 v[24:27], v[152:155], v[120:123], v[24:27]
	v_mfma_f32_16x16x32_bf16 v[20:23], v[152:155], v[128:131], v[20:23]
	v_mfma_f32_16x16x32_bf16 v[16:19], v[152:155], v[132:135], v[16:19]
	v_mfma_f32_16x16x32_bf16 v[12:15], v[162:165], v[116:119], v[12:15]
	v_mfma_f32_16x16x32_bf16 v[8:11], v[162:165], v[120:123], v[8:11]
	v_mfma_f32_16x16x32_bf16 v[4:7], v[162:165], v[128:131], v[4:7]
	v_mfma_f32_16x16x32_bf16 v[0:3], v[162:165], v[132:135], v[0:3]
	ds_read_b128 v[116:119], v166 offset:40960
	ds_read_b128 v[120:123], v166 offset:41984
	ds_read_b128 v[128:131], v166 offset:43008
	ds_read_b128 v[132:135], v166 offset:44032
	ds_read_b128 v[136:139], v156 offset:24576
	ds_read_b128 v[140:143], v156 offset:25600
	ds_read_b128 v[152:155], v156 offset:26624
	ds_read_b128 v[162:165], v156 offset:27648
	s_waitcnt lgkmcnt(3)
	v_mfma_f32_16x16x32_bf16 v[148:151], v[136:139], v[116:119], v[148:151]
	v_mfma_f32_16x16x32_bf16 v[144:147], v[136:139], v[120:123], v[144:147]
	v_mfma_f32_16x16x32_bf16 v[124:127], v[136:139], v[128:131], v[124:127]
	v_mfma_f32_16x16x32_bf16 v[112:115], v[136:139], v[132:135], v[112:115]
	s_waitcnt lgkmcnt(2)
	v_mfma_f32_16x16x32_bf16 v[108:111], v[140:143], v[116:119], v[108:111]
	v_mfma_f32_16x16x32_bf16 v[104:107], v[140:143], v[120:123], v[104:107]
	v_mfma_f32_16x16x32_bf16 v[136:139], v[140:143], v[128:131], v[100:103]
	v_mfma_f32_16x16x32_bf16 v[96:99], v[140:143], v[132:135], v[96:99]
	s_waitcnt lgkmcnt(1)
	v_mfma_f32_16x16x32_bf16 v[92:95], v[152:155], v[116:119], v[92:95]
	v_mfma_f32_16x16x32_bf16 v[88:91], v[152:155], v[120:123], v[88:91]
	v_mfma_f32_16x16x32_bf16 v[84:87], v[152:155], v[128:131], v[84:87]
	v_mfma_f32_16x16x32_bf16 v[80:83], v[152:155], v[132:135], v[80:83]
	s_waitcnt lgkmcnt(0)
	v_mfma_f32_16x16x32_bf16 v[76:79], v[162:165], v[116:119], v[76:79]
	v_mfma_f32_16x16x32_bf16 v[72:75], v[162:165], v[120:123], v[72:75]
	v_mfma_f32_16x16x32_bf16 v[68:71], v[162:165], v[128:131], v[68:71]
	v_mfma_f32_16x16x32_bf16 v[64:67], v[162:165], v[132:135], v[64:67]
	ds_read_b128 v[100:103], v156 offset:28672
	ds_read_b128 v[140:143], v156 offset:29696
	ds_read_b128 v[152:155], v156 offset:30720
	ds_read_b128 v[162:165], v156 offset:31744
	s_waitcnt lgkmcnt(0)
	s_barrier
; DEV int TID() { int t = threadIdx.x; asm volatile("" : "+v"(t)); return t; }
; DEV void store_tile_f32_add(const f32x4 (&acc)[8][4], const float* xres, float* out, int m0, int n0, unsigned char* smem) {
;   const int tid = TID(), lane = tid & 63, wid = tid >> 6;
;   const int wr = wid >> 1, wc = wid & 1, fr = lane & 15, fq = lane >> 4;
;   float* st = (float*)(smem + wid * 8704);
;   const int chunk = lane & 15;
; #pragma unroll
;   for (int mq = 0; mq < 4; ++mq) {
; #pragma unroll
;     for (int mh = 0; mh < 2; ++mh)
; #pragma unroll
;       for (int ni = 0; ni < 4; ++ni)
; #pragma unroll
;         for (int j = 0; j < 4; ++j) st[(mh * 16 + fq * 4 + j) * 68 + ni * 16 + fr] = acc[mq * 2 + mh][ni][j];
; #pragma unroll
;     for (int itr = 0; itr < 8; ++itr) {
;       const int rl = (lane >> 4) + 4 * itr;
;       const f32x4 v = *(const f32x4*)(st + rl * 68 + chunk * 4);
;       const size_t idx = (size_t)(m0 + wr * 128 + mq * 32 + rl) * 2048 + n0 + wc * 64 + chunk * 4;
;       const f32x4 x = *(const f32x4*)(xres + idx);
;       *(f32x4*)(out + idx) = x + v;
;     }
;   }
	v_mfma_f32_16x16x32_bf16 v[60:63], v[100:103], v[116:119], v[60:63]
	v_mfma_f32_16x16x32_bf16 v[56:59], v[100:103], v[120:123], v[56:59]
	v_mfma_f32_16x16x32_bf16 v[52:55], v[100:103], v[128:131], v[52:55]
	v_mfma_f32_16x16x32_bf16 v[48:51], v[100:103], v[132:135], v[48:51]
	v_mov_b32_e32 v102, v178
	s_nop 0
	v_lshrrev_b32_e32 v101, 6, v102
	v_and_b32_e32 v103, 15, v102
	v_mfma_f32_16x16x32_bf16 v[44:47], v[140:143], v[116:119], v[44:47]
	v_mul_lo_u32 v101, v101, s5
	v_bfe_u32 v100, v102, 4, 2
	v_mfma_f32_16x16x32_bf16 v[28:31], v[152:155], v[116:119], v[28:31]
	v_mfma_f32_16x16x32_bf16 v[12:15], v[162:165], v[116:119], v[12:15]
	v_lshlrev_b32_e32 v116, 2, v103
	v_or_b32_e32 v117, v101, v116
	v_and_b32_e32 v101, 0xffffff80, v102
	v_add_u32_e32 v101, s4, v101
	s_movk_i32 s4, 0x440
	v_mad_u32_u24 v118, v103, 12, v117
	v_and_or_b32 v116, v102, 64, v116
	v_mad_u32_u24 v103, v100, s4, v117
	v_readlane_b32 s4, v251, 7
	ds_write_b32 v103, v148
	ds_write_b32 v103, v149 offset:272
	ds_write_b32 v103, v150 offset:544
	ds_write_b32 v103, v151 offset:816
	ds_write_b32 v103, v144 offset:64
	ds_write_b32 v103, v145 offset:336
	ds_write_b32 v103, v146 offset:608
	ds_write_b32 v103, v147 offset:880
	ds_write_b32 v103, v124 offset:128
	ds_write_b32 v103, v125 offset:400
	ds_write_b32 v103, v126 offset:672
	ds_write_b32 v103, v127 offset:944
	ds_write_b32 v103, v112 offset:192
	ds_write_b32 v103, v113 offset:464
	ds_write_b32 v103, v114 offset:736
	ds_write_b32 v103, v115 offset:1008
	ds_write_b32 v103, v108 offset:4352
	ds_write_b32 v103, v109 offset:4624
	ds_write_b32 v103, v110 offset:4896
	ds_write_b32 v103, v111 offset:5168
	ds_write_b32 v103, v104 offset:4416
	ds_write_b32 v103, v105 offset:4688
	ds_write_b32 v103, v106 offset:4960
	ds_write_b32 v103, v107 offset:5232
	ds_write_b32 v103, v136 offset:4480
	ds_write_b32 v103, v137 offset:4752
	ds_write_b32 v103, v138 offset:5024
	ds_write_b32 v103, v139 offset:5296
	ds_write_b32 v103, v96 offset:4544
	ds_write_b32 v103, v97 offset:4816
	ds_write_b32 v103, v98 offset:5088
	ds_write_b32 v103, v99 offset:5360
	v_or_b32_e32 v98, v101, v100
	v_lshlrev_b32_e32 v156, 2, v116
	v_readlane_b32 s6, v251, 9
	v_readlane_b32 s7, v251, 10
	v_ashrrev_i32_e32 v99, 31, v98
	v_lshlrev_b64 v[98:99], 13, v[98:99]
	v_lshl_add_u64 v[96:97], s[6:7], 0, v[156:157]
	v_lshl_add_u64 v[96:97], s[2:3], 2, v[96:97]
	v_lshl_add_u64 v[98:99], v[96:97], 0, v[98:99]
	global_load_dwordx4 v[108:111], v[98:99], off
	v_mad_u32_u24 v102, v100, s8, v118
	ds_read_b128 v[104:107], v102
	v_mfma_f32_16x16x32_bf16 v[32:35], v[140:143], v[132:135], v[32:35]
	v_readlane_b32 s5, v251, 8
	s_waitcnt vmcnt(0) lgkmcnt(0)
	v_pk_add_f32 v[106:107], v[106:107], v[110:111]
	v_pk_add_f32 v[104:105], v[104:105], v[108:109]
	global_store_dwordx4 v[98:99], v[104:107], off
	v_or_b32_e32 v99, 4, v100
	v_or_b32_e32 v108, v99, v101
	v_ashrrev_i32_e32 v109, 31, v108
	v_lshlrev_b64 v[108:109], 13, v[108:109]
	v_lshl_add_u64 v[112:113], v[96:97], 0, v[108:109]
	global_load_dwordx4 v[108:111], v[112:113], off
	v_mad_u32_u24 v98, v99, s8, v118
	ds_read_b128 v[104:107], v98
	v_mfma_f32_16x16x32_bf16 v[40:43], v[140:143], v[120:123], v[40:43]
	s_waitcnt vmcnt(0) lgkmcnt(0)
	v_pk_add_f32 v[106:107], v[106:107], v[110:111]
	v_pk_add_f32 v[104:105], v[104:105], v[108:109]
	global_store_dwordx4 v[112:113], v[104:107], off
	ds_read_b128 v[106:109], v98 offset:1088
	v_mfma_f32_16x16x32_bf16 v[36:39], v[140:143], v[128:131], v[36:39]
	v_or_b32_e32 v104, 8, v100
	v_or_b32_e32 v110, v104, v101
	v_ashrrev_i32_e32 v111, 31, v110
	v_lshlrev_b64 v[110:111], 13, v[110:111]
	v_lshl_add_u64 v[114:115], v[96:97], 0, v[110:111]
	global_load_dwordx4 v[110:113], v[114:115], off
	v_or_b32_e32 v105, 12, v100
	v_mfma_f32_16x16x32_bf16 v[8:11], v[162:165], v[120:123], v[8:11]
	s_waitcnt vmcnt(0) lgkmcnt(0)
	v_pk_add_f32 v[106:107], v[106:107], v[110:111]
	v_or_b32_e32 v110, v105, v101
	v_ashrrev_i32_e32 v111, 31, v110
	v_pk_add_f32 v[108:109], v[108:109], v[112:113]
	v_lshlrev_b64 v[110:111], 13, v[110:111]
	global_store_dwordx4 v[114:115], v[106:109], off
	v_lshl_add_u64 v[114:115], v[96:97], 0, v[110:111]
	global_load_dwordx4 v[110:113], v[114:115], off
	ds_read_b128 v[106:109], v98 offset:2176
	v_mfma_f32_16x16x32_bf16 v[24:27], v[152:155], v[120:123], v[24:27]
	s_waitcnt vmcnt(0) lgkmcnt(0)
	v_pk_add_f32 v[108:109], v[108:109], v[112:113]
	v_pk_add_f32 v[106:107], v[106:107], v[110:111]
	global_store_dwordx4 v[114:115], v[106:109], off
	ds_read_b128 v[108:111], v98 offset:3264
	v_mfma_f32_16x16x32_bf16 v[20:23], v[152:155], v[128:131], v[20:23]
	v_or_b32_e32 v106, 16, v100
	v_or_b32_e32 v112, v106, v101
	v_ashrrev_i32_e32 v113, 31, v112
	v_lshlrev_b64 v[112:113], 13, v[112:113]
	v_lshl_add_u64 v[116:117], v[96:97], 0, v[112:113]
	global_load_dwordx4 v[112:115], v[116:117], off
	v_or_b32_e32 v107, 20, v100
	v_mfma_f32_16x16x32_bf16 v[16:19], v[152:155], v[132:135], v[16:19]
	s_waitcnt vmcnt(0) lgkmcnt(0)
	v_pk_add_f32 v[108:109], v[108:109], v[112:113]
	v_or_b32_e32 v112, v107, v101
	v_ashrrev_i32_e32 v113, 31, v112
	v_pk_add_f32 v[110:111], v[110:111], v[114:115]
	v_lshlrev_b64 v[112:113], 13, v[112:113]
	global_store_dwordx4 v[116:117], v[108:111], off
	v_lshl_add_u64 v[116:117], v[96:97], 0, v[112:113]
	global_load_dwordx4 v[112:115], v[116:117], off
	ds_read_b128 v[108:111], v98 offset:4352
	v_mfma_f32_16x16x32_bf16 v[4:7], v[162:165], v[128:131], v[4:7]
	s_waitcnt vmcnt(0) lgkmcnt(0)
; DEV void store_tile_f32_add(const f32x4 (&acc)[8][4], const float* xres, float* out, int m0, int n0, unsigned char* smem) {
;     ...
; #pragma unroll
;   for (int mq = 0; mq < 4; ++mq) {
; #pragma unroll
;     for (int mh = 0; mh < 2; ++mh)
; #pragma unroll
;       for (int ni = 0; ni < 4; ++ni)
; #pragma unroll
;         for (int j = 0; j < 4; ++j) st[(mh * 16 + fq * 4 + j) * 68 + ni * 16 + fr] = acc[mq * 2 + mh][ni][j];
; #pragma unroll
;     for (int itr = 0; itr < 8; ++itr) {
;       const int rl = (lane >> 4) + 4 * itr;
;       const f32x4 v = *(const f32x4*)(st + rl * 68 + chunk * 4);
;       const size_t idx = (size_t)(m0 + wr * 128 + mq * 32 + rl) * 2048 + n0 + wc * 64 + chunk * 4;
;       const f32x4 x = *(const f32x4*)(xres + idx);
;       *(f32x4*)(out + idx) = x + v;
;     }
;   }
	v_pk_add_f32 v[110:111], v[110:111], v[114:115]
	v_pk_add_f32 v[108:109], v[108:109], v[112:113]
	global_store_dwordx4 v[116:117], v[108:111], off
	ds_read_b128 v[110:113], v98 offset:5440
	v_mfma_f32_16x16x32_bf16 v[0:3], v[162:165], v[132:135], v[0:3]
	v_or_b32_e32 v108, 24, v100
	v_or_b32_e32 v114, v108, v101
	v_ashrrev_i32_e32 v115, 31, v114
	v_lshlrev_b64 v[114:115], 13, v[114:115]
	v_lshl_add_u64 v[118:119], v[96:97], 0, v[114:115]
	global_load_dwordx4 v[114:117], v[118:119], off
	v_or_b32_e32 v109, 28, v100
	s_waitcnt vmcnt(0) lgkmcnt(0)
	v_pk_add_f32 v[110:111], v[110:111], v[114:115]
	v_or_b32_e32 v114, v109, v101
	v_ashrrev_i32_e32 v115, 31, v114
	v_pk_add_f32 v[112:113], v[112:113], v[116:117]
	v_lshlrev_b64 v[114:115], 13, v[114:115]
	global_store_dwordx4 v[118:119], v[110:113], off
	v_lshl_add_u64 v[118:119], v[96:97], 0, v[114:115]
	global_load_dwordx4 v[114:117], v[118:119], off
	ds_read_b128 v[110:113], v98 offset:6528
	s_waitcnt vmcnt(0) lgkmcnt(0)
	v_pk_add_f32 v[112:113], v[112:113], v[116:117]
	v_pk_add_f32 v[110:111], v[110:111], v[114:115]
	global_store_dwordx4 v[118:119], v[110:113], off
	ds_write_b32 v103, v92
	ds_write_b32 v103, v93 offset:272
	ds_write_b32 v103, v94 offset:544
	ds_write_b32 v103, v95 offset:816
	ds_write_b32 v103, v88 offset:64
	ds_write_b32 v103, v89 offset:336
	ds_write_b32 v103, v90 offset:608
	ds_write_b32 v103, v91 offset:880
	ds_write_b32 v103, v84 offset:128
	ds_write_b32 v103, v85 offset:400
	ds_write_b32 v103, v86 offset:672
	ds_write_b32 v103, v87 offset:944
	ds_write_b32 v103, v80 offset:192
	ds_write_b32 v103, v81 offset:464
	ds_write_b32 v103, v82 offset:736
	ds_write_b32 v103, v83 offset:1008
	ds_write_b32 v103, v76 offset:4352
	ds_write_b32 v103, v77 offset:4624
	ds_write_b32 v103, v78 offset:4896
	ds_write_b32 v103, v79 offset:5168
	ds_write_b32 v103, v72 offset:4416
	ds_write_b32 v103, v73 offset:4688
	ds_write_b32 v103, v74 offset:4960
	ds_write_b32 v103, v75 offset:5232
	ds_write_b32 v103, v68 offset:4480
	ds_write_b32 v103, v69 offset:4752
	ds_write_b32 v103, v70 offset:5024
	ds_write_b32 v103, v71 offset:5296
	ds_write_b32 v103, v64 offset:4544
	ds_write_b32 v103, v65 offset:4816
	ds_write_b32 v103, v66 offset:5088
	ds_write_b32 v103, v67 offset:5360
	v_or_b32_e32 v64, 32, v101
	v_or_b32_e32 v70, v64, v100
	v_ashrrev_i32_e32 v71, 31, v70
	v_lshlrev_b64 v[70:71], 13, v[70:71]
	v_lshl_add_u64 v[74:75], v[96:97], 0, v[70:71]
	global_load_dwordx4 v[70:73], v[74:75], off
	ds_read_b128 v[66:69], v102
	s_waitcnt vmcnt(0) lgkmcnt(0)
	v_pk_add_f32 v[66:67], v[66:67], v[70:71]
	v_or_b32_e32 v70, v64, v99
	v_ashrrev_i32_e32 v71, 31, v70
	v_pk_add_f32 v[68:69], v[68:69], v[72:73]
	v_lshlrev_b64 v[70:71], 13, v[70:71]
	global_store_dwordx4 v[74:75], v[66:69], off
	v_lshl_add_u64 v[74:75], v[96:97], 0, v[70:71]
	global_load_dwordx4 v[70:73], v[74:75], off
	ds_read_b128 v[66:69], v98
	s_waitcnt vmcnt(0) lgkmcnt(0)
	v_pk_add_f32 v[66:67], v[66:67], v[70:71]
	v_or_b32_e32 v70, v64, v104
	v_ashrrev_i32_e32 v71, 31, v70
	v_pk_add_f32 v[68:69], v[68:69], v[72:73]
	v_lshlrev_b64 v[70:71], 13, v[70:71]
	global_store_dwordx4 v[74:75], v[66:69], off
	v_lshl_add_u64 v[74:75], v[96:97], 0, v[70:71]
	global_load_dwordx4 v[70:73], v[74:75], off
	ds_read_b128 v[66:69], v98 offset:1088
	s_waitcnt vmcnt(0) lgkmcnt(0)
	v_pk_add_f32 v[66:67], v[66:67], v[70:71]
	v_or_b32_e32 v70, v64, v105
	v_ashrrev_i32_e32 v71, 31, v70
	v_pk_add_f32 v[68:69], v[68:69], v[72:73]
	v_lshlrev_b64 v[70:71], 13, v[70:71]
	global_store_dwordx4 v[74:75], v[66:69], off
	v_lshl_add_u64 v[74:75], v[96:97], 0, v[70:71]
	global_load_dwordx4 v[70:73], v[74:75], off
	ds_read_b128 v[66:69], v98 offset:2176
	s_waitcnt vmcnt(0) lgkmcnt(0)
	v_pk_add_f32 v[66:67], v[66:67], v[70:71]
	v_or_b32_e32 v70, v64, v106
	v_ashrrev_i32_e32 v71, 31, v70
	v_pk_add_f32 v[68:69], v[68:69], v[72:73]
	v_lshlrev_b64 v[70:71], 13, v[70:71]
	global_store_dwordx4 v[74:75], v[66:69], off
	v_lshl_add_u64 v[74:75], v[96:97], 0, v[70:71]
	global_load_dwordx4 v[70:73], v[74:75], off
	ds_read_b128 v[66:69], v98 offset:3264
	s_waitcnt vmcnt(0) lgkmcnt(0)
	v_pk_add_f32 v[66:67], v[66:67], v[70:71]
	v_or_b32_e32 v70, v64, v107
	v_ashrrev_i32_e32 v71, 31, v70
	v_pk_add_f32 v[68:69], v[68:69], v[72:73]
	v_lshlrev_b64 v[70:71], 13, v[70:71]
	global_store_dwordx4 v[74:75], v[66:69], off
	v_lshl_add_u64 v[74:75], v[96:97], 0, v[70:71]
	global_load_dwordx4 v[70:73], v[74:75], off
	ds_read_b128 v[66:69], v98 offset:4352
	s_waitcnt vmcnt(0) lgkmcnt(0)
	v_pk_add_f32 v[66:67], v[66:67], v[70:71]
	v_or_b32_e32 v70, v64, v108
	v_ashrrev_i32_e32 v71, 31, v70
	v_pk_add_f32 v[68:69], v[68:69], v[72:73]
	v_lshlrev_b64 v[70:71], 13, v[70:71]
	global_store_dwordx4 v[74:75], v[66:69], off
	v_lshl_add_u64 v[74:75], v[96:97], 0, v[70:71]
	global_load_dwordx4 v[70:73], v[74:75], off
	ds_read_b128 v[66:69], v98 offset:5440
	v_or_b32_e32 v64, v64, v109
	v_ashrrev_i32_e32 v65, 31, v64
	v_lshlrev_b64 v[64:65], 13, v[64:65]
	v_lshl_add_u64 v[64:65], v[96:97], 0, v[64:65]
	s_waitcnt vmcnt(0) lgkmcnt(0)
	v_pk_add_f32 v[68:69], v[68:69], v[72:73]
	v_pk_add_f32 v[66:67], v[66:67], v[70:71]
	global_load_dwordx4 v[70:73], v[64:65], off
	s_nop 0
	global_store_dwordx4 v[74:75], v[66:69], off
	ds_read_b128 v[66:69], v98 offset:6528
	s_waitcnt vmcnt(1) lgkmcnt(0)
; DEV void store_tile_f32_add(const f32x4 (&acc)[8][4], const float* xres, float* out, int m0, int n0, unsigned char* smem) {
;     ...
; #pragma unroll
;   for (int mq = 0; mq < 4; ++mq) {
; #pragma unroll
;     for (int mh = 0; mh < 2; ++mh)
; #pragma unroll
;       for (int ni = 0; ni < 4; ++ni)
; #pragma unroll
;         for (int j = 0; j < 4; ++j) st[(mh * 16 + fq * 4 + j) * 68 + ni * 16 + fr] = acc[mq * 2 + mh][ni][j];
; #pragma unroll
;     for (int itr = 0; itr < 8; ++itr) {
;       const int rl = (lane >> 4) + 4 * itr;
;       const f32x4 v = *(const f32x4*)(st + rl * 68 + chunk * 4);
;       const size_t idx = (size_t)(m0 + wr * 128 + mq * 32 + rl) * 2048 + n0 + wc * 64 + chunk * 4;
;       const f32x4 x = *(const f32x4*)(xres + idx);
;       *(f32x4*)(out + idx) = x + v;
;     }
;   }
	v_pk_add_f32 v[68:69], v[68:69], v[72:73]
	v_pk_add_f32 v[66:67], v[66:67], v[70:71]
	global_store_dwordx4 v[64:65], v[66:69], off
	ds_write_b32 v103, v60
	ds_write_b32 v103, v61 offset:272
	ds_write_b32 v103, v62 offset:544
	ds_write_b32 v103, v63 offset:816
	ds_write_b32 v103, v56 offset:64
	ds_write_b32 v103, v57 offset:336
	ds_write_b32 v103, v58 offset:608
	ds_write_b32 v103, v59 offset:880
	ds_write_b32 v103, v52 offset:128
	ds_write_b32 v103, v53 offset:400
	ds_write_b32 v103, v54 offset:672
	ds_write_b32 v103, v55 offset:944
	ds_write_b32 v103, v48 offset:192
	ds_write_b32 v103, v49 offset:464
	ds_write_b32 v103, v50 offset:736
	ds_write_b32 v103, v51 offset:1008
	ds_write_b32 v103, v44 offset:4352
	ds_write_b32 v103, v45 offset:4624
	ds_write_b32 v103, v46 offset:4896
	ds_write_b32 v103, v47 offset:5168
	ds_write_b32 v103, v40 offset:4416
	ds_write_b32 v103, v41 offset:4688
	ds_write_b32 v103, v42 offset:4960
	ds_write_b32 v103, v43 offset:5232
	ds_write_b32 v103, v36 offset:4480
	ds_write_b32 v103, v37 offset:4752
	ds_write_b32 v103, v38 offset:5024
	ds_write_b32 v103, v39 offset:5296
	ds_write_b32 v103, v32 offset:4544
	ds_write_b32 v103, v33 offset:4816
	ds_write_b32 v103, v34 offset:5088
	ds_write_b32 v103, v35 offset:5360
	v_or_b32_e32 v32, 64, v101
	v_or_b32_e32 v38, v32, v100
	v_ashrrev_i32_e32 v39, 31, v38
	v_lshlrev_b64 v[38:39], 13, v[38:39]
	v_lshl_add_u64 v[42:43], v[96:97], 0, v[38:39]
	global_load_dwordx4 v[38:41], v[42:43], off
	ds_read_b128 v[34:37], v102
	s_waitcnt vmcnt(0) lgkmcnt(0)
	v_pk_add_f32 v[34:35], v[34:35], v[38:39]
	v_or_b32_e32 v38, v32, v99
	v_ashrrev_i32_e32 v39, 31, v38
	v_pk_add_f32 v[36:37], v[36:37], v[40:41]
	v_lshlrev_b64 v[38:39], 13, v[38:39]
	global_store_dwordx4 v[42:43], v[34:37], off
	v_lshl_add_u64 v[42:43], v[96:97], 0, v[38:39]
	global_load_dwordx4 v[38:41], v[42:43], off
	ds_read_b128 v[34:37], v98
	s_waitcnt vmcnt(0) lgkmcnt(0)
	v_pk_add_f32 v[34:35], v[34:35], v[38:39]
	v_or_b32_e32 v38, v32, v104
	v_ashrrev_i32_e32 v39, 31, v38
	v_pk_add_f32 v[36:37], v[36:37], v[40:41]
	v_lshlrev_b64 v[38:39], 13, v[38:39]
	global_store_dwordx4 v[42:43], v[34:37], off
	v_lshl_add_u64 v[42:43], v[96:97], 0, v[38:39]
	global_load_dwordx4 v[38:41], v[42:43], off
	ds_read_b128 v[34:37], v98 offset:1088
	s_waitcnt vmcnt(0) lgkmcnt(0)
	v_pk_add_f32 v[34:35], v[34:35], v[38:39]
	v_or_b32_e32 v38, v32, v105
	v_ashrrev_i32_e32 v39, 31, v38
	v_pk_add_f32 v[36:37], v[36:37], v[40:41]
	v_lshlrev_b64 v[38:39], 13, v[38:39]
	global_store_dwordx4 v[42:43], v[34:37], off
	v_lshl_add_u64 v[42:43], v[96:97], 0, v[38:39]
	global_load_dwordx4 v[38:41], v[42:43], off
	ds_read_b128 v[34:37], v98 offset:2176
	s_waitcnt vmcnt(0) lgkmcnt(0)
	v_pk_add_f32 v[34:35], v[34:35], v[38:39]
	v_or_b32_e32 v38, v32, v106
	v_ashrrev_i32_e32 v39, 31, v38
	v_pk_add_f32 v[36:37], v[36:37], v[40:41]
	v_lshlrev_b64 v[38:39], 13, v[38:39]
	global_store_dwordx4 v[42:43], v[34:37], off
	v_lshl_add_u64 v[42:43], v[96:97], 0, v[38:39]
	global_load_dwordx4 v[38:41], v[42:43], off
	ds_read_b128 v[34:37], v98 offset:3264
	s_waitcnt vmcnt(0) lgkmcnt(0)
	v_pk_add_f32 v[34:35], v[34:35], v[38:39]
	v_or_b32_e32 v38, v32, v107
	v_ashrrev_i32_e32 v39, 31, v38
	v_pk_add_f32 v[36:37], v[36:37], v[40:41]
	v_lshlrev_b64 v[38:39], 13, v[38:39]
	global_store_dwordx4 v[42:43], v[34:37], off
	v_lshl_add_u64 v[42:43], v[96:97], 0, v[38:39]
	global_load_dwordx4 v[38:41], v[42:43], off
	ds_read_b128 v[34:37], v98 offset:4352
	s_waitcnt vmcnt(0) lgkmcnt(0)
	v_pk_add_f32 v[34:35], v[34:35], v[38:39]
	v_or_b32_e32 v38, v32, v108
	v_ashrrev_i32_e32 v39, 31, v38
	v_pk_add_f32 v[36:37], v[36:37], v[40:41]
	v_lshlrev_b64 v[38:39], 13, v[38:39]
	global_store_dwordx4 v[42:43], v[34:37], off
	v_lshl_add_u64 v[42:43], v[96:97], 0, v[38:39]
	global_load_dwordx4 v[38:41], v[42:43], off
	ds_read_b128 v[34:37], v98 offset:5440
	v_or_b32_e32 v32, v32, v109
	v_ashrrev_i32_e32 v33, 31, v32
	v_lshlrev_b64 v[32:33], 13, v[32:33]
	v_lshl_add_u64 v[32:33], v[96:97], 0, v[32:33]
	s_waitcnt vmcnt(0) lgkmcnt(0)
	v_pk_add_f32 v[36:37], v[36:37], v[40:41]
	v_pk_add_f32 v[34:35], v[34:35], v[38:39]
	global_load_dwordx4 v[38:41], v[32:33], off
	s_nop 0
	global_store_dwordx4 v[42:43], v[34:37], off
	ds_read_b128 v[34:37], v98 offset:6528
	s_waitcnt vmcnt(1) lgkmcnt(0)
; DEV void store_tile_f32_add(const f32x4 (&acc)[8][4], const float* xres, float* out, int m0, int n0, unsigned char* smem) {
;     ...
; #pragma unroll
;   for (int mq = 0; mq < 4; ++mq) {
; #pragma unroll
;     for (int mh = 0; mh < 2; ++mh)
; #pragma unroll
;       for (int ni = 0; ni < 4; ++ni)
; #pragma unroll
;         for (int j = 0; j < 4; ++j) st[(mh * 16 + fq * 4 + j) * 68 + ni * 16 + fr] = acc[mq * 2 + mh][ni][j];
; #pragma unroll
;     for (int itr = 0; itr < 8; ++itr) {
;       const int rl = (lane >> 4) + 4 * itr;
;       const f32x4 v = *(const f32x4*)(st + rl * 68 + chunk * 4);
;       const size_t idx = (size_t)(m0 + wr * 128 + mq * 32 + rl) * 2048 + n0 + wc * 64 + chunk * 4;
;       const f32x4 x = *(const f32x4*)(xres + idx);
;       *(f32x4*)(out + idx) = x + v;
;     }
;   }
	v_pk_add_f32 v[36:37], v[36:37], v[40:41]
	v_pk_add_f32 v[34:35], v[34:35], v[38:39]
	global_store_dwordx4 v[32:33], v[34:37], off
	ds_write_b32 v103, v28
	ds_write_b32 v103, v29 offset:272
	ds_write_b32 v103, v30 offset:544
	ds_write_b32 v103, v31 offset:816
	ds_write_b32 v103, v24 offset:64
	ds_write_b32 v103, v25 offset:336
	ds_write_b32 v103, v26 offset:608
	ds_write_b32 v103, v27 offset:880
	ds_write_b32 v103, v20 offset:128
	ds_write_b32 v103, v21 offset:400
	ds_write_b32 v103, v22 offset:672
	ds_write_b32 v103, v23 offset:944
	ds_write_b32 v103, v16 offset:192
	ds_write_b32 v103, v17 offset:464
	ds_write_b32 v103, v18 offset:736
	ds_write_b32 v103, v19 offset:1008
	ds_write_b32 v103, v12 offset:4352
	ds_write_b32 v103, v13 offset:4624
	ds_write_b32 v103, v14 offset:4896
	ds_write_b32 v103, v15 offset:5168
	ds_write_b32 v103, v8 offset:4416
	ds_write_b32 v103, v9 offset:4688
	ds_write_b32 v103, v10 offset:4960
	ds_write_b32 v103, v11 offset:5232
	ds_write_b32 v103, v4 offset:4480
	ds_write_b32 v103, v5 offset:4752
	ds_write_b32 v103, v6 offset:5024
	ds_write_b32 v103, v7 offset:5296
	ds_write_b32 v103, v0 offset:4544
	ds_write_b32 v103, v1 offset:4816
	ds_write_b32 v103, v2 offset:5088
	ds_write_b32 v103, v3 offset:5360
	v_or_b32_e32 v10, 0x60, v101
	v_or_b32_e32 v4, v10, v100
	v_ashrrev_i32_e32 v5, 31, v4
	v_lshlrev_b64 v[4:5], 13, v[4:5]
	v_lshl_add_u64 v[8:9], v[96:97], 0, v[4:5]
	global_load_dwordx4 v[4:7], v[8:9], off
	ds_read_b128 v[0:3], v102
	s_waitcnt vmcnt(0) lgkmcnt(0)
	v_pk_add_f32 v[0:1], v[0:1], v[4:5]
	v_or_b32_e32 v4, v10, v99
	v_ashrrev_i32_e32 v5, 31, v4
	v_pk_add_f32 v[2:3], v[2:3], v[6:7]
	v_lshlrev_b64 v[4:5], 13, v[4:5]
	global_store_dwordx4 v[8:9], v[0:3], off
	v_lshl_add_u64 v[8:9], v[96:97], 0, v[4:5]
	global_load_dwordx4 v[4:7], v[8:9], off
	ds_read_b128 v[0:3], v98
	s_waitcnt vmcnt(0) lgkmcnt(0)
	v_pk_add_f32 v[0:1], v[0:1], v[4:5]
	v_or_b32_e32 v4, v10, v104
	v_ashrrev_i32_e32 v5, 31, v4
	v_pk_add_f32 v[2:3], v[2:3], v[6:7]
	v_lshlrev_b64 v[4:5], 13, v[4:5]
	global_store_dwordx4 v[8:9], v[0:3], off
	v_lshl_add_u64 v[8:9], v[96:97], 0, v[4:5]
	global_load_dwordx4 v[4:7], v[8:9], off
	ds_read_b128 v[0:3], v98 offset:1088
	s_waitcnt vmcnt(0) lgkmcnt(0)
	v_pk_add_f32 v[0:1], v[0:1], v[4:5]
	v_or_b32_e32 v4, v10, v105
	v_ashrrev_i32_e32 v5, 31, v4
	v_pk_add_f32 v[2:3], v[2:3], v[6:7]
	v_lshlrev_b64 v[4:5], 13, v[4:5]
	global_store_dwordx4 v[8:9], v[0:3], off
	v_lshl_add_u64 v[8:9], v[96:97], 0, v[4:5]
	global_load_dwordx4 v[4:7], v[8:9], off
	ds_read_b128 v[0:3], v98 offset:2176
	s_waitcnt vmcnt(0) lgkmcnt(0)
	v_pk_add_f32 v[0:1], v[0:1], v[4:5]
	v_or_b32_e32 v4, v10, v106
	v_ashrrev_i32_e32 v5, 31, v4
	v_pk_add_f32 v[2:3], v[2:3], v[6:7]
	v_lshlrev_b64 v[4:5], 13, v[4:5]
	global_store_dwordx4 v[8:9], v[0:3], off
	v_lshl_add_u64 v[8:9], v[96:97], 0, v[4:5]
	global_load_dwordx4 v[4:7], v[8:9], off
	ds_read_b128 v[0:3], v98 offset:3264
	s_waitcnt vmcnt(0) lgkmcnt(0)
	v_pk_add_f32 v[0:1], v[0:1], v[4:5]
	v_or_b32_e32 v4, v10, v107
	v_ashrrev_i32_e32 v5, 31, v4
	v_pk_add_f32 v[2:3], v[2:3], v[6:7]
	v_lshlrev_b64 v[4:5], 13, v[4:5]
	global_store_dwordx4 v[8:9], v[0:3], off
	v_lshl_add_u64 v[8:9], v[96:97], 0, v[4:5]
	global_load_dwordx4 v[4:7], v[8:9], off
	ds_read_b128 v[0:3], v98 offset:4352
	s_waitcnt vmcnt(0) lgkmcnt(0)
	v_pk_add_f32 v[0:1], v[0:1], v[4:5]
	v_or_b32_e32 v4, v10, v108
	v_ashrrev_i32_e32 v5, 31, v4
	v_pk_add_f32 v[2:3], v[2:3], v[6:7]
	v_lshlrev_b64 v[4:5], 13, v[4:5]
	global_store_dwordx4 v[8:9], v[0:3], off
	v_lshl_add_u64 v[8:9], v[96:97], 0, v[4:5]
	global_load_dwordx4 v[4:7], v[8:9], off
	ds_read_b128 v[0:3], v98 offset:5440
	s_waitcnt vmcnt(0) lgkmcnt(0)
	v_pk_add_f32 v[0:1], v[0:1], v[4:5]
	v_or_b32_e32 v4, v10, v109
	v_ashrrev_i32_e32 v5, 31, v4
	v_pk_add_f32 v[2:3], v[2:3], v[6:7]
	v_lshlrev_b64 v[4:5], 13, v[4:5]
	global_store_dwordx4 v[8:9], v[0:3], off
	v_lshl_add_u64 v[8:9], v[96:97], 0, v[4:5]
	global_load_dwordx4 v[4:7], v[8:9], off
	ds_read_b128 v[0:3], v98 offset:6528
	s_waitcnt vmcnt(0) lgkmcnt(0)
	v_pk_add_f32 v[2:3], v[2:3], v[6:7]
	v_pk_add_f32 v[0:1], v[0:1], v[4:5]
	global_store_dwordx4 v[8:9], v[0:3], off
	s_branch .LBB0_191

; DEV int TID() { int t = threadIdx.x; asm volatile("" : "+v"(t)); return t; }
; DEV void gemm_tile(const u16* __restrict__ A, size_t lda, const u16* __restrict__ Bt, size_t ldb, int K,
;                    u16* sA, u16* sB, f32x4 (&acc)[8][4]) {
;   const int tid = TID(), lane = tid & 63, wid = tid >> 6;
;   const int wr = wid >> 1, wc = wid & 1, fr = lane & 15, fq = lane >> 4;
; #pragma unroll
;   for (int mi = 0; mi < 8; ++mi)
; #pragma unroll
;     for (int ni = 0; ni < 4; ++ni) acc[mi][ni] = f32x4{0.f, 0.f, 0.f, 0.f};
;   const int lr = tid >> 2, lc = (tid & 3) * 8;
;   const u16* ap = A + (size_t)lr * lda + lc;
;   const u16* bp = Bt + (size_t)lr * ldb + lc;
;   u32x4 ra[4], rb[2];
;     ...
;   const int nk = K >> 5;
;   const int swz = ((fq ^ ((0 - (fr >> 2)) & 3)) << 3);
;   const u16* sAr = sA + (wr * 128 + fr) * 32 + swz;
;   const u16* sBr = sA + 256 * 32 + (wc * 64 + fr) * 32 + swz;
;   G_LOAD(0)
;   __syncthreads();
;   S_STORE(0)
;   if (nk > 1) G_LOAD(32)
;   __syncthreads();
; PHASE void gemm_up_phase(const u16* H, const u16* WTUP, int jc, u16* U, unsigned char* smem) {
;     ...
;   for (int it = 0; it < nit; ++it) {
;     int mt, nt;
;     if (!tile_map(it, 32, mt, nt)) continue;
;     const int m0 = mt * 256;
;     const int wrow = (nt < 16) ? (jc * 2048 + nt * 128) : (6144 + jc * 2048 + (nt - 16) * 128);
;     f32x4 acc[8][4];
;     gemm_tile(H + (size_t)m0 * 2048, 2048, WTUP + (size_t)wrow * 2048, 2048, 2048, sA, sB, acc);
.LBB0_225:
	s_lshl_b32 s4, s8, 8
	s_lshl_b32 s18, s9, 7
	s_cmp_lt_i32 s9, 16
	s_cselect_b32 s5, s12, s14
	s_add_i32 s6, s5, s18
	s_ashr_i32 s5, s4, 31
	v_mov_b32_e32 v7, v178
	s_lshl_b64 s[8:9], s[4:5], 12
	s_add_u32 s22, s64, s8
	v_ashrrev_i32_e32 v32, 2, v7
	v_ashrrev_i32_e32 v33, 31, v32
	s_addc_u32 s23, s65, s9
	s_ashr_i32 s7, s6, 31
	v_lshlrev_b64 v[34:35], 12, v[32:33]
	v_lshlrev_b32_e32 v2, 4, v7
	s_lshl_b64 s[10:11], s[6:7], 12
	v_readlane_b32 s6, v250, 28
	v_lshl_add_u64 v[0:1], s[22:23], 0, v[34:35]
	v_and_b32_e32 v156, 48, v2
	v_readlane_b32 s7, v250, 29
	s_add_u32 s6, s6, s10
	v_lshl_add_u64 v[36:37], v[0:1], 0, v[156:157]
	s_mov_b32 s5, 0x40000
	s_addc_u32 s7, s7, s11
	v_add_co_u32_e32 v38, vcc, s5, v36
	v_lshl_add_u64 v[0:1], s[6:7], 0, v[34:35]
	s_nop 0
	v_addc_co_u32_e32 v39, vcc, 0, v37, vcc
	s_mov_b32 s6, 0x80000
	v_add_co_u32_e32 v40, vcc, s6, v36
	s_mov_b32 s6, 0xc0000
	s_nop 0
	v_addc_co_u32_e32 v41, vcc, 0, v37, vcc
	v_add_co_u32_e32 v42, vcc, s6, v36
	v_lshl_add_u64 v[44:45], v[0:1], 0, v[156:157]
	s_nop 0
	v_addc_co_u32_e32 v43, vcc, 0, v37, vcc
	v_add_co_u32_e32 v46, vcc, s5, v44
	v_addc_co_u32_e32 v47, vcc, 0, v45, vcc
	s_barrier
	v_lshrrev_b32_e32 v48, 2, v7
	v_lshrrev_b32_e32 v33, 4, v7
	v_sub_u32_e32 v48, 0, v48
	v_sub_u32_e32 v49, 0, v33
	v_xor_b32_e32 v33, v33, v48
	v_lshlrev_b32_e32 v50, 6, v7
	v_xor_b32_e32 v7, v7, v49
	v_lshlrev_b32_e32 v33, 4, v33
	v_lshlrev_b32_e32 v7, 4, v7
	v_lshl_add_u64 v[48:49], v[34:35], 0, s[8:9]
	v_and_b32_e32 v33, 48, v33
	s_movk_i32 s8, 0xe3c0
	v_and_b32_e32 v7, 48, v7
	v_and_or_b32 v162, v50, s8, v33
	s_movk_i32 s8, 0x13c0
	v_lshl_or_b32 v164, v32, 6, v7
	v_and_or_b32 v163, v50, s8, v33
	v_lshl_add_u64 v[32:33], v[34:35], 0, s[10:11]
	v_mov_b32_e32 v0, 0
	v_or_b32_e32 v48, v48, v156
	v_or_b32_e32 v32, v32, v156
	s_mov_b32 s5, 0
	s_mov_b64 s[6:7], 0
	v_mov_b32_e32 v1, v0
	v_mov_b32_e32 v2, v0
	v_mov_b32_e32 v3, v0
	v_mov_b32_e32 v4, v0
	v_mov_b32_e32 v5, v0
	v_mov_b32_e32 v6, v0
	v_lshl_add_u64 v[158:159], s[46:47], 0, v[48:49]
	v_lshl_add_u64 v[160:161], s[46:47], 0, v[32:33]
	v_mov_b32_e32 v7, v0
	v_mov_b32_e32 v32, v0
	v_mov_b32_e32 v33, v0
	v_mov_b32_e32 v34, v0
	v_mov_b32_e32 v35, v0
	v_mov_b32_e32 v36, v0
	v_mov_b32_e32 v37, v0
	v_mov_b32_e32 v38, v0
	v_mov_b32_e32 v39, v0
	v_mov_b32_e32 v40, v0
	v_mov_b32_e32 v41, v0
	v_mov_b32_e32 v42, v0
	v_mov_b32_e32 v43, v0
	v_mov_b32_e32 v8, v0
	v_mov_b32_e32 v9, v0
	v_mov_b32_e32 v10, v0
	v_mov_b32_e32 v11, v0
	v_mov_b32_e32 v12, v0
	v_mov_b32_e32 v13, v0
	v_mov_b32_e32 v14, v0
	v_mov_b32_e32 v15, v0
	v_mov_b32_e32 v16, v0
	v_mov_b32_e32 v17, v0
	v_mov_b32_e32 v18, v0
	v_mov_b32_e32 v19, v0
	v_mov_b32_e32 v20, v0
	v_mov_b32_e32 v21, v0
	v_mov_b32_e32 v22, v0
	v_mov_b32_e32 v23, v0
	v_mov_b32_e32 v24, v0
	v_mov_b32_e32 v25, v0
	v_mov_b32_e32 v26, v0
	v_mov_b32_e32 v27, v0
	v_mov_b32_e32 v28, v0
	v_mov_b32_e32 v29, v0
	v_mov_b32_e32 v30, v0
	v_mov_b32_e32 v31, v0
	v_mov_b32_e32 v44, v0
	v_mov_b32_e32 v45, v0
	v_mov_b32_e32 v46, v0
	v_mov_b32_e32 v47, v0
	v_mov_b32_e32 v48, v0
	v_mov_b32_e32 v49, v0
	v_mov_b32_e32 v50, v0
	v_mov_b32_e32 v51, v0
	v_mov_b32_e32 v52, v0
	v_mov_b32_e32 v53, v0
	v_mov_b32_e32 v54, v0
	v_mov_b32_e32 v55, v0
	v_mov_b32_e32 v56, v0
	v_mov_b32_e32 v57, v0
	v_mov_b32_e32 v58, v0
	v_mov_b32_e32 v59, v0
	v_mov_b32_e32 v60, v0
	v_mov_b32_e32 v61, v0
	v_mov_b32_e32 v62, v0
	v_mov_b32_e32 v63, v0
	v_mov_b32_e32 v64, v0
	v_mov_b32_e32 v65, v0
	v_mov_b32_e32 v66, v0
	v_mov_b32_e32 v67, v0
	v_mov_b32_e32 v68, v0
	v_mov_b32_e32 v69, v0
	v_mov_b32_e32 v70, v0
	v_mov_b32_e32 v71, v0
	v_mov_b32_e32 v72, v0
	v_mov_b32_e32 v73, v0
	v_mov_b32_e32 v74, v0
	v_mov_b32_e32 v75, v0
	v_mov_b32_e32 v76, v0
	v_mov_b32_e32 v77, v0
	v_mov_b32_e32 v78, v0
	v_mov_b32_e32 v79, v0
	v_mov_b32_e32 v80, v0
	v_mov_b32_e32 v81, v0
	v_mov_b32_e32 v82, v0
	v_mov_b32_e32 v83, v0
	v_mov_b32_e32 v84, v0
	v_mov_b32_e32 v85, v0
	v_mov_b32_e32 v86, v0
	v_mov_b32_e32 v87, v0
	v_mov_b32_e32 v88, v0
	v_mov_b32_e32 v89, v0
	v_mov_b32_e32 v90, v0
	v_mov_b32_e32 v91, v0
	v_mov_b32_e32 v92, v0
	v_mov_b32_e32 v93, v0
	v_mov_b32_e32 v94, v0
	v_mov_b32_e32 v95, v0
	v_mov_b32_e32 v96, v0
	v_mov_b32_e32 v97, v0
	v_mov_b32_e32 v98, v0
	v_mov_b32_e32 v99, v0
	v_mov_b32_e32 v100, v0
	v_mov_b32_e32 v101, v0
	v_mov_b32_e32 v102, v0
	v_mov_b32_e32 v103, v0
	v_mov_b32_e32 v104, v0
	v_mov_b32_e32 v105, v0
	v_mov_b32_e32 v106, v0
	v_mov_b32_e32 v107, v0
	v_mov_b32_e32 v108, v0
	v_mov_b32_e32 v109, v0
	v_mov_b32_e32 v110, v0
	v_mov_b32_e32 v111, v0
	v_mov_b32_e32 v112, v0
	v_mov_b32_e32 v113, v0
	v_mov_b32_e32 v114, v0
	v_mov_b32_e32 v115, v0
	v_mov_b32_e32 v116, v0
	v_mov_b32_e32 v117, v0
	v_mov_b32_e32 v118, v0
	v_mov_b32_e32 v119, v0
	v_mov_b32_e32 v144, v0
	v_mov_b32_e32 v145, v0
	v_mov_b32_e32 v146, v0
	v_mov_b32_e32 v147, v0
	v_mov_b32_e32 v148, v0
	v_mov_b32_e32 v149, v0
	v_mov_b32_e32 v150, v0
	v_mov_b32_e32 v151, v0
	s_mov_b32 s10, 0xa6d0000
	s_mov_b32 s11, 0xa710000
	s_waitcnt lgkmcnt(0)
	s_barrier
; DEV f32x4 mfma16(bf16x8 a, bf16x8 b, f32x4 c) { return __builtin_amdgcn_mfma_f32_16x16x32_bf16(a, b, c, 0, 0, 0); }
; DEV void gemm_tile(const u16* __restrict__ A, size_t lda, const u16* __restrict__ Bt, size_t ldb, int K,
;                    u16* sA, u16* sB, f32x4 (&acc)[8][4]) {
;     ...
;   G_LOAD(0)
;   __syncthreads();
;   S_STORE(0)
;   if (nk > 1) G_LOAD(32)
;   __syncthreads();
;   for (int kt = 0; kt < nk; ++kt) {
;     const int st = kt & 1;
;     if (kt + 1 < nk) S_STORE(st ^ 1)
;     if (kt + 2 < nk) G_LOAD((kt + 2) << 5)
;     {
;       const u16* pa = sAr + st * 12288;
;       const u16* pb = sBr + st * 12288;
;       bf16x8 b[4];
; #pragma unroll
;       for (int ni = 0; ni < 4; ++ni) b[ni] = *(const bf16x8*)(pb + ni * 16 * 32);
; #pragma unroll
;       for (int mh = 0; mh < 2; ++mh) {
;         bf16x8 a[4];
; #pragma unroll
;         for (int mi = 0; mi < 4; ++mi) a[mi] = *(const bf16x8*)(pa + (mh * 64 + mi * 16) * 32);
; #pragma unroll
;         for (int mi = 0; mi < 4; ++mi)
; #pragma unroll
;           for (int ni = 0; ni < 4; ++ni) acc[mh * 4 + mi][ni] = mfma16(a[mi], b[ni], acc[mh * 4 + mi][ni]);
;       }
;     }
;     __syncthreads();
;   }
	v_lshl_add_u64 v[132:133], v[158:159], 0, s[6:7]
	v_add_co_u32_e32 v136, vcc, s10, v132
	s_nop 1
	v_addc_co_u32_e32 v137, vcc, 0, v133, vcc
	v_add_co_u32_e32 v138, vcc, s11, v132
	s_nop 1
	v_addc_co_u32_e32 v139, vcc, 0, v133, vcc
	v_add_co_u32_e32 v174, vcc, s95, v132
	s_nop 1
	v_addc_co_u32_e32 v175, vcc, 0, v133, vcc
	v_add_co_u32_e32 v176, vcc, s74, v132
	v_lshl_add_u64 v[134:135], v[160:161], 0, s[6:7]
	s_nop 1
	v_addc_co_u32_e32 v177, vcc, 0, v133, vcc
	s_mov_b32 s8, 0x5dd0000
	v_add_co_u32_e32 v186, vcc, s8, v134
	s_nop 1
	v_addc_co_u32_e32 v187, vcc, 0, v135, vcc
	s_mov_b32 s8, 0x5e10000
	v_add_co_u32_e32 v188, vcc, s8, v134
	s_nop 1
	v_addc_co_u32_e32 v189, vcc, 0, v135, vcc
	v_lshrrev_b32_e32 v228, 4, v178
	v_sub_u32_e32 v228, 0, v228
	v_and_b32_e32 v228, 3, v228
	v_lshlrev_b32_e32 v228, 4, v228
	v_lshrrev_b32_e32 v229, 6, v178
	v_lshlrev_b32_e32 v229, 10, v229
	v_xor_b32_e32 v136, v136, v228
	v_xor_b32_e32 v138, v138, v228
	v_xor_b32_e32 v174, v174, v228
	v_xor_b32_e32 v176, v176, v228
	v_xor_b32_e32 v186, v186, v228
	v_xor_b32_e32 v188, v188, v228
	v_readfirstlane_b32 s5, v229
	s_nop 1
	s_add_i32 s9, s5, 0x6000
	s_add_i32 m0, s9, 0x0
	s_nop 0
	global_load_lds_dwordx4 v[136:137], off
	v_lshl_add_u64 v[136:137], v[136:137], 0, 64
	s_add_i32 m0, s9, 0x1000
	s_nop 0
	global_load_lds_dwordx4 v[138:139], off
	v_lshl_add_u64 v[138:139], v[138:139], 0, 64
	s_add_i32 m0, s9, 0x2000
	s_nop 0
	global_load_lds_dwordx4 v[174:175], off
	v_lshl_add_u64 v[174:175], v[174:175], 0, 64
	s_add_i32 m0, s9, 0x3000
	s_nop 0
	global_load_lds_dwordx4 v[176:177], off
	v_lshl_add_u64 v[176:177], v[176:177], 0, 64
	s_add_i32 m0, s9, 0x4000
	s_nop 0
	global_load_lds_dwordx4 v[186:187], off
	v_lshl_add_u64 v[186:187], v[186:187], 0, 64
	s_add_i32 m0, s9, 0x5000
	s_nop 0
	global_load_lds_dwordx4 v[188:189], off
	v_lshl_add_u64 v[188:189], v[188:189], 0, 64
	s_add_i32 s9, s5, 0xc000
	s_add_i32 m0, s9, 0x0
	s_nop 0
	global_load_lds_dwordx4 v[136:137], off
	v_lshl_add_u64 v[136:137], v[136:137], 0, 64
	s_add_i32 m0, s9, 0x1000
	s_nop 0
	global_load_lds_dwordx4 v[138:139], off
	v_lshl_add_u64 v[138:139], v[138:139], 0, 64
	s_add_i32 m0, s9, 0x2000
	s_nop 0
	global_load_lds_dwordx4 v[174:175], off
	v_lshl_add_u64 v[174:175], v[174:175], 0, 64
	s_add_i32 m0, s9, 0x3000
	s_nop 0
	global_load_lds_dwordx4 v[176:177], off
	v_lshl_add_u64 v[176:177], v[176:177], 0, 64
	s_add_i32 m0, s9, 0x4000
	s_nop 0
	global_load_lds_dwordx4 v[186:187], off
	v_lshl_add_u64 v[186:187], v[186:187], 0, 64
	s_add_i32 m0, s9, 0x5000
	s_nop 0
	global_load_lds_dwordx4 v[188:189], off
	v_lshl_add_u64 v[188:189], v[188:189], 0, 64
	v_and_b32_e32 v230, 63, v178
	v_lshlrev_b32_e32 v230, 4, v230
	s_mov_b32 s8, 0x6000
	s_mov_b32 s9, s5
	s_waitcnt vmcnt(6)
	s_barrier
.LBB0_226:
	v_add_u32_e32 v229, s8, v163
	v_add_u32_e32 v228, s8, v162
	ds_read_b128 v[120:123], v229 offset:16384
	ds_read_b128 v[166:169], v228
	ds_read_b128 v[128:131], v229 offset:17408
	ds_read_b128 v[140:143], v229 offset:18432
	ds_read_b128 v[124:127], v229 offset:19456
	ds_read_b128 v[152:155], v228 offset:1024
	ds_read_b128 v[170:173], v228 offset:2048
	ds_read_b128 v[132:135], v228 offset:3072
	s_waitcnt lgkmcnt(6)
	v_mfma_f32_16x16x32_bf16 v[148:151], v[166:169], v[120:123], v[148:151]
	s_add_i32 m0, s9, 0x0
	s_waitcnt lgkmcnt(5)
	v_mfma_f32_16x16x32_bf16 v[144:147], v[166:169], v[128:131], v[144:147]
	global_load_lds_dwordx4 v[136:137], off
	v_lshl_add_u64 v[136:137], v[136:137], 0, 64
	global_load_dwordx4 v[244:247], v[136:137], off
	v_lshl_add_u64 v[136:137], v[136:137], 0, 64
	s_waitcnt lgkmcnt(4)
	v_mfma_f32_16x16x32_bf16 v[116:119], v[166:169], v[140:143], v[116:119]
	s_add_i32 m0, s9, 0x1000
	s_waitcnt lgkmcnt(3)
	v_mfma_f32_16x16x32_bf16 v[112:115], v[166:169], v[124:127], v[112:115]
	ds_read_b128 v[232:235], v228 offset:4096
	ds_read_b128 v[236:239], v228 offset:5120
	s_waitcnt lgkmcnt(4)
	v_mfma_f32_16x16x32_bf16 v[108:111], v[152:155], v[120:123], v[108:111]
	global_load_lds_dwordx4 v[138:139], off
	v_lshl_add_u64 v[138:139], v[138:139], 0, 64
	global_load_dwordx4 v[252:255], v[138:139], off
	v_lshl_add_u64 v[138:139], v[138:139], 0, 64
	v_mfma_f32_16x16x32_bf16 v[104:107], v[152:155], v[128:131], v[104:107]
	s_add_i32 m0, s9, 0x2000
	v_mfma_f32_16x16x32_bf16 v[100:103], v[152:155], v[140:143], v[100:103]
	global_load_lds_dwordx4 v[174:175], off
	v_lshl_add_u64 v[174:175], v[174:175], 0, 64
	global_load_dwordx4 v[208:211], v[174:175], off
	v_lshl_add_u64 v[174:175], v[174:175], 0, 64
	v_mfma_f32_16x16x32_bf16 v[96:99], v[152:155], v[124:127], v[96:99]
	s_add_i32 m0, s9, 0x3000
	s_waitcnt lgkmcnt(3)
	v_mfma_f32_16x16x32_bf16 v[92:95], v[170:173], v[120:123], v[92:95]
	global_load_lds_dwordx4 v[176:177], off
	v_lshl_add_u64 v[176:177], v[176:177], 0, 64
	global_load_dwordx4 v[212:215], v[176:177], off
	v_lshl_add_u64 v[176:177], v[176:177], 0, 64
	v_mfma_f32_16x16x32_bf16 v[88:91], v[170:173], v[128:131], v[88:91]
	s_add_i32 m0, s9, 0x4000
	v_mfma_f32_16x16x32_bf16 v[84:87], v[170:173], v[140:143], v[84:87]
	global_load_lds_dwordx4 v[186:187], off
	v_lshl_add_u64 v[186:187], v[186:187], 0, 64
	global_load_dwordx4 v[216:219], v[186:187], off
	v_lshl_add_u64 v[186:187], v[186:187], 0, 64
	v_mfma_f32_16x16x32_bf16 v[80:83], v[170:173], v[124:127], v[80:83]
	ds_read_b128 v[240:243], v228 offset:6144
	ds_read_b128 v[166:169], v228 offset:7168
	s_waitcnt lgkmcnt(4)
	v_mfma_f32_16x16x32_bf16 v[76:79], v[132:135], v[120:123], v[76:79]
	s_add_i32 m0, s9, 0x5000
	v_mfma_f32_16x16x32_bf16 v[72:75], v[132:135], v[128:131], v[72:75]
	global_load_lds_dwordx4 v[188:189], off
	v_lshl_add_u64 v[188:189], v[188:189], 0, 64
	global_load_dwordx4 v[220:223], v[188:189], off
	v_lshl_add_u64 v[188:189], v[188:189], 0, 64
	v_mfma_f32_16x16x32_bf16 v[68:71], v[132:135], v[140:143], v[68:71]
	s_add_i32 s9, s8, s5
	s_add_i32 s8, s8, 0x6000
	v_mfma_f32_16x16x32_bf16 v[64:67], v[132:135], v[124:127], v[64:67]
	s_cmp_eq_u32 s8, 0x12000
	s_cselect_b32 s8, 0, s8
	s_waitcnt lgkmcnt(3)
	v_mfma_f32_16x16x32_bf16 v[60:63], v[232:235], v[120:123], v[60:63]
	s_add_u32 s6, s6, 64
	s_addc_u32 s7, s7, 0
	s_cmpk_lg_i32 s6, 0xf80
	v_mfma_f32_16x16x32_bf16 v[56:59], v[232:235], v[128:131], v[56:59]
	v_mfma_f32_16x16x32_bf16 v[52:55], v[232:235], v[140:143], v[52:55]
	v_mfma_f32_16x16x32_bf16 v[48:51], v[232:235], v[124:127], v[48:51]
	s_waitcnt lgkmcnt(2)
	v_mfma_f32_16x16x32_bf16 v[44:47], v[236:239], v[120:123], v[44:47]
	v_mfma_f32_16x16x32_bf16 v[40:43], v[236:239], v[128:131], v[40:43]
	v_mfma_f32_16x16x32_bf16 v[36:39], v[236:239], v[140:143], v[36:39]
	v_mfma_f32_16x16x32_bf16 v[32:35], v[236:239], v[124:127], v[32:35]
	s_waitcnt lgkmcnt(1)
	v_mfma_f32_16x16x32_bf16 v[28:31], v[240:243], v[120:123], v[28:31]
	v_mfma_f32_16x16x32_bf16 v[24:27], v[240:243], v[128:131], v[24:27]
	v_mfma_f32_16x16x32_bf16 v[20:23], v[240:243], v[140:143], v[20:23]
	v_mfma_f32_16x16x32_bf16 v[16:19], v[240:243], v[124:127], v[16:19]
	s_waitcnt lgkmcnt(0)
	s_waitcnt vmcnt(12)
	s_barrier
; DEV f32x4 mfma16(bf16x8 a, bf16x8 b, f32x4 c) { return __builtin_amdgcn_mfma_f32_16x16x32_bf16(a, b, c, 0, 0, 0); }
; DEV void gemm_tile(const u16* __restrict__ A, size_t lda, const u16* __restrict__ Bt, size_t ldb, int K,
;                    u16* sA, u16* sB, f32x4 (&acc)[8][4]) {
;     ...
;   for (int kt = 0; kt < nk; ++kt) {
;     const int st = kt & 1;
;     if (kt + 1 < nk) S_STORE(st ^ 1)
;     if (kt + 2 < nk) G_LOAD((kt + 2) << 5)
;     {
;       const u16* pa = sAr + st * 12288;
;       const u16* pb = sBr + st * 12288;
;       bf16x8 b[4];
; #pragma unroll
;       for (int ni = 0; ni < 4; ++ni) b[ni] = *(const bf16x8*)(pb + ni * 16 * 32);
; #pragma unroll
;       for (int mh = 0; mh < 2; ++mh) {
;         bf16x8 a[4];
; #pragma unroll
;         for (int mi = 0; mi < 4; ++mi) a[mi] = *(const bf16x8*)(pa + (mh * 64 + mi * 16) * 32);
; #pragma unroll
;         for (int mi = 0; mi < 4; ++mi)
; #pragma unroll
;           for (int ni = 0; ni < 4; ++ni) acc[mh * 4 + mi][ni] = mfma16(a[mi], b[ni], acc[mh * 4 + mi][ni]);
;       }
;     }
;     __syncthreads();
;   }
	v_mfma_f32_16x16x32_bf16 v[12:15], v[166:169], v[120:123], v[12:15]
	v_mfma_f32_16x16x32_bf16 v[8:11], v[166:169], v[128:131], v[8:11]
	v_mfma_f32_16x16x32_bf16 v[4:7], v[166:169], v[140:143], v[4:7]
	v_mfma_f32_16x16x32_bf16 v[0:3], v[166:169], v[124:127], v[0:3]
	v_add_u32_e32 v229, s8, v163
	v_add_u32_e32 v228, s8, v162
	ds_read_b128 v[120:123], v229 offset:16384
	ds_read_b128 v[166:169], v228
	ds_read_b128 v[128:131], v229 offset:17408
	ds_read_b128 v[140:143], v229 offset:18432
	ds_read_b128 v[124:127], v229 offset:19456
	ds_read_b128 v[152:155], v228 offset:1024
	ds_read_b128 v[170:173], v228 offset:2048
	ds_read_b128 v[132:135], v228 offset:3072
	s_waitcnt lgkmcnt(6)
	v_mfma_f32_16x16x32_bf16 v[148:151], v[166:169], v[120:123], v[148:151]
	s_waitcnt vmcnt(0)
	v_add_u32_e32 v231, s9, v230
	s_waitcnt lgkmcnt(5)
	v_mfma_f32_16x16x32_bf16 v[144:147], v[166:169], v[128:131], v[144:147]
	ds_write_b128 v231, v[244:247]
	s_waitcnt lgkmcnt(5)
	v_mfma_f32_16x16x32_bf16 v[116:119], v[166:169], v[140:143], v[116:119]
	ds_write_b128 v231, v[252:255] offset:4096
	s_waitcnt lgkmcnt(5)
	v_mfma_f32_16x16x32_bf16 v[112:115], v[166:169], v[124:127], v[112:115]
	ds_read_b128 v[232:235], v228 offset:4096
	ds_read_b128 v[236:239], v228 offset:5120
	s_waitcnt lgkmcnt(6)
	v_mfma_f32_16x16x32_bf16 v[108:111], v[152:155], v[120:123], v[108:111]
	ds_write_b128 v231, v[208:211] offset:8192
	v_mfma_f32_16x16x32_bf16 v[104:107], v[152:155], v[128:131], v[104:107]
	ds_write_b128 v231, v[212:215] offset:12288
	v_mfma_f32_16x16x32_bf16 v[100:103], v[152:155], v[140:143], v[100:103]
	ds_write_b128 v231, v[216:219] offset:16384
	v_mfma_f32_16x16x32_bf16 v[96:99], v[152:155], v[124:127], v[96:99]
	ds_write_b128 v231, v[220:223] offset:20480
	s_waitcnt lgkmcnt(9)
	v_mfma_f32_16x16x32_bf16 v[92:95], v[170:173], v[120:123], v[92:95]
	s_add_i32 s9, s8, s5
	s_add_i32 s8, s8, 0x6000
	v_mfma_f32_16x16x32_bf16 v[88:91], v[170:173], v[128:131], v[88:91]
	s_cmp_eq_u32 s8, 0x12000
	s_cselect_b32 s8, 0, s8
	v_mfma_f32_16x16x32_bf16 v[84:87], v[170:173], v[140:143], v[84:87]
	s_add_u32 s6, s6, 64
	s_addc_u32 s7, s7, 0
	s_cmpk_lg_i32 s6, 0xf80
	v_mfma_f32_16x16x32_bf16 v[80:83], v[170:173], v[124:127], v[80:83]
	ds_read_b128 v[240:243], v228 offset:6144
	ds_read_b128 v[166:169], v228 offset:7168
	s_waitcnt lgkmcnt(10)
	v_mfma_f32_16x16x32_bf16 v[76:79], v[132:135], v[120:123], v[76:79]
	v_mfma_f32_16x16x32_bf16 v[72:75], v[132:135], v[128:131], v[72:75]
	v_mfma_f32_16x16x32_bf16 v[68:71], v[132:135], v[140:143], v[68:71]
	v_mfma_f32_16x16x32_bf16 v[64:67], v[132:135], v[124:127], v[64:67]
	s_waitcnt lgkmcnt(7)
	v_mfma_f32_16x16x32_bf16 v[60:63], v[232:235], v[120:123], v[60:63]
	v_mfma_f32_16x16x32_bf16 v[56:59], v[232:235], v[128:131], v[56:59]
	v_mfma_f32_16x16x32_bf16 v[52:55], v[232:235], v[140:143], v[52:55]
	v_mfma_f32_16x16x32_bf16 v[48:51], v[232:235], v[124:127], v[48:51]
	s_waitcnt lgkmcnt(6)
	v_mfma_f32_16x16x32_bf16 v[44:47], v[236:239], v[120:123], v[44:47]
	v_mfma_f32_16x16x32_bf16 v[40:43], v[236:239], v[128:131], v[40:43]
	v_mfma_f32_16x16x32_bf16 v[36:39], v[236:239], v[140:143], v[36:39]
	v_mfma_f32_16x16x32_bf16 v[32:35], v[236:239], v[124:127], v[32:35]
	s_waitcnt lgkmcnt(1)
	v_mfma_f32_16x16x32_bf16 v[28:31], v[240:243], v[120:123], v[28:31]
	v_mfma_f32_16x16x32_bf16 v[24:27], v[240:243], v[128:131], v[24:27]
	v_mfma_f32_16x16x32_bf16 v[20:23], v[240:243], v[140:143], v[20:23]
	v_mfma_f32_16x16x32_bf16 v[16:19], v[240:243], v[124:127], v[16:19]
	s_waitcnt lgkmcnt(0)
	s_waitcnt lgkmcnt(0)
	s_barrier
	v_mfma_f32_16x16x32_bf16 v[12:15], v[166:169], v[120:123], v[12:15]
	v_mfma_f32_16x16x32_bf16 v[8:11], v[166:169], v[128:131], v[8:11]
	v_mfma_f32_16x16x32_bf16 v[4:7], v[166:169], v[140:143], v[4:7]
	v_mfma_f32_16x16x32_bf16 v[0:3], v[166:169], v[124:127], v[0:3]
	s_cbranch_scc1 .LBB0_226
	ds_read_b128 v[120:123], v163 offset:16384
	ds_read_b128 v[124:127], v163 offset:17408
	ds_read_b128 v[128:131], v163 offset:18432
	ds_read_b128 v[132:135], v163 offset:19456
	ds_read_b128 v[136:139], v162
	ds_read_b128 v[140:143], v162 offset:1024
	ds_read_b128 v[152:155], v162 offset:2048
	ds_read_b128 v[158:161], v162 offset:3072
	s_waitcnt lgkmcnt(3)
	v_mfma_f32_16x16x32_bf16 v[148:151], v[136:139], v[120:123], v[148:151]
	v_mfma_f32_16x16x32_bf16 v[144:147], v[136:139], v[124:127], v[144:147]
	v_mfma_f32_16x16x32_bf16 v[116:119], v[136:139], v[128:131], v[116:119]
	v_mfma_f32_16x16x32_bf16 v[112:115], v[136:139], v[132:135], v[112:115]
	s_waitcnt lgkmcnt(2)
	v_mfma_f32_16x16x32_bf16 v[108:111], v[140:143], v[120:123], v[108:111]
	v_mfma_f32_16x16x32_bf16 v[104:107], v[140:143], v[124:127], v[104:107]
	v_mfma_f32_16x16x32_bf16 v[100:103], v[140:143], v[128:131], v[100:103]
	v_mfma_f32_16x16x32_bf16 v[96:99], v[140:143], v[132:135], v[96:99]
	s_waitcnt lgkmcnt(1)
	v_mfma_f32_16x16x32_bf16 v[92:95], v[152:155], v[120:123], v[92:95]
	v_mfma_f32_16x16x32_bf16 v[88:91], v[152:155], v[124:127], v[88:91]
	v_mfma_f32_16x16x32_bf16 v[84:87], v[152:155], v[128:131], v[84:87]
	v_mfma_f32_16x16x32_bf16 v[80:83], v[152:155], v[132:135], v[80:83]
	s_waitcnt lgkmcnt(0)
	v_mfma_f32_16x16x32_bf16 v[76:79], v[158:161], v[120:123], v[76:79]
	v_mfma_f32_16x16x32_bf16 v[72:75], v[158:161], v[124:127], v[72:75]
	v_mfma_f32_16x16x32_bf16 v[68:71], v[158:161], v[128:131], v[68:71]
	v_mfma_f32_16x16x32_bf16 v[64:67], v[158:161], v[132:135], v[64:67]
	ds_read_b128 v[136:139], v162 offset:4096
	ds_read_b128 v[140:143], v162 offset:5120
	ds_read_b128 v[152:155], v162 offset:6144
	ds_read_b128 v[158:161], v162 offset:7168
	s_waitcnt lgkmcnt(0)
	s_waitcnt vmcnt(0)
	s_barrier
; DEV f32x4 mfma16(bf16x8 a, bf16x8 b, f32x4 c) { return __builtin_amdgcn_mfma_f32_16x16x32_bf16(a, b, c, 0, 0, 0); }
; DEV void gemm_tile(const u16* __restrict__ A, size_t lda, const u16* __restrict__ Bt, size_t ldb, int K,
;                    u16* sA, u16* sB, f32x4 (&acc)[8][4]) {
;     ...
;   for (int kt = 0; kt < nk; ++kt) {
;     const int st = kt & 1;
;     if (kt + 1 < nk) S_STORE(st ^ 1)
;     if (kt + 2 < nk) G_LOAD((kt + 2) << 5)
;     {
;       const u16* pa = sAr + st * 12288;
;       const u16* pb = sBr + st * 12288;
;       bf16x8 b[4];
; #pragma unroll
;       for (int ni = 0; ni < 4; ++ni) b[ni] = *(const bf16x8*)(pb + ni * 16 * 32);
; #pragma unroll
;       for (int mh = 0; mh < 2; ++mh) {
;         bf16x8 a[4];
; #pragma unroll
;         for (int mi = 0; mi < 4; ++mi) a[mi] = *(const bf16x8*)(pa + (mh * 64 + mi * 16) * 32);
; #pragma unroll
;         for (int mi = 0; mi < 4; ++mi)
; #pragma unroll
;           for (int ni = 0; ni < 4; ++ni) acc[mh * 4 + mi][ni] = mfma16(a[mi], b[ni], acc[mh * 4 + mi][ni]);
;       }
;     }
;     __syncthreads();
;   }
; DEV void store_tile_bf16(const f32x4 (&acc)[8][4], u16* __restrict__ OUT, size_t ld, int m0, int n0, int ncols,
;                          unsigned char* smem) {
;     ...
; #pragma unroll
;   for (int mh = 0; mh < 2; ++mh) {
; #pragma unroll
;     for (int mi = 0; mi < 4; ++mi)
; #pragma unroll
;       for (int ni = 0; ni < 4; ++ni)
; #pragma unroll
;         for (int j = 0; j < 4; ++j) st[(mi * 16 + fq * 4 + j) * 72 + ni * 16 + fr] = f2bf(acc[mh * 4 + mi][ni][j]);
	v_mfma_f32_16x16x32_bf16 v[60:63], v[136:139], v[120:123], v[60:63]
	v_mfma_f32_16x16x32_bf16 v[56:59], v[136:139], v[124:127], v[56:59]
	v_mfma_f32_16x16x32_bf16 v[52:55], v[136:139], v[128:131], v[52:55]
	v_mfma_f32_16x16x32_bf16 v[48:51], v[136:139], v[132:135], v[48:51]
	v_mfma_f32_16x16x32_bf16 v[44:47], v[140:143], v[120:123], v[44:47]
	v_mfma_f32_16x16x32_bf16 v[40:43], v[140:143], v[124:127], v[40:43]
	v_mfma_f32_16x16x32_bf16 v[36:39], v[140:143], v[128:131], v[36:39]
	v_mfma_f32_16x16x32_bf16 v[32:35], v[140:143], v[132:135], v[32:35]
	v_mfma_f32_16x16x32_bf16 v[28:31], v[152:155], v[120:123], v[28:31]
	v_mfma_f32_16x16x32_bf16 v[24:27], v[152:155], v[124:127], v[24:27]
	v_mfma_f32_16x16x32_bf16 v[20:23], v[152:155], v[128:131], v[20:23]
	v_mfma_f32_16x16x32_bf16 v[16:19], v[152:155], v[132:135], v[16:19]
	v_mfma_f32_16x16x32_bf16 v[12:15], v[158:161], v[120:123], v[12:15]
	v_mfma_f32_16x16x32_bf16 v[8:11], v[158:161], v[124:127], v[8:11]
	v_mfma_f32_16x16x32_bf16 v[4:7], v[158:161], v[128:131], v[4:7]
	v_mfma_f32_16x16x32_bf16 v[0:3], v[158:161], v[132:135], v[0:3]
	ds_read_b128 v[128:131], v163 offset:40960
	ds_read_b128 v[132:135], v163 offset:41984
	ds_read_b128 v[136:139], v163 offset:43008
	ds_read_b128 v[140:143], v163 offset:44032
	ds_read_b128 v[152:155], v162 offset:24576
	ds_read_b128 v[158:161], v162 offset:25600
	ds_read_b128 v[164:167], v162 offset:26624
	ds_read_b128 v[168:171], v162 offset:27648
	s_waitcnt lgkmcnt(3)
	v_mfma_f32_16x16x32_bf16 v[124:127], v[152:155], v[128:131], v[148:151]
	v_mfma_f32_16x16x32_bf16 v[120:123], v[152:155], v[132:135], v[144:147]
	v_mfma_f32_16x16x32_bf16 v[116:119], v[152:155], v[136:139], v[116:119]
	v_mfma_f32_16x16x32_bf16 v[112:115], v[152:155], v[140:143], v[112:115]
	s_waitcnt lgkmcnt(2)
	v_mfma_f32_16x16x32_bf16 v[108:111], v[158:161], v[128:131], v[108:111]
	v_mfma_f32_16x16x32_bf16 v[104:107], v[158:161], v[132:135], v[104:107]
	v_mfma_f32_16x16x32_bf16 v[100:103], v[158:161], v[136:139], v[100:103]
	v_mfma_f32_16x16x32_bf16 v[96:99], v[158:161], v[140:143], v[96:99]
	ds_read_b128 v[144:147], v162 offset:28672
	ds_read_b128 v[148:151], v162 offset:29696
	ds_read_b128 v[152:155], v162 offset:30720
	ds_read_b128 v[158:161], v162 offset:31744
	s_waitcnt lgkmcnt(0)
	s_barrier
	v_mfma_f32_16x16x32_bf16 v[92:95], v[164:167], v[128:131], v[92:95]
	v_mfma_f32_16x16x32_bf16 v[76:79], v[168:171], v[128:131], v[76:79]
	v_mfma_f32_16x16x32_bf16 v[60:63], v[144:147], v[128:131], v[60:63]
	v_mfma_f32_16x16x32_bf16 v[44:47], v[148:151], v[128:131], v[44:47]
	v_mfma_f32_16x16x32_bf16 v[28:31], v[152:155], v[128:131], v[28:31]
	v_mfma_f32_16x16x32_bf16 v[12:15], v[158:161], v[128:131], v[12:15]
	v_mov_b32_e32 v129, v178
	s_nop 0
	v_lshrrev_b32_e32 v128, 6, v129
	v_mfma_f32_16x16x32_bf16 v[88:91], v[164:167], v[132:135], v[88:91]
	v_mul_lo_u32 v131, v128, s75
	v_lshrrev_b32_e32 v128, 2, v129
	v_and_b32_e32 v130, 15, v129
	v_mfma_f32_16x16x32_bf16 v[72:75], v[168:171], v[132:135], v[72:75]
	v_lshl_or_b32 v130, v130, 1, v131
	v_mfma_f32_16x16x32_bf16 v[56:59], v[144:147], v[132:135], v[56:59]
	v_mfma_f32_16x16x32_bf16 v[40:43], v[148:151], v[132:135], v[40:43]
	v_mfma_f32_16x16x32_bf16 v[24:27], v[152:155], v[132:135], v[24:27]
	v_mfma_f32_16x16x32_bf16 v[8:11], v[158:161], v[132:135], v[8:11]
	v_lshlrev_b32_e32 v133, 3, v129
	v_and_b32_e32 v132, 12, v128
	v_and_b32_e32 v128, 64, v129
	v_and_b32_e32 v133, 56, v133
	v_or3_b32 v128, v128, s18, v133
	v_lshl_or_b32 v131, v133, 1, v131
	v_bfe_u32 v133, v129, 3, 3
	v_and_b32_e32 v129, 0xffffff80, v129
	v_add_u32_e32 v134, s4, v129
	v_bfe_u32 v135, v124, 16, 1
	s_movk_i32 s4, 0x90
	v_add3_u32 v135, v124, v135, s71
	v_mad_u32_u24 v124, v132, s4, v130
	v_bfe_u32 v130, v125, 16, 1
	v_add3_u32 v125, v125, v130, s71
	ds_write_b16_d16_hi v124, v125 offset:144
	v_bfe_u32 v125, v126, 16, 1
	v_add3_u32 v125, v126, v125, s71
	ds_write_b16_d16_hi v124, v125 offset:288
	v_bfe_u32 v125, v127, 16, 1
	v_add3_u32 v125, v127, v125, s71
	ds_write_b16_d16_hi v124, v125 offset:432
	v_bfe_u32 v125, v120, 16, 1
	v_add3_u32 v120, v120, v125, s71
	ds_write_b16_d16_hi v124, v120 offset:32
	v_bfe_u32 v120, v121, 16, 1
	v_add3_u32 v120, v121, v120, s71
	ds_write_b16_d16_hi v124, v120 offset:176
	v_bfe_u32 v120, v122, 16, 1
	v_add3_u32 v120, v122, v120, s71
	ds_write_b16_d16_hi v124, v120 offset:320
	v_bfe_u32 v120, v123, 16, 1
	v_add3_u32 v120, v123, v120, s71
	ds_write_b16_d16_hi v124, v120 offset:464
	v_bfe_u32 v120, v116, 16, 1
	v_add3_u32 v116, v116, v120, s71
	ds_write_b16_d16_hi v124, v116 offset:64
	v_bfe_u32 v116, v117, 16, 1
	v_add3_u32 v116, v117, v116, s71
	ds_write_b16_d16_hi v124, v116 offset:208
	v_bfe_u32 v116, v118, 16, 1
	v_add3_u32 v116, v118, v116, s71
	ds_write_b16_d16_hi v124, v116 offset:352
	v_bfe_u32 v116, v119, 16, 1
	v_add3_u32 v116, v119, v116, s71
	ds_write_b16_d16_hi v124, v116 offset:496
	v_bfe_u32 v116, v112, 16, 1
	v_add3_u32 v112, v112, v116, s71
	ds_write_b16_d16_hi v124, v112 offset:96
	v_bfe_u32 v112, v113, 16, 1
	v_add3_u32 v112, v113, v112, s71
	ds_write_b16_d16_hi v124, v112 offset:240
	v_bfe_u32 v112, v114, 16, 1
	v_add3_u32 v112, v114, v112, s71
	ds_write_b16_d16_hi v124, v112 offset:384
	v_bfe_u32 v112, v115, 16, 1
	v_add3_u32 v112, v115, v112, s71
	ds_write_b16_d16_hi v124, v112 offset:528
	v_bfe_u32 v112, v108, 16, 1
	v_add3_u32 v108, v108, v112, s71
	ds_write_b16_d16_hi v124, v108 offset:2304
	v_bfe_u32 v108, v109, 16, 1
	v_add3_u32 v108, v109, v108, s71
	ds_write_b16_d16_hi v124, v108 offset:2448
	v_bfe_u32 v108, v110, 16, 1
	v_add3_u32 v108, v110, v108, s71
	ds_write_b16_d16_hi v124, v108 offset:2592
	v_bfe_u32 v108, v111, 16, 1
; DEV void store_tile_bf16(const f32x4 (&acc)[8][4], u16* __restrict__ OUT, size_t ld, int m0, int n0, int ncols,
;                          unsigned char* smem) {
;     ...
; #pragma unroll
;   for (int mh = 0; mh < 2; ++mh) {
; #pragma unroll
;     for (int mi = 0; mi < 4; ++mi)
; #pragma unroll
;       for (int ni = 0; ni < 4; ++ni)
; #pragma unroll
;         for (int j = 0; j < 4; ++j) st[(mi * 16 + fq * 4 + j) * 72 + ni * 16 + fr] = f2bf(acc[mh * 4 + mi][ni][j]);
	v_add3_u32 v108, v111, v108, s71
	ds_write_b16_d16_hi v124, v108 offset:2736
	v_bfe_u32 v108, v104, 16, 1
	v_add3_u32 v104, v104, v108, s71
	ds_write_b16_d16_hi v124, v104 offset:2336
	v_bfe_u32 v104, v105, 16, 1
	v_add3_u32 v104, v105, v104, s71
	ds_write_b16_d16_hi v124, v104 offset:2480
	v_bfe_u32 v104, v106, 16, 1
	v_add3_u32 v104, v106, v104, s71
	ds_write_b16_d16_hi v124, v104 offset:2624
	v_bfe_u32 v104, v107, 16, 1
	v_add3_u32 v104, v107, v104, s71
	ds_write_b16_d16_hi v124, v104 offset:2768
	v_bfe_u32 v104, v100, 16, 1
	v_add3_u32 v100, v100, v104, s71
	ds_write_b16_d16_hi v124, v100 offset:2368
	v_bfe_u32 v100, v101, 16, 1
	v_add3_u32 v100, v101, v100, s71
	ds_write_b16_d16_hi v124, v100 offset:2512
	v_bfe_u32 v100, v102, 16, 1
	v_add3_u32 v100, v102, v100, s71
	ds_write_b16_d16_hi v124, v100 offset:2656
	v_bfe_u32 v100, v103, 16, 1
	v_add3_u32 v100, v103, v100, s71
	ds_write_b16_d16_hi v124, v100 offset:2800
	v_bfe_u32 v100, v96, 16, 1
	v_add3_u32 v96, v96, v100, s71
	ds_write_b16_d16_hi v124, v96 offset:2400
	v_bfe_u32 v96, v97, 16, 1
	v_add3_u32 v96, v97, v96, s71
	ds_write_b16_d16_hi v124, v96 offset:2544
	v_bfe_u32 v96, v98, 16, 1
	v_add3_u32 v96, v98, v96, s71
	ds_write_b16_d16_hi v124, v96 offset:2688
	v_bfe_u32 v96, v99, 16, 1
	v_add3_u32 v96, v99, v96, s71
	ds_write_b16_d16_hi v124, v96 offset:2832
	v_bfe_u32 v96, v92, 16, 1
	v_add3_u32 v92, v92, v96, s71
	ds_write_b16_d16_hi v124, v92 offset:4608
	v_bfe_u32 v92, v93, 16, 1
	v_add3_u32 v92, v93, v92, s71
	ds_write_b16_d16_hi v124, v92 offset:4752
	v_bfe_u32 v92, v94, 16, 1
	v_add3_u32 v92, v94, v92, s71
	ds_write_b16_d16_hi v124, v92 offset:4896
	v_bfe_u32 v92, v95, 16, 1
	v_add3_u32 v92, v95, v92, s71
	ds_write_b16_d16_hi v124, v92 offset:5040
	v_bfe_u32 v92, v88, 16, 1
	v_add3_u32 v88, v88, v92, s71
	ds_write_b16_d16_hi v124, v88 offset:4640
	v_bfe_u32 v88, v89, 16, 1
	v_add3_u32 v88, v89, v88, s71
	v_mfma_f32_16x16x32_bf16 v[84:87], v[164:167], v[136:139], v[84:87]
	ds_write_b16_d16_hi v124, v88 offset:4784
	v_bfe_u32 v88, v90, 16, 1
	v_add3_u32 v88, v90, v88, s71
	ds_write_b16_d16_hi v124, v88 offset:4928
	v_bfe_u32 v88, v91, 16, 1
	v_add3_u32 v88, v91, v88, s71
	ds_write_b16_d16_hi v124, v88 offset:5072
	s_nop 0
	v_bfe_u32 v88, v84, 16, 1
	v_add3_u32 v84, v84, v88, s71
	ds_write_b16_d16_hi v124, v84 offset:4672
	v_bfe_u32 v84, v85, 16, 1
	v_add3_u32 v84, v85, v84, s71
	v_mfma_f32_16x16x32_bf16 v[80:83], v[164:167], v[140:143], v[80:83]
	ds_write_b16_d16_hi v124, v84 offset:4816
	v_bfe_u32 v84, v86, 16, 1
	v_add3_u32 v84, v86, v84, s71
	ds_write_b16_d16_hi v124, v84 offset:4960
	v_bfe_u32 v84, v87, 16, 1
	v_add3_u32 v84, v87, v84, s71
	ds_write_b16_d16_hi v124, v84 offset:5104
	s_nop 0
	v_bfe_u32 v84, v80, 16, 1
	v_add3_u32 v80, v80, v84, s71
	ds_write_b16_d16_hi v124, v80 offset:4704
	v_bfe_u32 v80, v81, 16, 1
	v_add3_u32 v80, v81, v80, s71
	ds_write_b16_d16_hi v124, v80 offset:4848
	v_bfe_u32 v80, v82, 16, 1
	v_add3_u32 v80, v82, v80, s71
	ds_write_b16_d16_hi v124, v80 offset:4992
	v_bfe_u32 v80, v83, 16, 1
	v_add3_u32 v80, v83, v80, s71
	ds_write_b16_d16_hi v124, v80 offset:5136
	v_bfe_u32 v80, v76, 16, 1
	v_add3_u32 v76, v76, v80, s71
	ds_write_b16_d16_hi v124, v76 offset:6912
	v_bfe_u32 v76, v77, 16, 1
	v_add3_u32 v76, v77, v76, s71
	ds_write_b16_d16_hi v124, v76 offset:7056
	v_bfe_u32 v76, v78, 16, 1
	v_add3_u32 v76, v78, v76, s71
	ds_write_b16_d16_hi v124, v76 offset:7200
	v_bfe_u32 v76, v79, 16, 1
	v_add3_u32 v76, v79, v76, s71
	ds_write_b16_d16_hi v124, v76 offset:7344
	v_bfe_u32 v76, v72, 16, 1
	v_add3_u32 v72, v72, v76, s71
	ds_write_b16_d16_hi v124, v72 offset:6944
	v_bfe_u32 v72, v73, 16, 1
	v_add3_u32 v72, v73, v72, s71
	v_mfma_f32_16x16x32_bf16 v[68:71], v[168:171], v[136:139], v[68:71]
	ds_write_b16_d16_hi v124, v72 offset:7088
	v_bfe_u32 v72, v74, 16, 1
	v_add3_u32 v72, v74, v72, s71
	ds_write_b16_d16_hi v124, v72 offset:7232
	v_bfe_u32 v72, v75, 16, 1
	v_add3_u32 v72, v75, v72, s71
	ds_write_b16_d16_hi v124, v72 offset:7376
	s_nop 0
	v_bfe_u32 v72, v68, 16, 1
	v_add3_u32 v68, v68, v72, s71
	ds_write_b16_d16_hi v124, v68 offset:6976
	v_bfe_u32 v68, v69, 16, 1
	v_add3_u32 v68, v69, v68, s71
	v_mfma_f32_16x16x32_bf16 v[64:67], v[168:171], v[140:143], v[64:67]
	ds_write_b16_d16_hi v124, v68 offset:7120
	v_bfe_u32 v68, v70, 16, 1
	v_add3_u32 v68, v70, v68, s71
	ds_write_b16_d16_hi v124, v68 offset:7264
	v_bfe_u32 v68, v71, 16, 1
	v_add3_u32 v68, v71, v68, s71
	ds_write_b16_d16_hi v124, v68 offset:7408
	s_nop 0
	v_bfe_u32 v68, v64, 16, 1
	v_add3_u32 v64, v64, v68, s71
	ds_write_b16_d16_hi v124, v64 offset:7008
	v_bfe_u32 v64, v65, 16, 1
	v_add3_u32 v64, v65, v64, s71
	ds_write_b16_d16_hi v124, v64 offset:7152
	v_bfe_u32 v64, v66, 16, 1
	v_mfma_f32_16x16x32_bf16 v[52:55], v[144:147], v[136:139], v[52:55]
	v_add3_u32 v64, v66, v64, s71
	ds_write_b16_d16_hi v124, v64 offset:7296
	v_bfe_u32 v64, v67, 16, 1
	v_mfma_f32_16x16x32_bf16 v[48:51], v[144:147], v[140:143], v[48:51]
	v_ashrrev_i32_e32 v129, 31, v128
	v_add3_u32 v64, v67, v64, s71
	v_cmp_gt_i32_e32 vcc, s33, v128
	v_mfma_f32_16x16x32_bf16 v[36:39], v[148:151], v[136:139], v[36:39]
	v_lshl_add_u64 v[128:129], v[128:129], 1, s[68:69]
	ds_write_b16_d16_hi v124, v64 offset:7440
	v_mad_u32_u24 v66, v133, s4, v131
	v_mfma_f32_16x16x32_bf16 v[32:35], v[148:151], v[140:143], v[32:35]
	v_or_b32_e32 v64, v134, v133
	ds_write_b16_d16_hi v124, v135
	v_mfma_f32_16x16x32_bf16 v[20:23], v[152:155], v[136:139], v[20:23]
	v_mfma_f32_16x16x32_bf16 v[16:19], v[152:155], v[140:143], v[16:19]
	v_mfma_f32_16x16x32_bf16 v[4:7], v[158:161], v[136:139], v[4:7]
	v_mfma_f32_16x16x32_bf16 v[0:3], v[158:161], v[140:143], v[0:3]
	s_and_saveexec_b64 s[4:5], vcc
	s_cbranch_execz .LBB0_229
; DEV void store_tile_bf16(const f32x4 (&acc)[8][4], u16* __restrict__ OUT, size_t ld, int m0, int n0, int ncols,
;                          unsigned char* smem) {
;     ...
;     const int chunk = lane & 7;
;     const int c0 = n0 + wc * 64 + chunk * 8;
; #pragma unroll
;     for (int itr = 0; itr < 8; ++itr) {
;       const int rl = (lane >> 3) + 8 * itr;
;       const u32x4 v = *(const u32x4*)(st + rl * 72 + chunk * 8);
;       if (c0 + 8 <= ncols) *(u32x4*)(OUT + (size_t)(m0 + wr * 128 + mh * 64 + rl) * ld + c0) = v;
;     }
	ds_read_b128 v[68:71], v66
	v_ashrrev_i32_e32 v65, 31, v64
	v_lshlrev_b64 v[72:73], 13, v[64:65]
	v_lshl_add_u64 v[72:73], v[128:129], 0, v[72:73]
	s_waitcnt lgkmcnt(0)
	global_store_dwordx4 v[72:73], v[68:71], off
	ds_read_b128 v[68:71], v66 offset:1152
	v_or_b32_e32 v72, 8, v64
	v_ashrrev_i32_e32 v73, 31, v72
	v_lshlrev_b64 v[72:73], 13, v[72:73]
	v_lshl_add_u64 v[72:73], v[128:129], 0, v[72:73]
	s_waitcnt lgkmcnt(0)
	global_store_dwordx4 v[72:73], v[68:71], off
	ds_read_b128 v[68:71], v66 offset:2304
	v_or_b32_e32 v72, 16, v64
	v_ashrrev_i32_e32 v73, 31, v72
	v_lshlrev_b64 v[72:73], 13, v[72:73]
	v_lshl_add_u64 v[72:73], v[128:129], 0, v[72:73]
	s_waitcnt lgkmcnt(0)
	global_store_dwordx4 v[72:73], v[68:71], off
	ds_read_b128 v[68:71], v66 offset:3456
	v_or_b32_e32 v72, 24, v64
	v_ashrrev_i32_e32 v73, 31, v72
	v_lshlrev_b64 v[72:73], 13, v[72:73]
	v_lshl_add_u64 v[72:73], v[128:129], 0, v[72:73]
	s_waitcnt lgkmcnt(0)
	global_store_dwordx4 v[72:73], v[68:71], off
	ds_read_b128 v[68:71], v66 offset:4608
	v_or_b32_e32 v72, 32, v64
	v_ashrrev_i32_e32 v73, 31, v72
	v_lshlrev_b64 v[72:73], 13, v[72:73]
	v_lshl_add_u64 v[72:73], v[128:129], 0, v[72:73]
	s_waitcnt lgkmcnt(0)
	global_store_dwordx4 v[72:73], v[68:71], off
	ds_read_b128 v[68:71], v66 offset:5760
	v_or_b32_e32 v72, 40, v64
	v_ashrrev_i32_e32 v73, 31, v72
	v_lshlrev_b64 v[72:73], 13, v[72:73]
	v_lshl_add_u64 v[72:73], v[128:129], 0, v[72:73]
	s_waitcnt lgkmcnt(0)
	global_store_dwordx4 v[72:73], v[68:71], off
	ds_read_b128 v[68:71], v66 offset:6912
	v_or_b32_e32 v72, 48, v64
	v_ashrrev_i32_e32 v73, 31, v72
	v_lshlrev_b64 v[72:73], 13, v[72:73]
	v_lshl_add_u64 v[72:73], v[128:129], 0, v[72:73]
	s_waitcnt lgkmcnt(0)
	global_store_dwordx4 v[72:73], v[68:71], off
	ds_read_b128 v[68:71], v66 offset:8064
	v_or_b32_e32 v72, 56, v64
	v_ashrrev_i32_e32 v73, 31, v72
	v_lshlrev_b64 v[72:73], 13, v[72:73]
	v_lshl_add_u64 v[72:73], v[128:129], 0, v[72:73]
	s_waitcnt lgkmcnt(0)
	global_store_dwordx4 v[72:73], v[68:71], off

; DEV int TID() { int t = threadIdx.x; asm volatile("" : "+v"(t)); return t; }
; DEV void gemm_tile(const u16* __restrict__ A, size_t lda, const u16* __restrict__ Bt, size_t ldb, int K,
;                    u16* sA, u16* sB, f32x4 (&acc)[8][4]) {
;   const int tid = TID(), lane = tid & 63, wid = tid >> 6;
;   const int wr = wid >> 1, wc = wid & 1, fr = lane & 15, fq = lane >> 4;
; #pragma unroll
;   for (int mi = 0; mi < 8; ++mi)
; #pragma unroll
;     for (int ni = 0; ni < 4; ++ni) acc[mi][ni] = f32x4{0.f, 0.f, 0.f, 0.f};
;   const int lr = tid >> 2, lc = (tid & 3) * 8;
;   const u16* ap = A + (size_t)lr * lda + lc;
;   const u16* bp = Bt + (size_t)lr * ldb + lc;
;   u32x4 ra[4], rb[2];
;     ...
;   const int nk = K >> 5;
;   const int swz = ((fq ^ ((0 - (fr >> 2)) & 3)) << 3);
;   const u16* sAr = sA + (wr * 128 + fr) * 32 + swz;
;   const u16* sBr = sA + 256 * 32 + (wc * 64 + fr) * 32 + swz;
;   G_LOAD(0)
; PHASE void gemm_out_phase(const u16* MG, const u16* WT, const float* xres, float* out, unsigned char* smem) {
;     ...
;   for (int it = 0; it < nit; ++it) {
;     int mt, nt;
;     if (!tile_map(it, 16, mt, nt)) continue;
;     const int m0 = mt * 256, n0 = nt * 128;
;     f32x4 acc[8][4];
;     gemm_tile(MG + (size_t)m0 * 2048, 2048, WT + (size_t)n0 * 2048, 2048, 2048, sA, sB, acc);
.LBB0_250:
	s_lshl_b32 s4, s6, 8
	s_ashr_i32 s5, s4, 31
	v_mov_b32_e32 v9, v178
	s_lshl_b32 s2, s7, 7
	s_lshl_b64 s[8:9], s[4:5], 12
	s_add_u32 s6, s68, s8
	v_ashrrev_i32_e32 v34, 2, v9
	v_ashrrev_i32_e32 v35, 31, v34
	s_addc_u32 s7, s69, s9
	v_lshlrev_b64 v[36:37], 12, v[34:35]
	v_lshlrev_b32_e32 v2, 4, v9
	v_lshl_add_u64 v[0:1], s[6:7], 0, v[36:37]
	v_and_b32_e32 v156, 48, v2
	v_lshl_add_u64 v[38:39], v[0:1], 0, v[156:157]
	s_mov_b32 s5, 0x40000
	s_ashr_i32 s3, s2, 31
	v_add_co_u32_e32 v40, vcc, s5, v38
	s_lshl_b64 s[10:11], s[2:3], 12
	v_readlane_b32 s16, v250, 26
	v_addc_co_u32_e32 v41, vcc, 0, v39, vcc
	s_mov_b32 s6, 0x80000
	v_readlane_b32 s17, v250, 27
	s_add_u32 s16, s16, s10
	v_add_co_u32_e32 v42, vcc, s6, v38
	s_addc_u32 s17, s17, s11
	s_nop 0
	v_addc_co_u32_e32 v43, vcc, 0, v39, vcc
	s_mov_b32 s6, 0xc0000
	v_lshl_add_u64 v[0:1], s[16:17], 0, v[36:37]
	v_add_co_u32_e32 v44, vcc, s6, v38
	v_lshl_add_u64 v[46:47], v[0:1], 0, v[156:157]
	s_nop 0
	v_addc_co_u32_e32 v45, vcc, 0, v39, vcc
	v_add_co_u32_e32 v48, vcc, s5, v46
	v_addc_co_u32_e32 v49, vcc, 0, v47, vcc
	s_barrier
	v_lshrrev_b32_e32 v35, 4, v9
	v_lshrrev_b32_e32 v50, 2, v9
	v_sub_u32_e32 v50, 0, v50
	v_sub_u32_e32 v51, 0, v35
	v_lshlrev_b32_e32 v52, 6, v9
	v_xor_b32_e32 v35, v35, v50
	v_xor_b32_e32 v9, v9, v51
	v_lshlrev_b32_e32 v35, 4, v35
	v_lshlrev_b32_e32 v9, 4, v9
	v_lshl_add_u64 v[50:51], v[36:37], 0, s[8:9]
	v_and_b32_e32 v35, 48, v35
	v_and_b32_e32 v9, 48, v9
	v_lshl_add_u64 v[36:37], v[36:37], 0, s[10:11]
	s_movk_i32 s8, 0xe3c0
	v_mov_b32_e32 v0, 0
	v_or_b32_e32 v50, v50, v156
	v_and_or_b32 v162, v52, s8, v35
	v_lshl_or_b32 v164, v34, 6, v9
	s_movk_i32 s8, 0x13c0
	v_or_b32_e32 v36, v36, v156
	s_mov_b32 s5, 0
	s_mov_b64 s[6:7], 0
	v_mov_b32_e32 v1, v0
	v_mov_b32_e32 v2, v0
	v_mov_b32_e32 v3, v0
	v_mov_b32_e32 v4, v0
	v_mov_b32_e32 v5, v0
	v_mov_b32_e32 v6, v0
	v_mov_b32_e32 v7, v0
	v_mov_b32_e32 v8, v0
	v_and_or_b32 v163, v52, s8, v35
	v_lshl_add_u64 v[158:159], s[46:47], 0, v[50:51]
	v_lshl_add_u64 v[160:161], s[46:47], 0, v[36:37]
	v_mov_b32_e32 v9, v0
	v_mov_b32_e32 v34, v0
	v_mov_b32_e32 v35, v0
	v_mov_b32_e32 v36, v0
	v_mov_b32_e32 v37, v0
	v_mov_b32_e32 v38, v0
	v_mov_b32_e32 v39, v0
	v_mov_b32_e32 v40, v0
	v_mov_b32_e32 v41, v0
	v_mov_b32_e32 v42, v0
	v_mov_b32_e32 v43, v0
	v_mov_b32_e32 v44, v0
	v_mov_b32_e32 v10, v0
	v_mov_b32_e32 v11, v0
	v_mov_b32_e32 v12, v0
	v_mov_b32_e32 v13, v0
	v_mov_b32_e32 v14, v0
	v_mov_b32_e32 v15, v0
	v_mov_b32_e32 v16, v0
	v_mov_b32_e32 v17, v0
	v_mov_b32_e32 v18, v0
	v_mov_b32_e32 v19, v0
	v_mov_b32_e32 v20, v0
	v_mov_b32_e32 v21, v0
	v_mov_b32_e32 v22, v0
	v_mov_b32_e32 v23, v0
	v_mov_b32_e32 v24, v0
	v_mov_b32_e32 v25, v0
	v_mov_b32_e32 v26, v0
	v_mov_b32_e32 v27, v0
	v_mov_b32_e32 v28, v0
	v_mov_b32_e32 v29, v0
	v_mov_b32_e32 v30, v0
	v_mov_b32_e32 v31, v0
	v_mov_b32_e32 v32, v0
	v_mov_b32_e32 v33, v0
	v_mov_b32_e32 v45, v0
	v_mov_b32_e32 v46, v0
	v_mov_b32_e32 v47, v0
	v_mov_b32_e32 v48, v0
	v_mov_b32_e32 v49, v0
	v_mov_b32_e32 v50, v0
	v_mov_b32_e32 v51, v0
	v_mov_b32_e32 v52, v0
	v_mov_b32_e32 v53, v0
	v_mov_b32_e32 v54, v0
	v_mov_b32_e32 v55, v0
	v_mov_b32_e32 v56, v0
	v_mov_b32_e32 v57, v0
	v_mov_b32_e32 v58, v0
	v_mov_b32_e32 v59, v0
	v_mov_b32_e32 v60, v0
	v_mov_b32_e32 v61, v0
	v_mov_b32_e32 v62, v0
	v_mov_b32_e32 v63, v0
	v_mov_b32_e32 v64, v0
	v_mov_b32_e32 v65, v0
	v_mov_b32_e32 v66, v0
	v_mov_b32_e32 v67, v0
	v_mov_b32_e32 v68, v0
	v_mov_b32_e32 v69, v0
	v_mov_b32_e32 v70, v0
	v_mov_b32_e32 v71, v0
	v_mov_b32_e32 v72, v0
	v_mov_b32_e32 v73, v0
	v_mov_b32_e32 v74, v0
	v_mov_b32_e32 v75, v0
	v_mov_b32_e32 v76, v0
	v_mov_b32_e32 v77, v0
	v_mov_b32_e32 v78, v0
	v_mov_b32_e32 v79, v0
	v_mov_b32_e32 v80, v0
	v_mov_b32_e32 v81, v0
	v_mov_b32_e32 v82, v0
	v_mov_b32_e32 v83, v0
	v_mov_b32_e32 v84, v0
	v_mov_b32_e32 v85, v0
	v_mov_b32_e32 v86, v0
	v_mov_b32_e32 v87, v0
	v_mov_b32_e32 v88, v0
	v_mov_b32_e32 v89, v0
	v_mov_b32_e32 v90, v0
	v_mov_b32_e32 v91, v0
	v_mov_b32_e32 v92, v0
	v_mov_b32_e32 v93, v0
	v_mov_b32_e32 v94, v0
	v_mov_b32_e32 v95, v0
	v_mov_b32_e32 v96, v0
	v_mov_b32_e32 v97, v0
	v_mov_b32_e32 v98, v0
	v_mov_b32_e32 v99, v0
	v_mov_b32_e32 v100, v0
	v_mov_b32_e32 v101, v0
	v_mov_b32_e32 v102, v0
	v_mov_b32_e32 v103, v0
	v_mov_b32_e32 v104, v0
	v_mov_b32_e32 v105, v0
	v_mov_b32_e32 v106, v0
	v_mov_b32_e32 v107, v0
	v_mov_b32_e32 v108, v0
	v_mov_b32_e32 v109, v0
	v_mov_b32_e32 v110, v0
	v_mov_b32_e32 v111, v0
	v_mov_b32_e32 v112, v0
	v_mov_b32_e32 v113, v0
	v_mov_b32_e32 v114, v0
	v_mov_b32_e32 v115, v0
	v_mov_b32_e32 v116, v0
	v_mov_b32_e32 v117, v0
	v_mov_b32_e32 v118, v0
	v_mov_b32_e32 v119, v0
	v_mov_b32_e32 v120, v0
	v_mov_b32_e32 v121, v0
	v_mov_b32_e32 v122, v0
	v_mov_b32_e32 v123, v0
	v_mov_b32_e32 v148, v0
	v_mov_b32_e32 v149, v0
	v_mov_b32_e32 v150, v0
	v_mov_b32_e32 v151, v0
	s_waitcnt lgkmcnt(0)
	s_barrier
; DEV f32x4 mfma16(bf16x8 a, bf16x8 b, f32x4 c) { return __builtin_amdgcn_mfma_f32_16x16x32_bf16(a, b, c, 0, 0, 0); }
; DEV void gemm_tile(const u16* __restrict__ A, size_t lda, const u16* __restrict__ Bt, size_t ldb, int K,
;                    u16* sA, u16* sB, f32x4 (&acc)[8][4]) {
;     ...
;   const int nk = K >> 5;
;   const int swz = ((fq ^ ((0 - (fr >> 2)) & 3)) << 3);
;   const u16* sAr = sA + (wr * 128 + fr) * 32 + swz;
;   const u16* sBr = sA + 256 * 32 + (wc * 64 + fr) * 32 + swz;
;   G_LOAD(0)
;   __syncthreads();
;   S_STORE(0)
;   if (nk > 1) G_LOAD(32)
;   __syncthreads();
;   for (int kt = 0; kt < nk; ++kt) {
;     const int st = kt & 1;
;     if (kt + 1 < nk) S_STORE(st ^ 1)
;     if (kt + 2 < nk) G_LOAD((kt + 2) << 5)
;     {
;       const u16* pa = sAr + st * 12288;
;       const u16* pb = sBr + st * 12288;
;       bf16x8 b[4];
; #pragma unroll
;       for (int ni = 0; ni < 4; ++ni) b[ni] = *(const bf16x8*)(pb + ni * 16 * 32);
; #pragma unroll
;       for (int mh = 0; mh < 2; ++mh) {
;         bf16x8 a[4];
; #pragma unroll
;         for (int mi = 0; mi < 4; ++mi) a[mi] = *(const bf16x8*)(pa + (mh * 64 + mi * 16) * 32);
; #pragma unroll
;         for (int mi = 0; mi < 4; ++mi)
; #pragma unroll
;           for (int ni = 0; ni < 4; ++ni) acc[mh * 4 + mi][ni] = mfma16(a[mi], b[ni], acc[mh * 4 + mi][ni]);
;       }
;     }
;     __syncthreads();
;   }
	v_lshl_add_u64 v[136:137], v[158:159], 0, s[6:7]
	s_mov_b32 s8, 0x126d0000
	v_add_co_u32_e32 v140, vcc, s8, v136
	s_nop 1
	v_addc_co_u32_e32 v141, vcc, 0, v137, vcc
	s_mov_b32 s8, 0x12710000
	v_add_co_u32_e32 v142, vcc, s8, v136
	s_mov_b32 s8, 0x12750000
	s_nop 1
	v_addc_co_u32_e32 v143, vcc, 0, v137, vcc
	v_add_co_u32_e32 v174, vcc, s8, v136
	s_nop 1
	v_addc_co_u32_e32 v175, vcc, 0, v137, vcc
	s_mov_b32 s8, 0x12790000
	v_add_co_u32_e32 v176, vcc, s8, v136
	v_lshl_add_u64 v[138:139], v[160:161], 0, s[6:7]
	s_nop 1
	v_addc_co_u32_e32 v177, vcc, 0, v137, vcc
	s_mov_b32 s8, 0x55d0000
	v_add_co_u32_e32 v186, vcc, s8, v138
	s_nop 1
	v_addc_co_u32_e32 v187, vcc, 0, v139, vcc
	s_mov_b32 s8, 0x5610000
	v_add_co_u32_e32 v188, vcc, s8, v138
	s_nop 1
	v_addc_co_u32_e32 v189, vcc, 0, v139, vcc
	v_lshrrev_b32_e32 v228, 4, v178
	v_sub_u32_e32 v228, 0, v228
	v_and_b32_e32 v228, 3, v228
	v_lshlrev_b32_e32 v228, 4, v228
	v_lshrrev_b32_e32 v229, 6, v178
	v_lshlrev_b32_e32 v229, 10, v229
	v_xor_b32_e32 v140, v140, v228
	v_xor_b32_e32 v142, v142, v228
	v_xor_b32_e32 v174, v174, v228
	v_xor_b32_e32 v176, v176, v228
	v_xor_b32_e32 v186, v186, v228
	v_xor_b32_e32 v188, v188, v228
	v_readfirstlane_b32 s5, v229
	s_nop 1
	s_add_i32 s9, s5, 0x6000
	s_add_i32 m0, s9, 0x0
	s_nop 0
	global_load_lds_dwordx4 v[140:141], off
	v_lshl_add_u64 v[140:141], v[140:141], 0, 64
	s_add_i32 m0, s9, 0x1000
	s_nop 0
	global_load_lds_dwordx4 v[142:143], off
	v_lshl_add_u64 v[142:143], v[142:143], 0, 64
	s_add_i32 m0, s9, 0x2000
	s_nop 0
	global_load_lds_dwordx4 v[174:175], off
	v_lshl_add_u64 v[174:175], v[174:175], 0, 64
	s_add_i32 m0, s9, 0x3000
	s_nop 0
	global_load_lds_dwordx4 v[176:177], off
	v_lshl_add_u64 v[176:177], v[176:177], 0, 64
	s_add_i32 m0, s9, 0x4000
	s_nop 0
	global_load_lds_dwordx4 v[186:187], off
	v_lshl_add_u64 v[186:187], v[186:187], 0, 64
	s_add_i32 m0, s9, 0x5000
	s_nop 0
	global_load_lds_dwordx4 v[188:189], off
	v_lshl_add_u64 v[188:189], v[188:189], 0, 64
	s_add_i32 s9, s5, 0xc000
	s_add_i32 m0, s9, 0x0
	s_nop 0
	global_load_lds_dwordx4 v[140:141], off
	v_lshl_add_u64 v[140:141], v[140:141], 0, 64
	s_add_i32 m0, s9, 0x1000
	s_nop 0
	global_load_lds_dwordx4 v[142:143], off
	v_lshl_add_u64 v[142:143], v[142:143], 0, 64
	s_add_i32 m0, s9, 0x2000
	s_nop 0
	global_load_lds_dwordx4 v[174:175], off
	v_lshl_add_u64 v[174:175], v[174:175], 0, 64
	s_add_i32 m0, s9, 0x3000
	s_nop 0
	global_load_lds_dwordx4 v[176:177], off
	v_lshl_add_u64 v[176:177], v[176:177], 0, 64
	s_add_i32 m0, s9, 0x4000
	s_nop 0
	global_load_lds_dwordx4 v[186:187], off
	v_lshl_add_u64 v[186:187], v[186:187], 0, 64
	s_add_i32 m0, s9, 0x5000
	s_nop 0
	global_load_lds_dwordx4 v[188:189], off
	v_lshl_add_u64 v[188:189], v[188:189], 0, 64
	v_and_b32_e32 v230, 63, v178
	v_lshlrev_b32_e32 v230, 4, v230
	s_mov_b32 s8, 0x6000
	s_mov_b32 s9, s5
	s_waitcnt vmcnt(6)
	s_barrier
.LBB0_251:
	v_add_u32_e32 v229, s8, v163
	v_add_u32_e32 v228, s8, v162
	ds_read_b128 v[124:127], v229 offset:16384
	ds_read_b128 v[166:169], v228
	ds_read_b128 v[132:135], v229 offset:17408
	ds_read_b128 v[144:147], v229 offset:18432
	ds_read_b128 v[128:131], v229 offset:19456
	ds_read_b128 v[152:155], v228 offset:1024
	ds_read_b128 v[170:173], v228 offset:2048
	ds_read_b128 v[136:139], v228 offset:3072
	s_waitcnt lgkmcnt(6)
	v_mfma_f32_16x16x32_bf16 v[148:151], v[166:169], v[124:127], v[148:151]
	s_add_i32 m0, s9, 0x0
	s_waitcnt lgkmcnt(5)
	v_mfma_f32_16x16x32_bf16 v[120:123], v[166:169], v[132:135], v[120:123]
	global_load_lds_dwordx4 v[140:141], off
	v_lshl_add_u64 v[140:141], v[140:141], 0, 64
	global_load_dwordx4 v[244:247], v[140:141], off
	v_lshl_add_u64 v[140:141], v[140:141], 0, 64
	s_waitcnt lgkmcnt(4)
	v_mfma_f32_16x16x32_bf16 v[116:119], v[166:169], v[144:147], v[116:119]
	s_add_i32 m0, s9, 0x1000
	s_waitcnt lgkmcnt(3)
	v_mfma_f32_16x16x32_bf16 v[112:115], v[166:169], v[128:131], v[112:115]
	ds_read_b128 v[232:235], v228 offset:4096
	ds_read_b128 v[236:239], v228 offset:5120
	s_waitcnt lgkmcnt(4)
	v_mfma_f32_16x16x32_bf16 v[108:111], v[152:155], v[124:127], v[108:111]
	global_load_lds_dwordx4 v[142:143], off
	v_lshl_add_u64 v[142:143], v[142:143], 0, 64
	global_load_dwordx4 v[252:255], v[142:143], off
	v_lshl_add_u64 v[142:143], v[142:143], 0, 64
	v_mfma_f32_16x16x32_bf16 v[104:107], v[152:155], v[132:135], v[104:107]
	s_add_i32 m0, s9, 0x2000
	v_mfma_f32_16x16x32_bf16 v[100:103], v[152:155], v[144:147], v[100:103]
	global_load_lds_dwordx4 v[174:175], off
	v_lshl_add_u64 v[174:175], v[174:175], 0, 64
	global_load_dwordx4 v[208:211], v[174:175], off
	v_lshl_add_u64 v[174:175], v[174:175], 0, 64
	v_mfma_f32_16x16x32_bf16 v[96:99], v[152:155], v[128:131], v[96:99]
	s_add_i32 m0, s9, 0x3000
	s_waitcnt lgkmcnt(3)
	v_mfma_f32_16x16x32_bf16 v[92:95], v[170:173], v[124:127], v[92:95]
	global_load_lds_dwordx4 v[176:177], off
	v_lshl_add_u64 v[176:177], v[176:177], 0, 64
	global_load_dwordx4 v[212:215], v[176:177], off
	v_lshl_add_u64 v[176:177], v[176:177], 0, 64
	v_mfma_f32_16x16x32_bf16 v[88:91], v[170:173], v[132:135], v[88:91]
	s_add_i32 m0, s9, 0x4000
	v_mfma_f32_16x16x32_bf16 v[84:87], v[170:173], v[144:147], v[84:87]
	global_load_lds_dwordx4 v[186:187], off
	v_lshl_add_u64 v[186:187], v[186:187], 0, 64
	global_load_dwordx4 v[216:219], v[186:187], off
	v_lshl_add_u64 v[186:187], v[186:187], 0, 64
	v_mfma_f32_16x16x32_bf16 v[80:83], v[170:173], v[128:131], v[80:83]
	ds_read_b128 v[240:243], v228 offset:6144
	ds_read_b128 v[166:169], v228 offset:7168
	s_waitcnt lgkmcnt(4)
; DEV f32x4 mfma16(bf16x8 a, bf16x8 b, f32x4 c) { return __builtin_amdgcn_mfma_f32_16x16x32_bf16(a, b, c, 0, 0, 0); }
; DEV void gemm_tile(const u16* __restrict__ A, size_t lda, const u16* __restrict__ Bt, size_t ldb, int K,
;                    u16* sA, u16* sB, f32x4 (&acc)[8][4]) {
;     ...
;   for (int kt = 0; kt < nk; ++kt) {
;     const int st = kt & 1;
;     if (kt + 1 < nk) S_STORE(st ^ 1)
;     if (kt + 2 < nk) G_LOAD((kt + 2) << 5)
;     {
;       const u16* pa = sAr + st * 12288;
;       const u16* pb = sBr + st * 12288;
;       bf16x8 b[4];
; #pragma unroll
;       for (int ni = 0; ni < 4; ++ni) b[ni] = *(const bf16x8*)(pb + ni * 16 * 32);
; #pragma unroll
;       for (int mh = 0; mh < 2; ++mh) {
;         bf16x8 a[4];
; #pragma unroll
;         for (int mi = 0; mi < 4; ++mi) a[mi] = *(const bf16x8*)(pa + (mh * 64 + mi * 16) * 32);
; #pragma unroll
;         for (int mi = 0; mi < 4; ++mi)
; #pragma unroll
;           for (int ni = 0; ni < 4; ++ni) acc[mh * 4 + mi][ni] = mfma16(a[mi], b[ni], acc[mh * 4 + mi][ni]);
;       }
;     }
;     __syncthreads();
;   }
	v_mfma_f32_16x16x32_bf16 v[76:79], v[136:139], v[124:127], v[76:79]
	s_add_i32 m0, s9, 0x5000
	v_mfma_f32_16x16x32_bf16 v[72:75], v[136:139], v[132:135], v[72:75]
	global_load_lds_dwordx4 v[188:189], off
	v_lshl_add_u64 v[188:189], v[188:189], 0, 64
	global_load_dwordx4 v[220:223], v[188:189], off
	v_lshl_add_u64 v[188:189], v[188:189], 0, 64
	v_mfma_f32_16x16x32_bf16 v[68:71], v[136:139], v[144:147], v[68:71]
	s_add_i32 s9, s8, s5
	s_add_i32 s8, s8, 0x6000
	v_mfma_f32_16x16x32_bf16 v[64:67], v[136:139], v[128:131], v[64:67]
	s_cmp_eq_u32 s8, 0x12000
	s_cselect_b32 s8, 0, s8
	s_waitcnt lgkmcnt(3)
	v_mfma_f32_16x16x32_bf16 v[60:63], v[232:235], v[124:127], v[60:63]
	s_add_u32 s6, s6, 64
	s_addc_u32 s7, s7, 0
	s_cmpk_lg_i32 s6, 0xf80
	v_mfma_f32_16x16x32_bf16 v[56:59], v[232:235], v[132:135], v[56:59]
	v_mfma_f32_16x16x32_bf16 v[52:55], v[232:235], v[144:147], v[52:55]
	v_mfma_f32_16x16x32_bf16 v[48:51], v[232:235], v[128:131], v[48:51]
	s_waitcnt lgkmcnt(2)
	v_mfma_f32_16x16x32_bf16 v[44:47], v[236:239], v[124:127], v[44:47]
	v_mfma_f32_16x16x32_bf16 v[40:43], v[236:239], v[132:135], v[40:43]
	v_mfma_f32_16x16x32_bf16 v[36:39], v[236:239], v[144:147], v[36:39]
	v_mfma_f32_16x16x32_bf16 v[32:35], v[236:239], v[128:131], v[32:35]
	s_waitcnt lgkmcnt(1)
	v_mfma_f32_16x16x32_bf16 v[28:31], v[240:243], v[124:127], v[28:31]
	v_mfma_f32_16x16x32_bf16 v[24:27], v[240:243], v[132:135], v[24:27]
	v_mfma_f32_16x16x32_bf16 v[20:23], v[240:243], v[144:147], v[20:23]
	v_mfma_f32_16x16x32_bf16 v[16:19], v[240:243], v[128:131], v[16:19]
	s_waitcnt lgkmcnt(0)
	s_waitcnt vmcnt(12)
	s_barrier
	v_mfma_f32_16x16x32_bf16 v[12:15], v[166:169], v[124:127], v[12:15]
	v_mfma_f32_16x16x32_bf16 v[8:11], v[166:169], v[132:135], v[8:11]
	v_mfma_f32_16x16x32_bf16 v[4:7], v[166:169], v[144:147], v[4:7]
	v_mfma_f32_16x16x32_bf16 v[0:3], v[166:169], v[128:131], v[0:3]
	v_add_u32_e32 v229, s8, v163
	v_add_u32_e32 v228, s8, v162
	ds_read_b128 v[124:127], v229 offset:16384
	ds_read_b128 v[166:169], v228
	ds_read_b128 v[132:135], v229 offset:17408
	ds_read_b128 v[144:147], v229 offset:18432
	ds_read_b128 v[128:131], v229 offset:19456
	ds_read_b128 v[152:155], v228 offset:1024
	ds_read_b128 v[170:173], v228 offset:2048
	ds_read_b128 v[136:139], v228 offset:3072
	s_waitcnt lgkmcnt(6)
	v_mfma_f32_16x16x32_bf16 v[148:151], v[166:169], v[124:127], v[148:151]
	s_waitcnt vmcnt(0)
	v_add_u32_e32 v231, s9, v230
	s_waitcnt lgkmcnt(5)
	v_mfma_f32_16x16x32_bf16 v[120:123], v[166:169], v[132:135], v[120:123]
	ds_write_b128 v231, v[244:247]
	s_waitcnt lgkmcnt(5)
	v_mfma_f32_16x16x32_bf16 v[116:119], v[166:169], v[144:147], v[116:119]
	ds_write_b128 v231, v[252:255] offset:4096
	s_waitcnt lgkmcnt(5)
	v_mfma_f32_16x16x32_bf16 v[112:115], v[166:169], v[128:131], v[112:115]
	ds_read_b128 v[232:235], v228 offset:4096
	ds_read_b128 v[236:239], v228 offset:5120
	s_waitcnt lgkmcnt(6)
	v_mfma_f32_16x16x32_bf16 v[108:111], v[152:155], v[124:127], v[108:111]
	ds_write_b128 v231, v[208:211] offset:8192
	v_mfma_f32_16x16x32_bf16 v[104:107], v[152:155], v[132:135], v[104:107]
	ds_write_b128 v231, v[212:215] offset:12288
	v_mfma_f32_16x16x32_bf16 v[100:103], v[152:155], v[144:147], v[100:103]
	ds_write_b128 v231, v[216:219] offset:16384
	v_mfma_f32_16x16x32_bf16 v[96:99], v[152:155], v[128:131], v[96:99]
	ds_write_b128 v231, v[220:223] offset:20480
	s_waitcnt lgkmcnt(9)
	v_mfma_f32_16x16x32_bf16 v[92:95], v[170:173], v[124:127], v[92:95]
	s_add_i32 s9, s8, s5
	s_add_i32 s8, s8, 0x6000
	v_mfma_f32_16x16x32_bf16 v[88:91], v[170:173], v[132:135], v[88:91]
	s_cmp_eq_u32 s8, 0x12000
	s_cselect_b32 s8, 0, s8
	v_mfma_f32_16x16x32_bf16 v[84:87], v[170:173], v[144:147], v[84:87]
	s_add_u32 s6, s6, 64
	s_addc_u32 s7, s7, 0
	s_cmpk_lg_i32 s6, 0xf80
	v_mfma_f32_16x16x32_bf16 v[80:83], v[170:173], v[128:131], v[80:83]
	ds_read_b128 v[240:243], v228 offset:6144
	ds_read_b128 v[166:169], v228 offset:7168
	s_waitcnt lgkmcnt(10)
	v_mfma_f32_16x16x32_bf16 v[76:79], v[136:139], v[124:127], v[76:79]
	v_mfma_f32_16x16x32_bf16 v[72:75], v[136:139], v[132:135], v[72:75]
	v_mfma_f32_16x16x32_bf16 v[68:71], v[136:139], v[144:147], v[68:71]
	v_mfma_f32_16x16x32_bf16 v[64:67], v[136:139], v[128:131], v[64:67]
	s_waitcnt lgkmcnt(7)
	v_mfma_f32_16x16x32_bf16 v[60:63], v[232:235], v[124:127], v[60:63]
	v_mfma_f32_16x16x32_bf16 v[56:59], v[232:235], v[132:135], v[56:59]
	v_mfma_f32_16x16x32_bf16 v[52:55], v[232:235], v[144:147], v[52:55]
	v_mfma_f32_16x16x32_bf16 v[48:51], v[232:235], v[128:131], v[48:51]
	s_waitcnt lgkmcnt(6)
	v_mfma_f32_16x16x32_bf16 v[44:47], v[236:239], v[124:127], v[44:47]
	v_mfma_f32_16x16x32_bf16 v[40:43], v[236:239], v[132:135], v[40:43]
	v_mfma_f32_16x16x32_bf16 v[36:39], v[236:239], v[144:147], v[36:39]
	v_mfma_f32_16x16x32_bf16 v[32:35], v[236:239], v[128:131], v[32:35]
	s_waitcnt lgkmcnt(1)
	v_mfma_f32_16x16x32_bf16 v[28:31], v[240:243], v[124:127], v[28:31]
	v_mfma_f32_16x16x32_bf16 v[24:27], v[240:243], v[132:135], v[24:27]
	v_mfma_f32_16x16x32_bf16 v[20:23], v[240:243], v[144:147], v[20:23]
	v_mfma_f32_16x16x32_bf16 v[16:19], v[240:243], v[128:131], v[16:19]
	s_waitcnt lgkmcnt(0)
	s_waitcnt lgkmcnt(0)
	s_barrier
	v_mfma_f32_16x16x32_bf16 v[12:15], v[166:169], v[124:127], v[12:15]
	v_mfma_f32_16x16x32_bf16 v[8:11], v[166:169], v[132:135], v[8:11]
	v_mfma_f32_16x16x32_bf16 v[4:7], v[166:169], v[144:147], v[4:7]
	v_mfma_f32_16x16x32_bf16 v[0:3], v[166:169], v[128:131], v[0:3]
	s_cbranch_scc1 .LBB0_251
; DEV f32x4 mfma16(bf16x8 a, bf16x8 b, f32x4 c) { return __builtin_amdgcn_mfma_f32_16x16x32_bf16(a, b, c, 0, 0, 0); }
; DEV void gemm_tile(const u16* __restrict__ A, size_t lda, const u16* __restrict__ Bt, size_t ldb, int K,
;                    u16* sA, u16* sB, f32x4 (&acc)[8][4]) {
;     ...
;   for (int kt = 0; kt < nk; ++kt) {
;     const int st = kt & 1;
;     if (kt + 1 < nk) S_STORE(st ^ 1)
;     if (kt + 2 < nk) G_LOAD((kt + 2) << 5)
;     {
;       const u16* pa = sAr + st * 12288;
;       const u16* pb = sBr + st * 12288;
;       bf16x8 b[4];
; #pragma unroll
;       for (int ni = 0; ni < 4; ++ni) b[ni] = *(const bf16x8*)(pb + ni * 16 * 32);
; #pragma unroll
;       for (int mh = 0; mh < 2; ++mh) {
;         bf16x8 a[4];
; #pragma unroll
;         for (int mi = 0; mi < 4; ++mi) a[mi] = *(const bf16x8*)(pa + (mh * 64 + mi * 16) * 32);
; #pragma unroll
;         for (int mi = 0; mi < 4; ++mi)
; #pragma unroll
;           for (int ni = 0; ni < 4; ++ni) acc[mh * 4 + mi][ni] = mfma16(a[mi], b[ni], acc[mh * 4 + mi][ni]);
;       }
;     }
;     __syncthreads();
;   }
	ds_read_b128 v[124:127], v163 offset:16384
	ds_read_b128 v[128:131], v163 offset:17408
	ds_read_b128 v[132:135], v163 offset:18432
	ds_read_b128 v[136:139], v163 offset:19456
	ds_read_b128 v[140:143], v162
	ds_read_b128 v[144:147], v162 offset:1024
	ds_read_b128 v[152:155], v162 offset:2048
	ds_read_b128 v[158:161], v162 offset:3072
	s_movk_i32 s5, 0x2200
	s_waitcnt lgkmcnt(3)
	v_mfma_f32_16x16x32_bf16 v[148:151], v[140:143], v[124:127], v[148:151]
	v_mfma_f32_16x16x32_bf16 v[120:123], v[140:143], v[128:131], v[120:123]
	v_mfma_f32_16x16x32_bf16 v[116:119], v[140:143], v[132:135], v[116:119]
	v_mfma_f32_16x16x32_bf16 v[112:115], v[140:143], v[136:139], v[112:115]
	s_waitcnt lgkmcnt(2)
	v_mfma_f32_16x16x32_bf16 v[108:111], v[144:147], v[124:127], v[108:111]
	v_mfma_f32_16x16x32_bf16 v[104:107], v[144:147], v[128:131], v[104:107]
	v_mfma_f32_16x16x32_bf16 v[100:103], v[144:147], v[132:135], v[100:103]
	v_mfma_f32_16x16x32_bf16 v[96:99], v[144:147], v[136:139], v[96:99]
	s_waitcnt lgkmcnt(1)
	v_mfma_f32_16x16x32_bf16 v[92:95], v[152:155], v[124:127], v[92:95]
	v_mfma_f32_16x16x32_bf16 v[88:91], v[152:155], v[128:131], v[88:91]
	v_mfma_f32_16x16x32_bf16 v[84:87], v[152:155], v[132:135], v[84:87]
	v_mfma_f32_16x16x32_bf16 v[80:83], v[152:155], v[136:139], v[80:83]
	s_waitcnt lgkmcnt(0)
	v_mfma_f32_16x16x32_bf16 v[76:79], v[158:161], v[124:127], v[76:79]
	v_mfma_f32_16x16x32_bf16 v[72:75], v[158:161], v[128:131], v[72:75]
	v_mfma_f32_16x16x32_bf16 v[68:71], v[158:161], v[132:135], v[68:71]
	v_mfma_f32_16x16x32_bf16 v[64:67], v[158:161], v[136:139], v[64:67]
	ds_read_b128 v[140:143], v162 offset:4096
	ds_read_b128 v[144:147], v162 offset:5120
	ds_read_b128 v[152:155], v162 offset:6144
	ds_read_b128 v[158:161], v162 offset:7168
	s_waitcnt lgkmcnt(0)
	s_waitcnt vmcnt(0)
	s_barrier
	v_mfma_f32_16x16x32_bf16 v[60:63], v[140:143], v[124:127], v[60:63]
	v_mfma_f32_16x16x32_bf16 v[56:59], v[140:143], v[128:131], v[56:59]
	v_mfma_f32_16x16x32_bf16 v[52:55], v[140:143], v[132:135], v[52:55]
	v_mfma_f32_16x16x32_bf16 v[48:51], v[140:143], v[136:139], v[48:51]
	v_mfma_f32_16x16x32_bf16 v[44:47], v[144:147], v[124:127], v[44:47]
	v_mfma_f32_16x16x32_bf16 v[40:43], v[144:147], v[128:131], v[40:43]
	v_mfma_f32_16x16x32_bf16 v[36:39], v[144:147], v[132:135], v[36:39]
	v_mfma_f32_16x16x32_bf16 v[32:35], v[144:147], v[136:139], v[32:35]
	v_mfma_f32_16x16x32_bf16 v[28:31], v[152:155], v[124:127], v[28:31]
	v_mfma_f32_16x16x32_bf16 v[24:27], v[152:155], v[128:131], v[24:27]
	v_mfma_f32_16x16x32_bf16 v[20:23], v[152:155], v[132:135], v[20:23]
	v_mfma_f32_16x16x32_bf16 v[16:19], v[152:155], v[136:139], v[16:19]
	v_mfma_f32_16x16x32_bf16 v[12:15], v[158:161], v[124:127], v[12:15]
	v_mfma_f32_16x16x32_bf16 v[8:11], v[158:161], v[128:131], v[8:11]
	v_mfma_f32_16x16x32_bf16 v[4:7], v[158:161], v[132:135], v[4:7]
	v_mfma_f32_16x16x32_bf16 v[0:3], v[158:161], v[136:139], v[0:3]
	ds_read_b128 v[124:127], v163 offset:40960
	ds_read_b128 v[128:131], v163 offset:41984
	ds_read_b128 v[132:135], v163 offset:43008
	ds_read_b128 v[136:139], v163 offset:44032
	ds_read_b128 v[140:143], v162 offset:24576
	ds_read_b128 v[144:147], v162 offset:25600
	ds_read_b128 v[152:155], v162 offset:26624
	ds_read_b128 v[158:161], v162 offset:27648
	s_waitcnt lgkmcnt(3)
	v_mfma_f32_16x16x32_bf16 v[148:151], v[140:143], v[124:127], v[148:151]
	v_mfma_f32_16x16x32_bf16 v[120:123], v[140:143], v[128:131], v[120:123]
	v_mfma_f32_16x16x32_bf16 v[116:119], v[140:143], v[132:135], v[116:119]
	v_mfma_f32_16x16x32_bf16 v[112:115], v[140:143], v[136:139], v[112:115]
	s_waitcnt lgkmcnt(2)
	v_mfma_f32_16x16x32_bf16 v[108:111], v[144:147], v[124:127], v[108:111]
	v_mfma_f32_16x16x32_bf16 v[140:143], v[144:147], v[128:131], v[104:107]
	v_mfma_f32_16x16x32_bf16 v[164:167], v[144:147], v[132:135], v[100:103]
	v_mfma_f32_16x16x32_bf16 v[96:99], v[144:147], v[136:139], v[96:99]
	s_waitcnt lgkmcnt(1)
	v_mfma_f32_16x16x32_bf16 v[92:95], v[152:155], v[124:127], v[92:95]
	v_mfma_f32_16x16x32_bf16 v[88:91], v[152:155], v[128:131], v[88:91]
	v_mfma_f32_16x16x32_bf16 v[84:87], v[152:155], v[132:135], v[84:87]
	v_mfma_f32_16x16x32_bf16 v[80:83], v[152:155], v[136:139], v[80:83]
	ds_read_b128 v[100:103], v162 offset:28672
	ds_read_b128 v[104:107], v162 offset:29696
	ds_read_b128 v[144:147], v162 offset:30720
	ds_read_b128 v[152:155], v162 offset:31744
	s_waitcnt lgkmcnt(0)
	s_barrier
; DEV int TID() { int t = threadIdx.x; asm volatile("" : "+v"(t)); return t; }
; DEV void store_tile_f32_add(const f32x4 (&acc)[8][4], const float* xres, float* out, int m0, int n0, unsigned char* smem) {
;   const int tid = TID(), lane = tid & 63, wid = tid >> 6;
;   const int wr = wid >> 1, wc = wid & 1, fr = lane & 15, fq = lane >> 4;
;   float* st = (float*)(smem + wid * 8704);
;   const int chunk = lane & 15;
; #pragma unroll
;   for (int mq = 0; mq < 4; ++mq) {
; #pragma unroll
;     for (int mh = 0; mh < 2; ++mh)
; #pragma unroll
;       for (int ni = 0; ni < 4; ++ni)
; #pragma unroll
;         for (int j = 0; j < 4; ++j) st[(mh * 16 + fq * 4 + j) * 68 + ni * 16 + fr] = acc[mq * 2 + mh][ni][j];
; #pragma unroll
;     for (int itr = 0; itr < 8; ++itr) {
;       const int rl = (lane >> 4) + 4 * itr;
;       const f32x4 v = *(const f32x4*)(st + rl * 68 + chunk * 4);
;       const size_t idx = (size_t)(m0 + wr * 128 + mq * 32 + rl) * 2048 + n0 + wc * 64 + chunk * 4;
;       const f32x4 x = *(const f32x4*)(xres + idx);
;       *(f32x4*)(out + idx) = x + v;
;     }
;   }
	v_mfma_f32_16x16x32_bf16 v[60:63], v[100:103], v[124:127], v[60:63]
	v_mfma_f32_16x16x32_bf16 v[56:59], v[100:103], v[128:131], v[56:59]
	v_mfma_f32_16x16x32_bf16 v[52:55], v[100:103], v[132:135], v[52:55]
	v_mfma_f32_16x16x32_bf16 v[48:51], v[100:103], v[136:139], v[48:51]
	v_mov_b32_e32 v100, v178
	s_nop 0
	v_lshrrev_b32_e32 v101, 6, v100
	v_and_b32_e32 v103, 15, v100
	v_mfma_f32_16x16x32_bf16 v[44:47], v[104:107], v[124:127], v[44:47]
	v_mul_lo_u32 v101, v101, s5
	v_bfe_u32 v102, v100, 4, 2
	v_mfma_f32_16x16x32_bf16 v[40:43], v[104:107], v[128:131], v[40:43]
	v_mfma_f32_16x16x32_bf16 v[36:39], v[104:107], v[132:135], v[36:39]
	v_mfma_f32_16x16x32_bf16 v[32:35], v[104:107], v[136:139], v[32:35]
	v_lshlrev_b32_e32 v104, 2, v103
	v_or_b32_e32 v105, v101, v104
	v_and_b32_e32 v101, 0xffffff80, v100
	v_mad_u32_u24 v107, v103, 12, v105
	v_add_u32_e32 v103, s4, v101
	v_mov_b32_e32 v101, s3
	s_movk_i32 s3, 0x440
	v_mad_u32_u24 v106, v102, s3, v105
	ds_write_b32 v106, v148
	ds_write_b32 v106, v149 offset:272
	ds_write_b32 v106, v150 offset:544
	ds_write_b32 v106, v151 offset:816
	ds_write_b32 v106, v120 offset:64
	ds_write_b32 v106, v121 offset:336
	ds_write_b32 v106, v122 offset:608
	ds_write_b32 v106, v123 offset:880
	ds_write_b32 v106, v116 offset:128
	ds_write_b32 v106, v117 offset:400
	ds_write_b32 v106, v118 offset:672
	ds_write_b32 v106, v119 offset:944
	ds_write_b32 v106, v112 offset:192
	ds_write_b32 v106, v113 offset:464
	ds_write_b32 v106, v114 offset:736
	ds_write_b32 v106, v115 offset:1008
	ds_write_b32 v106, v108 offset:4352
	ds_write_b32 v106, v109 offset:4624
	ds_write_b32 v106, v110 offset:4896
	ds_write_b32 v106, v111 offset:5168
	ds_write_b32 v106, v140 offset:4416
	ds_write_b32 v106, v141 offset:4688
	ds_write_b32 v106, v142 offset:4960
	ds_write_b32 v106, v143 offset:5232
	ds_write_b32 v106, v164 offset:4480
	ds_write_b32 v106, v165 offset:4752
	ds_write_b32 v106, v166 offset:5024
	ds_write_b32 v106, v167 offset:5296
	ds_write_b32 v106, v96 offset:4544
	ds_write_b32 v106, v97 offset:4816
	ds_write_b32 v106, v98 offset:5088
	ds_write_b32 v106, v99 offset:5360
	v_or_b32_e32 v108, v103, v102
	v_and_b32_e32 v100, 64, v100
	v_ashrrev_i32_e32 v109, 31, v108
	v_or3_b32 v100, v104, v100, s2
	v_lshlrev_b64 v[108:109], 11, v[108:109]
	v_lshl_add_u64 v[108:109], v[100:101], 0, v[108:109]
	v_lshlrev_b64 v[112:113], 2, v[108:109]
	v_lshl_add_u64 v[108:109], s[20:21], 0, v[112:113]
	global_load_dwordx4 v[108:111], v[108:109], off
	s_movk_i32 s2, 0x110
	v_mad_u32_u24 v104, v102, s2, v107
	ds_read_b128 v[96:99], v104
	v_readlane_b32 s4, v251, 7
	v_readlane_b32 s6, v251, 9
	v_readlane_b32 s7, v251, 10
	v_or_b32_e32 v105, 20, v102
	v_mfma_f32_16x16x32_bf16 v[64:67], v[158:161], v[136:139], v[64:67]
	v_readlane_b32 s5, v251, 8
	s_waitcnt vmcnt(0) lgkmcnt(0)
	v_pk_add_f32 v[98:99], v[98:99], v[110:111]
	v_pk_add_f32 v[96:97], v[96:97], v[108:109]
	v_lshl_add_u64 v[108:109], s[6:7], 0, v[112:113]
	global_store_dwordx4 v[108:109], v[96:99], off
	v_or_b32_e32 v109, 4, v102
	v_or_b32_e32 v108, 28, v102
	v_or_b32_e32 v98, v109, v103
	v_ashrrev_i32_e32 v99, 31, v98
	v_lshlrev_b64 v[98:99], 11, v[98:99]
	v_lshl_add_u64 v[98:99], v[98:99], 0, v[100:101]
	v_lshlrev_b64 v[98:99], 2, v[98:99]
	v_lshl_add_u64 v[114:115], s[20:21], 0, v[98:99]
	global_load_dwordx4 v[114:117], v[114:115], off
	v_mad_u32_u24 v96, v109, s2, v107
	ds_read_b128 v[110:113], v96
	v_lshl_add_u64 v[98:99], s[6:7], 0, v[98:99]
	v_or_b32_e32 v97, 8, v102
	v_or_b32_e32 v107, 24, v102
	v_mfma_f32_16x16x32_bf16 v[76:79], v[158:161], v[124:127], v[76:79]
	s_waitcnt vmcnt(0) lgkmcnt(0)
	v_pk_add_f32 v[112:113], v[112:113], v[116:117]
	v_pk_add_f32 v[110:111], v[110:111], v[114:115]
	global_store_dwordx4 v[98:99], v[110:113], off
	v_or_b32_e32 v98, v97, v103
	v_ashrrev_i32_e32 v99, 31, v98
	v_lshlrev_b64 v[98:99], 11, v[98:99]
	v_lshl_add_u64 v[98:99], v[98:99], 0, v[100:101]
	v_lshlrev_b64 v[98:99], 2, v[98:99]
	v_lshl_add_u64 v[114:115], s[20:21], 0, v[98:99]
	global_load_dwordx4 v[114:117], v[114:115], off
	ds_read_b128 v[110:113], v96 offset:1088
	v_lshl_add_u64 v[98:99], s[6:7], 0, v[98:99]
	v_mfma_f32_16x16x32_bf16 v[72:75], v[158:161], v[128:131], v[72:75]
	s_waitcnt vmcnt(0) lgkmcnt(0)
	v_pk_add_f32 v[112:113], v[112:113], v[116:117]
	v_pk_add_f32 v[110:111], v[110:111], v[114:115]
	global_store_dwordx4 v[98:99], v[110:113], off
	v_or_b32_e32 v98, 12, v102
	v_or_b32_e32 v114, v98, v103
	v_ashrrev_i32_e32 v115, 31, v114
	v_lshlrev_b64 v[114:115], 11, v[114:115]
	v_lshl_add_u64 v[114:115], v[114:115], 0, v[100:101]
	v_lshlrev_b64 v[118:119], 2, v[114:115]
	v_lshl_add_u64 v[114:115], s[20:21], 0, v[118:119]
	global_load_dwordx4 v[114:117], v[114:115], off
	ds_read_b128 v[110:113], v96 offset:2176
	v_or_b32_e32 v99, 16, v102
	v_mfma_f32_16x16x32_bf16 v[68:71], v[158:161], v[132:135], v[68:71]
	s_waitcnt vmcnt(0) lgkmcnt(0)
	v_pk_add_f32 v[112:113], v[112:113], v[116:117]
	v_pk_add_f32 v[110:111], v[110:111], v[114:115]
	v_lshl_add_u64 v[114:115], s[6:7], 0, v[118:119]
	global_store_dwordx4 v[114:115], v[110:113], off
	v_or_b32_e32 v114, v99, v103
	v_ashrrev_i32_e32 v115, 31, v114
	v_lshlrev_b64 v[114:115], 11, v[114:115]
	v_lshl_add_u64 v[114:115], v[114:115], 0, v[100:101]
	v_lshlrev_b64 v[118:119], 2, v[114:115]
	v_lshl_add_u64 v[114:115], s[20:21], 0, v[118:119]
	global_load_dwordx4 v[114:117], v[114:115], off
	ds_read_b128 v[110:113], v96 offset:3264
	v_mfma_f32_16x16x32_bf16 v[28:31], v[144:147], v[124:127], v[28:31]
	s_waitcnt vmcnt(0) lgkmcnt(0)
; DEV int TID() { int t = threadIdx.x; asm volatile("" : "+v"(t)); return t; }
; DEV void store_tile_f32_add(const f32x4 (&acc)[8][4], const float* xres, float* out, int m0, int n0, unsigned char* smem) {
;   const int tid = TID(), lane = tid & 63, wid = tid >> 6;
;   const int wr = wid >> 1, wc = wid & 1, fr = lane & 15, fq = lane >> 4;
;   float* st = (float*)(smem + wid * 8704);
;   const int chunk = lane & 15;
; #pragma unroll
;   for (int mq = 0; mq < 4; ++mq) {
; #pragma unroll
;     for (int mh = 0; mh < 2; ++mh)
; #pragma unroll
;       for (int ni = 0; ni < 4; ++ni)
; #pragma unroll
;         for (int j = 0; j < 4; ++j) st[(mh * 16 + fq * 4 + j) * 68 + ni * 16 + fr] = acc[mq * 2 + mh][ni][j];
; #pragma unroll
;     for (int itr = 0; itr < 8; ++itr) {
;       const int rl = (lane >> 4) + 4 * itr;
;       const f32x4 v = *(const f32x4*)(st + rl * 68 + chunk * 4);
;       const size_t idx = (size_t)(m0 + wr * 128 + mq * 32 + rl) * 2048 + n0 + wc * 64 + chunk * 4;
;       const f32x4 x = *(const f32x4*)(xres + idx);
;       *(f32x4*)(out + idx) = x + v;
;     }
;   }
	v_pk_add_f32 v[112:113], v[112:113], v[116:117]
	v_pk_add_f32 v[110:111], v[110:111], v[114:115]
	v_lshl_add_u64 v[114:115], s[6:7], 0, v[118:119]
	global_store_dwordx4 v[114:115], v[110:113], off
	v_or_b32_e32 v114, v105, v103
	v_ashrrev_i32_e32 v115, 31, v114
	v_lshlrev_b64 v[114:115], 11, v[114:115]
	v_lshl_add_u64 v[114:115], v[114:115], 0, v[100:101]
	v_lshlrev_b64 v[118:119], 2, v[114:115]
	v_lshl_add_u64 v[114:115], s[20:21], 0, v[118:119]
	global_load_dwordx4 v[114:117], v[114:115], off
	ds_read_b128 v[110:113], v96 offset:4352
	v_mfma_f32_16x16x32_bf16 v[0:3], v[152:155], v[136:139], v[0:3]
	s_waitcnt vmcnt(0) lgkmcnt(0)
	v_pk_add_f32 v[112:113], v[112:113], v[116:117]
	v_pk_add_f32 v[110:111], v[110:111], v[114:115]
	v_lshl_add_u64 v[114:115], s[6:7], 0, v[118:119]
	global_store_dwordx4 v[114:115], v[110:113], off
	v_or_b32_e32 v114, v107, v103
	v_ashrrev_i32_e32 v115, 31, v114
	v_lshlrev_b64 v[114:115], 11, v[114:115]
	v_lshl_add_u64 v[114:115], v[114:115], 0, v[100:101]
	v_lshlrev_b64 v[118:119], 2, v[114:115]
	v_lshl_add_u64 v[114:115], s[20:21], 0, v[118:119]
	global_load_dwordx4 v[114:117], v[114:115], off
	ds_read_b128 v[110:113], v96 offset:5440
	v_mfma_f32_16x16x32_bf16 v[24:27], v[144:147], v[128:131], v[24:27]
	s_waitcnt vmcnt(0) lgkmcnt(0)
	v_pk_add_f32 v[112:113], v[112:113], v[116:117]
	v_pk_add_f32 v[110:111], v[110:111], v[114:115]
	v_lshl_add_u64 v[114:115], s[6:7], 0, v[118:119]
	global_store_dwordx4 v[114:115], v[110:113], off
	v_or_b32_e32 v114, v108, v103
	v_ashrrev_i32_e32 v115, 31, v114
	v_lshlrev_b64 v[114:115], 11, v[114:115]
	v_lshl_add_u64 v[114:115], v[114:115], 0, v[100:101]
	v_lshlrev_b64 v[118:119], 2, v[114:115]
	v_lshl_add_u64 v[114:115], s[20:21], 0, v[118:119]
	global_load_dwordx4 v[114:117], v[114:115], off
	ds_read_b128 v[110:113], v96 offset:6528
	v_mfma_f32_16x16x32_bf16 v[20:23], v[144:147], v[132:135], v[20:23]
	s_waitcnt vmcnt(0) lgkmcnt(0)
	v_pk_add_f32 v[112:113], v[112:113], v[116:117]
	v_pk_add_f32 v[110:111], v[110:111], v[114:115]
	v_lshl_add_u64 v[114:115], s[6:7], 0, v[118:119]
	global_store_dwordx4 v[114:115], v[110:113], off
	ds_write_b32 v106, v92
	ds_write_b32 v106, v93 offset:272
	ds_write_b32 v106, v94 offset:544
	ds_write_b32 v106, v95 offset:816
	ds_write_b32 v106, v88 offset:64
	ds_write_b32 v106, v89 offset:336
	ds_write_b32 v106, v90 offset:608
	ds_write_b32 v106, v91 offset:880
	ds_write_b32 v106, v84 offset:128
	ds_write_b32 v106, v85 offset:400
	ds_write_b32 v106, v86 offset:672
	ds_write_b32 v106, v87 offset:944
	ds_write_b32 v106, v80 offset:192
	ds_write_b32 v106, v81 offset:464
	ds_write_b32 v106, v82 offset:736
	ds_write_b32 v106, v83 offset:1008
	ds_write_b32 v106, v76 offset:4352
	ds_write_b32 v106, v77 offset:4624
	ds_write_b32 v106, v78 offset:4896
	ds_write_b32 v106, v79 offset:5168
	ds_write_b32 v106, v72 offset:4416
	ds_write_b32 v106, v73 offset:4688
	ds_write_b32 v106, v74 offset:4960
	ds_write_b32 v106, v75 offset:5232
	ds_write_b32 v106, v68 offset:4480
	ds_write_b32 v106, v69 offset:4752
	ds_write_b32 v106, v70 offset:5024
	ds_write_b32 v106, v71 offset:5296
	ds_write_b32 v106, v64 offset:4544
	ds_write_b32 v106, v65 offset:4816
	ds_write_b32 v106, v66 offset:5088
	ds_write_b32 v106, v67 offset:5360
	v_or_b32_e32 v64, 32, v103
	v_or_b32_e32 v70, v64, v102
	v_ashrrev_i32_e32 v71, 31, v70
	v_lshlrev_b64 v[70:71], 11, v[70:71]
	v_lshl_add_u64 v[70:71], v[70:71], 0, v[100:101]
	v_lshlrev_b64 v[74:75], 2, v[70:71]
	v_lshl_add_u64 v[70:71], s[20:21], 0, v[74:75]
	global_load_dwordx4 v[70:73], v[70:71], off
	ds_read_b128 v[66:69], v104
	v_mfma_f32_16x16x32_bf16 v[16:19], v[144:147], v[136:139], v[16:19]
	s_waitcnt vmcnt(0) lgkmcnt(0)
	v_pk_add_f32 v[68:69], v[68:69], v[72:73]
	v_pk_add_f32 v[66:67], v[66:67], v[70:71]
	v_lshl_add_u64 v[70:71], s[6:7], 0, v[74:75]
	global_store_dwordx4 v[70:71], v[66:69], off
	v_or_b32_e32 v70, v64, v109
	v_ashrrev_i32_e32 v71, 31, v70
	v_lshlrev_b64 v[70:71], 11, v[70:71]
	v_lshl_add_u64 v[70:71], v[70:71], 0, v[100:101]
	v_lshlrev_b64 v[74:75], 2, v[70:71]
	v_lshl_add_u64 v[70:71], s[20:21], 0, v[74:75]
	global_load_dwordx4 v[70:73], v[70:71], off
	ds_read_b128 v[66:69], v96
	v_mfma_f32_16x16x32_bf16 v[12:15], v[152:155], v[124:127], v[12:15]
	s_waitcnt vmcnt(0) lgkmcnt(0)
	v_pk_add_f32 v[68:69], v[68:69], v[72:73]
	v_pk_add_f32 v[66:67], v[66:67], v[70:71]
	v_lshl_add_u64 v[70:71], s[6:7], 0, v[74:75]
	global_store_dwordx4 v[70:71], v[66:69], off
	v_or_b32_e32 v70, v64, v97
	v_ashrrev_i32_e32 v71, 31, v70
	v_lshlrev_b64 v[70:71], 11, v[70:71]
	v_lshl_add_u64 v[70:71], v[70:71], 0, v[100:101]
	v_lshlrev_b64 v[74:75], 2, v[70:71]
	v_lshl_add_u64 v[70:71], s[20:21], 0, v[74:75]
	global_load_dwordx4 v[70:73], v[70:71], off
	ds_read_b128 v[66:69], v96 offset:1088
	v_mfma_f32_16x16x32_bf16 v[8:11], v[152:155], v[128:131], v[8:11]
	s_waitcnt vmcnt(0) lgkmcnt(0)
	v_pk_add_f32 v[68:69], v[68:69], v[72:73]
	v_pk_add_f32 v[66:67], v[66:67], v[70:71]
	v_lshl_add_u64 v[70:71], s[6:7], 0, v[74:75]
	global_store_dwordx4 v[70:71], v[66:69], off
	v_or_b32_e32 v70, v64, v98
	v_ashrrev_i32_e32 v71, 31, v70
	v_lshlrev_b64 v[70:71], 11, v[70:71]
	v_lshl_add_u64 v[70:71], v[70:71], 0, v[100:101]
	v_lshlrev_b64 v[74:75], 2, v[70:71]
	v_lshl_add_u64 v[70:71], s[20:21], 0, v[74:75]
	global_load_dwordx4 v[70:73], v[70:71], off
	ds_read_b128 v[66:69], v96 offset:2176
	v_mfma_f32_16x16x32_bf16 v[4:7], v[152:155], v[132:135], v[4:7]
	s_waitcnt vmcnt(0) lgkmcnt(0)
; DEV int TID() { int t = threadIdx.x; asm volatile("" : "+v"(t)); return t; }
; DEV void store_tile_f32_add(const f32x4 (&acc)[8][4], const float* xres, float* out, int m0, int n0, unsigned char* smem) {
;   const int tid = TID(), lane = tid & 63, wid = tid >> 6;
;   const int wr = wid >> 1, wc = wid & 1, fr = lane & 15, fq = lane >> 4;
;   float* st = (float*)(smem + wid * 8704);
;   const int chunk = lane & 15;
; #pragma unroll
;   for (int mq = 0; mq < 4; ++mq) {
; #pragma unroll
;     for (int mh = 0; mh < 2; ++mh)
; #pragma unroll
;       for (int ni = 0; ni < 4; ++ni)
; #pragma unroll
;         for (int j = 0; j < 4; ++j) st[(mh * 16 + fq * 4 + j) * 68 + ni * 16 + fr] = acc[mq * 2 + mh][ni][j];
; #pragma unroll
;     for (int itr = 0; itr < 8; ++itr) {
;       const int rl = (lane >> 4) + 4 * itr;
;       const f32x4 v = *(const f32x4*)(st + rl * 68 + chunk * 4);
;       const size_t idx = (size_t)(m0 + wr * 128 + mq * 32 + rl) * 2048 + n0 + wc * 64 + chunk * 4;
;       const f32x4 x = *(const f32x4*)(xres + idx);
;       *(f32x4*)(out + idx) = x + v;
;     }
;   }
	v_pk_add_f32 v[68:69], v[68:69], v[72:73]
	v_pk_add_f32 v[66:67], v[66:67], v[70:71]
	v_lshl_add_u64 v[70:71], s[6:7], 0, v[74:75]
	global_store_dwordx4 v[70:71], v[66:69], off
	v_or_b32_e32 v70, v64, v99
	v_ashrrev_i32_e32 v71, 31, v70
	v_lshlrev_b64 v[70:71], 11, v[70:71]
	v_lshl_add_u64 v[70:71], v[70:71], 0, v[100:101]
	v_lshlrev_b64 v[74:75], 2, v[70:71]
	v_lshl_add_u64 v[70:71], s[20:21], 0, v[74:75]
	global_load_dwordx4 v[70:73], v[70:71], off
	ds_read_b128 v[66:69], v96 offset:3264
	s_waitcnt vmcnt(0) lgkmcnt(0)
	v_pk_add_f32 v[68:69], v[68:69], v[72:73]
	v_pk_add_f32 v[66:67], v[66:67], v[70:71]
	v_lshl_add_u64 v[70:71], s[6:7], 0, v[74:75]
	global_store_dwordx4 v[70:71], v[66:69], off
	v_or_b32_e32 v70, v64, v105
	v_ashrrev_i32_e32 v71, 31, v70
	v_lshlrev_b64 v[70:71], 11, v[70:71]
	v_lshl_add_u64 v[70:71], v[70:71], 0, v[100:101]
	v_lshlrev_b64 v[74:75], 2, v[70:71]
	v_lshl_add_u64 v[70:71], s[20:21], 0, v[74:75]
	global_load_dwordx4 v[70:73], v[70:71], off
	ds_read_b128 v[66:69], v96 offset:4352
	s_waitcnt vmcnt(0) lgkmcnt(0)
	v_pk_add_f32 v[68:69], v[68:69], v[72:73]
	v_pk_add_f32 v[66:67], v[66:67], v[70:71]
	v_lshl_add_u64 v[70:71], s[6:7], 0, v[74:75]
	global_store_dwordx4 v[70:71], v[66:69], off
	v_or_b32_e32 v70, v64, v107
	v_ashrrev_i32_e32 v71, 31, v70
	v_lshlrev_b64 v[70:71], 11, v[70:71]
	v_lshl_add_u64 v[70:71], v[70:71], 0, v[100:101]
	v_lshlrev_b64 v[74:75], 2, v[70:71]
	v_lshl_add_u64 v[70:71], s[20:21], 0, v[74:75]
	global_load_dwordx4 v[70:73], v[70:71], off
	ds_read_b128 v[66:69], v96 offset:5440
	v_or_b32_e32 v64, v64, v108
	v_ashrrev_i32_e32 v65, 31, v64
	v_lshlrev_b64 v[64:65], 11, v[64:65]
	v_lshl_add_u64 v[64:65], v[64:65], 0, v[100:101]
	v_lshlrev_b64 v[64:65], 2, v[64:65]
	s_waitcnt vmcnt(0) lgkmcnt(0)
	v_pk_add_f32 v[68:69], v[68:69], v[72:73]
	v_pk_add_f32 v[66:67], v[66:67], v[70:71]
	v_lshl_add_u64 v[70:71], s[6:7], 0, v[74:75]
	global_store_dwordx4 v[70:71], v[66:69], off
	v_lshl_add_u64 v[70:71], s[20:21], 0, v[64:65]
	global_load_dwordx4 v[70:73], v[70:71], off
	ds_read_b128 v[66:69], v96 offset:6528
	v_lshl_add_u64 v[64:65], s[6:7], 0, v[64:65]
	s_waitcnt vmcnt(0) lgkmcnt(0)
	v_pk_add_f32 v[68:69], v[68:69], v[72:73]
	v_pk_add_f32 v[66:67], v[66:67], v[70:71]
	global_store_dwordx4 v[64:65], v[66:69], off
	ds_write_b32 v106, v60
	ds_write_b32 v106, v61 offset:272
	ds_write_b32 v106, v62 offset:544
	ds_write_b32 v106, v63 offset:816
	ds_write_b32 v106, v56 offset:64
	ds_write_b32 v106, v57 offset:336
	ds_write_b32 v106, v58 offset:608
	ds_write_b32 v106, v59 offset:880
	ds_write_b32 v106, v52 offset:128
	ds_write_b32 v106, v53 offset:400
	ds_write_b32 v106, v54 offset:672
	ds_write_b32 v106, v55 offset:944
	ds_write_b32 v106, v48 offset:192
	ds_write_b32 v106, v49 offset:464
	ds_write_b32 v106, v50 offset:736
	ds_write_b32 v106, v51 offset:1008
	ds_write_b32 v106, v44 offset:4352
	ds_write_b32 v106, v45 offset:4624
	ds_write_b32 v106, v46 offset:4896
	ds_write_b32 v106, v47 offset:5168
	ds_write_b32 v106, v40 offset:4416
	ds_write_b32 v106, v41 offset:4688
	ds_write_b32 v106, v42 offset:4960
	ds_write_b32 v106, v43 offset:5232
	ds_write_b32 v106, v36 offset:4480
	ds_write_b32 v106, v37 offset:4752
	ds_write_b32 v106, v38 offset:5024
	ds_write_b32 v106, v39 offset:5296
	ds_write_b32 v106, v32 offset:4544
	ds_write_b32 v106, v33 offset:4816
	ds_write_b32 v106, v34 offset:5088
	ds_write_b32 v106, v35 offset:5360
	v_or_b32_e32 v32, 64, v103
	v_or_b32_e32 v38, v32, v102
	v_ashrrev_i32_e32 v39, 31, v38
	v_lshlrev_b64 v[38:39], 11, v[38:39]
	v_lshl_add_u64 v[38:39], v[38:39], 0, v[100:101]
	v_lshlrev_b64 v[42:43], 2, v[38:39]
	v_lshl_add_u64 v[38:39], s[20:21], 0, v[42:43]
	global_load_dwordx4 v[38:41], v[38:39], off
	ds_read_b128 v[34:37], v104
	s_waitcnt vmcnt(0) lgkmcnt(0)
	v_pk_add_f32 v[36:37], v[36:37], v[40:41]
	v_pk_add_f32 v[34:35], v[34:35], v[38:39]
	v_lshl_add_u64 v[38:39], s[6:7], 0, v[42:43]
	global_store_dwordx4 v[38:39], v[34:37], off
	v_or_b32_e32 v38, v32, v109
	v_ashrrev_i32_e32 v39, 31, v38
	v_lshlrev_b64 v[38:39], 11, v[38:39]
	v_lshl_add_u64 v[38:39], v[38:39], 0, v[100:101]
	v_lshlrev_b64 v[42:43], 2, v[38:39]
	v_lshl_add_u64 v[38:39], s[20:21], 0, v[42:43]
	global_load_dwordx4 v[38:41], v[38:39], off
	ds_read_b128 v[34:37], v96
	s_waitcnt vmcnt(0) lgkmcnt(0)
	v_pk_add_f32 v[36:37], v[36:37], v[40:41]
	v_pk_add_f32 v[34:35], v[34:35], v[38:39]
	v_lshl_add_u64 v[38:39], s[6:7], 0, v[42:43]
	global_store_dwordx4 v[38:39], v[34:37], off
	v_or_b32_e32 v38, v32, v97
	v_ashrrev_i32_e32 v39, 31, v38
	v_lshlrev_b64 v[38:39], 11, v[38:39]
	v_lshl_add_u64 v[38:39], v[38:39], 0, v[100:101]
	v_lshlrev_b64 v[42:43], 2, v[38:39]
	v_lshl_add_u64 v[38:39], s[20:21], 0, v[42:43]
	global_load_dwordx4 v[38:41], v[38:39], off
	ds_read_b128 v[34:37], v96 offset:1088
	s_waitcnt vmcnt(0) lgkmcnt(0)
	v_pk_add_f32 v[36:37], v[36:37], v[40:41]
	v_pk_add_f32 v[34:35], v[34:35], v[38:39]
	v_lshl_add_u64 v[38:39], s[6:7], 0, v[42:43]
	global_store_dwordx4 v[38:39], v[34:37], off
	v_or_b32_e32 v38, v32, v98
	v_ashrrev_i32_e32 v39, 31, v38
	v_lshlrev_b64 v[38:39], 11, v[38:39]
	v_lshl_add_u64 v[38:39], v[38:39], 0, v[100:101]
	v_lshlrev_b64 v[42:43], 2, v[38:39]
	v_lshl_add_u64 v[38:39], s[20:21], 0, v[42:43]
	global_load_dwordx4 v[38:41], v[38:39], off
	ds_read_b128 v[34:37], v96 offset:2176
	s_waitcnt vmcnt(0) lgkmcnt(0)
	v_pk_add_f32 v[36:37], v[36:37], v[40:41]
	v_pk_add_f32 v[34:35], v[34:35], v[38:39]
	v_lshl_add_u64 v[38:39], s[6:7], 0, v[42:43]
	global_store_dwordx4 v[38:39], v[34:37], off
	v_or_b32_e32 v38, v32, v99
	v_ashrrev_i32_e32 v39, 31, v38
	v_lshlrev_b64 v[38:39], 11, v[38:39]
	v_lshl_add_u64 v[38:39], v[38:39], 0, v[100:101]
	v_lshlrev_b64 v[42:43], 2, v[38:39]
	v_lshl_add_u64 v[38:39], s[20:21], 0, v[42:43]
	global_load_dwordx4 v[38:41], v[38:39], off
	ds_read_b128 v[34:37], v96 offset:3264
	s_waitcnt vmcnt(0) lgkmcnt(0)
; DEV int TID() { int t = threadIdx.x; asm volatile("" : "+v"(t)); return t; }
; DEV void store_tile_f32_add(const f32x4 (&acc)[8][4], const float* xres, float* out, int m0, int n0, unsigned char* smem) {
;   const int tid = TID(), lane = tid & 63, wid = tid >> 6;
;   const int wr = wid >> 1, wc = wid & 1, fr = lane & 15, fq = lane >> 4;
;   float* st = (float*)(smem + wid * 8704);
;   const int chunk = lane & 15;
; #pragma unroll
;   for (int mq = 0; mq < 4; ++mq) {
; #pragma unroll
;     for (int mh = 0; mh < 2; ++mh)
; #pragma unroll
;       for (int ni = 0; ni < 4; ++ni)
; #pragma unroll
;         for (int j = 0; j < 4; ++j) st[(mh * 16 + fq * 4 + j) * 68 + ni * 16 + fr] = acc[mq * 2 + mh][ni][j];
; #pragma unroll
;     for (int itr = 0; itr < 8; ++itr) {
;       const int rl = (lane >> 4) + 4 * itr;
;       const f32x4 v = *(const f32x4*)(st + rl * 68 + chunk * 4);
;       const size_t idx = (size_t)(m0 + wr * 128 + mq * 32 + rl) * 2048 + n0 + wc * 64 + chunk * 4;
;       const f32x4 x = *(const f32x4*)(xres + idx);
;       *(f32x4*)(out + idx) = x + v;
;     }
;   }
	v_pk_add_f32 v[36:37], v[36:37], v[40:41]
	v_pk_add_f32 v[34:35], v[34:35], v[38:39]
	v_lshl_add_u64 v[38:39], s[6:7], 0, v[42:43]
	global_store_dwordx4 v[38:39], v[34:37], off
	v_or_b32_e32 v38, v32, v105
	v_ashrrev_i32_e32 v39, 31, v38
	v_lshlrev_b64 v[38:39], 11, v[38:39]
	v_lshl_add_u64 v[38:39], v[38:39], 0, v[100:101]
	v_lshlrev_b64 v[42:43], 2, v[38:39]
	v_lshl_add_u64 v[38:39], s[20:21], 0, v[42:43]
	global_load_dwordx4 v[38:41], v[38:39], off
	ds_read_b128 v[34:37], v96 offset:4352
	s_waitcnt vmcnt(0) lgkmcnt(0)
	v_pk_add_f32 v[36:37], v[36:37], v[40:41]
	v_pk_add_f32 v[34:35], v[34:35], v[38:39]
	v_lshl_add_u64 v[38:39], s[6:7], 0, v[42:43]
	global_store_dwordx4 v[38:39], v[34:37], off
	v_or_b32_e32 v38, v32, v107
	v_ashrrev_i32_e32 v39, 31, v38
	v_lshlrev_b64 v[38:39], 11, v[38:39]
	v_lshl_add_u64 v[38:39], v[38:39], 0, v[100:101]
	v_lshlrev_b64 v[42:43], 2, v[38:39]
	v_lshl_add_u64 v[38:39], s[20:21], 0, v[42:43]
	global_load_dwordx4 v[38:41], v[38:39], off
	ds_read_b128 v[34:37], v96 offset:5440
	v_or_b32_e32 v32, v32, v108
	v_ashrrev_i32_e32 v33, 31, v32
	v_lshlrev_b64 v[32:33], 11, v[32:33]
	v_lshl_add_u64 v[32:33], v[32:33], 0, v[100:101]
	v_lshlrev_b64 v[32:33], 2, v[32:33]
	s_waitcnt vmcnt(0) lgkmcnt(0)
	v_pk_add_f32 v[36:37], v[36:37], v[40:41]
	v_pk_add_f32 v[34:35], v[34:35], v[38:39]
	v_lshl_add_u64 v[38:39], s[6:7], 0, v[42:43]
	global_store_dwordx4 v[38:39], v[34:37], off
	v_lshl_add_u64 v[38:39], s[20:21], 0, v[32:33]
	global_load_dwordx4 v[38:41], v[38:39], off
	ds_read_b128 v[34:37], v96 offset:6528
	v_lshl_add_u64 v[32:33], s[6:7], 0, v[32:33]
	s_waitcnt vmcnt(0) lgkmcnt(0)
	v_pk_add_f32 v[36:37], v[36:37], v[40:41]
	v_pk_add_f32 v[34:35], v[34:35], v[38:39]
	global_store_dwordx4 v[32:33], v[34:37], off
	ds_write_b32 v106, v28
	ds_write_b32 v106, v29 offset:272
	ds_write_b32 v106, v30 offset:544
	ds_write_b32 v106, v31 offset:816
	ds_write_b32 v106, v24 offset:64
	ds_write_b32 v106, v25 offset:336
	ds_write_b32 v106, v26 offset:608
	ds_write_b32 v106, v27 offset:880
	ds_write_b32 v106, v20 offset:128
	ds_write_b32 v106, v21 offset:400
	ds_write_b32 v106, v22 offset:672
	ds_write_b32 v106, v23 offset:944
	ds_write_b32 v106, v16 offset:192
	ds_write_b32 v106, v17 offset:464
	ds_write_b32 v106, v18 offset:736
	ds_write_b32 v106, v19 offset:1008
	ds_write_b32 v106, v12 offset:4352
	ds_write_b32 v106, v13 offset:4624
	ds_write_b32 v106, v14 offset:4896
	ds_write_b32 v106, v15 offset:5168
	ds_write_b32 v106, v8 offset:4416
	ds_write_b32 v106, v9 offset:4688
	ds_write_b32 v106, v10 offset:4960
	ds_write_b32 v106, v11 offset:5232
	ds_write_b32 v106, v4 offset:4480
	ds_write_b32 v106, v5 offset:4752
	ds_write_b32 v106, v6 offset:5024
	ds_write_b32 v106, v7 offset:5296
	ds_write_b32 v106, v0 offset:4544
	ds_write_b32 v106, v1 offset:4816
	ds_write_b32 v106, v2 offset:5088
	ds_write_b32 v106, v3 offset:5360
	v_or_b32_e32 v0, 0x60, v103
	v_or_b32_e32 v6, v0, v102
	v_ashrrev_i32_e32 v7, 31, v6
	v_lshlrev_b64 v[6:7], 11, v[6:7]
	v_lshl_add_u64 v[6:7], v[6:7], 0, v[100:101]
	v_lshlrev_b64 v[10:11], 2, v[6:7]
	v_lshl_add_u64 v[6:7], s[20:21], 0, v[10:11]
	global_load_dwordx4 v[6:9], v[6:7], off
	ds_read_b128 v[2:5], v104
	s_waitcnt vmcnt(0) lgkmcnt(0)
	v_pk_add_f32 v[4:5], v[4:5], v[8:9]
	v_pk_add_f32 v[2:3], v[2:3], v[6:7]
	v_lshl_add_u64 v[6:7], s[6:7], 0, v[10:11]
	global_store_dwordx4 v[6:7], v[2:5], off
	v_or_b32_e32 v6, v0, v109
	v_ashrrev_i32_e32 v7, 31, v6
	v_lshlrev_b64 v[6:7], 11, v[6:7]
	v_lshl_add_u64 v[6:7], v[6:7], 0, v[100:101]
	v_lshlrev_b64 v[10:11], 2, v[6:7]
	v_lshl_add_u64 v[6:7], s[20:21], 0, v[10:11]
	global_load_dwordx4 v[6:9], v[6:7], off
	ds_read_b128 v[2:5], v96
	s_waitcnt vmcnt(0) lgkmcnt(0)
	v_pk_add_f32 v[4:5], v[4:5], v[8:9]
	v_pk_add_f32 v[2:3], v[2:3], v[6:7]
	v_lshl_add_u64 v[6:7], s[6:7], 0, v[10:11]
	global_store_dwordx4 v[6:7], v[2:5], off
	v_or_b32_e32 v6, v0, v97
	v_ashrrev_i32_e32 v7, 31, v6
	v_lshlrev_b64 v[6:7], 11, v[6:7]
	v_lshl_add_u64 v[6:7], v[6:7], 0, v[100:101]
	v_lshlrev_b64 v[10:11], 2, v[6:7]
	v_lshl_add_u64 v[6:7], s[20:21], 0, v[10:11]
	global_load_dwordx4 v[6:9], v[6:7], off
	ds_read_b128 v[2:5], v96 offset:1088
	s_waitcnt vmcnt(0) lgkmcnt(0)
	v_pk_add_f32 v[4:5], v[4:5], v[8:9]
	v_pk_add_f32 v[2:3], v[2:3], v[6:7]
	v_lshl_add_u64 v[6:7], s[6:7], 0, v[10:11]
	global_store_dwordx4 v[6:7], v[2:5], off
	v_or_b32_e32 v6, v0, v98
	v_ashrrev_i32_e32 v7, 31, v6
	v_lshlrev_b64 v[6:7], 11, v[6:7]
	v_lshl_add_u64 v[6:7], v[6:7], 0, v[100:101]
	v_lshlrev_b64 v[10:11], 2, v[6:7]
	v_lshl_add_u64 v[6:7], s[20:21], 0, v[10:11]
	global_load_dwordx4 v[6:9], v[6:7], off
	ds_read_b128 v[2:5], v96 offset:2176
	s_waitcnt vmcnt(0) lgkmcnt(0)
	v_pk_add_f32 v[4:5], v[4:5], v[8:9]
	v_pk_add_f32 v[2:3], v[2:3], v[6:7]
	v_lshl_add_u64 v[6:7], s[6:7], 0, v[10:11]
	global_store_dwordx4 v[6:7], v[2:5], off
	v_or_b32_e32 v6, v0, v99
	v_ashrrev_i32_e32 v7, 31, v6
	v_lshlrev_b64 v[6:7], 11, v[6:7]
	v_lshl_add_u64 v[6:7], v[6:7], 0, v[100:101]
	v_lshlrev_b64 v[10:11], 2, v[6:7]
	v_lshl_add_u64 v[6:7], s[20:21], 0, v[10:11]
	global_load_dwordx4 v[6:9], v[6:7], off
	ds_read_b128 v[2:5], v96 offset:3264
	s_waitcnt vmcnt(0) lgkmcnt(0)
	v_pk_add_f32 v[4:5], v[4:5], v[8:9]
	v_pk_add_f32 v[2:3], v[2:3], v[6:7]
	v_lshl_add_u64 v[6:7], s[6:7], 0, v[10:11]
	global_store_dwordx4 v[6:7], v[2:5], off
	v_or_b32_e32 v6, v0, v105
	v_ashrrev_i32_e32 v7, 31, v6
	v_lshlrev_b64 v[6:7], 11, v[6:7]
	v_lshl_add_u64 v[6:7], v[6:7], 0, v[100:101]
	v_lshlrev_b64 v[10:11], 2, v[6:7]
	v_lshl_add_u64 v[6:7], s[20:21], 0, v[10:11]
	global_load_dwordx4 v[6:9], v[6:7], off
	ds_read_b128 v[2:5], v96 offset:4352
	s_waitcnt vmcnt(0) lgkmcnt(0)
	v_pk_add_f32 v[4:5], v[4:5], v[8:9]
	v_pk_add_f32 v[2:3], v[2:3], v[6:7]
	v_lshl_add_u64 v[6:7], s[6:7], 0, v[10:11]
	global_store_dwordx4 v[6:7], v[2:5], off
	v_or_b32_e32 v6, v0, v107
	v_ashrrev_i32_e32 v7, 31, v6
	v_lshlrev_b64 v[6:7], 11, v[6:7]
	v_lshl_add_u64 v[6:7], v[6:7], 0, v[100:101]
	v_lshlrev_b64 v[10:11], 2, v[6:7]
	v_lshl_add_u64 v[6:7], s[20:21], 0, v[10:11]
	global_load_dwordx4 v[6:9], v[6:7], off
	ds_read_b128 v[2:5], v96 offset:5440
	v_or_b32_e32 v0, v0, v108
	v_ashrrev_i32_e32 v1, 31, v0
	v_lshlrev_b64 v[0:1], 11, v[0:1]
	v_lshl_add_u64 v[0:1], v[0:1], 0, v[100:101]
	v_lshlrev_b64 v[0:1], 2, v[0:1]
	s_waitcnt vmcnt(0) lgkmcnt(0)
	v_pk_add_f32 v[4:5], v[4:5], v[8:9]
	v_pk_add_f32 v[2:3], v[2:3], v[6:7]
	v_lshl_add_u64 v[6:7], s[6:7], 0, v[10:11]
	global_store_dwordx4 v[6:7], v[2:5], off
	v_lshl_add_u64 v[6:7], s[20:21], 0, v[0:1]
	global_load_dwordx4 v[6:9], v[6:7], off
	ds_read_b128 v[2:5], v96 offset:6528
	v_lshl_add_u64 v[0:1], s[6:7], 0, v[0:1]
	s_waitcnt vmcnt(0) lgkmcnt(0)
	v_pk_add_f32 v[4:5], v[4:5], v[8:9]
	v_pk_add_f32 v[2:3], v[2:3], v[6:7]
	global_store_dwordx4 v[0:1], v[2:5], off
	s_branch .LBB0_244

; DEV int TID() { int t = threadIdx.x; asm volatile("" : "+v"(t)); return t; }
; DEV void gemm_tile(const u16* __restrict__ A, size_t lda, const u16* __restrict__ Bt, size_t ldb, int K,
;                    u16* sA, u16* sB, f32x4 (&acc)[8][4]) {
;   const int tid = TID(), lane = tid & 63, wid = tid >> 6;
;   const int wr = wid >> 1, wc = wid & 1, fr = lane & 15, fq = lane >> 4;
; #pragma unroll
;   for (int mi = 0; mi < 8; ++mi)
; #pragma unroll
;     for (int ni = 0; ni < 4; ++ni) acc[mi][ni] = f32x4{0.f, 0.f, 0.f, 0.f};
;   const int lr = tid >> 2, lc = (tid & 3) * 8;
;   const u16* ap = A + (size_t)lr * lda + lc;
;   const u16* bp = Bt + (size_t)lr * ldb + lc;
;   u32x4 ra[4], rb[2];
;     ...
;   const int nk = K >> 5;
;   const int swz = ((fq ^ ((0 - (fr >> 2)) & 3)) << 3);
;   const u16* sAr = sA + (wr * 128 + fr) * 32 + swz;
;   const u16* sBr = sA + 256 * 32 + (wc * 64 + fr) * 32 + swz;
;   G_LOAD(0)
; PHASE void gemm_in_phase(const u16* H, const u16* WT, int nstart, int ncols, u16* OUT, unsigned char* smem) {
;     ...
;   for (int it = 0; it < nit; ++it) {
;     int mt, nt;
;     if (!tile_map(it, NT, mt, nt)) continue;
;     const int m0 = mt * 256, n0 = nt * 128;
;     f32x4 acc[8][4];
;     gemm_tile(H + (size_t)m0 * 2048, 2048, WT + (size_t)(nstart + n0) * 2048, 2048, 2048, sA, sB, acc);
.LBB0_413:
	s_lshl_b32 s4, s8, 8
	s_ashr_i32 s5, s4, 31
	v_mov_b32_e32 v7, v178
	s_lshl_b32 s14, s9, 7
	s_lshl_b64 s[8:9], s[4:5], 12
	s_add_u32 s6, s64, s8
	v_ashrrev_i32_e32 v32, 2, v7
	v_ashrrev_i32_e32 v33, 31, v32
	s_addc_u32 s7, s65, s9
	v_lshlrev_b64 v[34:35], 12, v[32:33]
	v_lshlrev_b32_e32 v2, 4, v7
	v_lshl_add_u64 v[0:1], s[6:7], 0, v[34:35]
	v_and_b32_e32 v156, 48, v2
	v_readlane_b32 s18, v249, 62
	v_lshl_add_u64 v[36:37], v[0:1], 0, v[156:157]
	s_mov_b32 s5, 0x40000
	v_readlane_b32 s19, v249, 63
	s_add_i32 s18, s14, 0x1d50
	v_add_co_u32_e32 v38, vcc, s5, v36
	s_lshl_b64 s[16:17], s[18:19], 12
	s_nop 0
	v_addc_co_u32_e32 v39, vcc, 0, v37, vcc
	s_mov_b32 s6, 0x80000
	s_add_u32 s16, s46, s16
	v_add_co_u32_e32 v40, vcc, s6, v36
	s_addc_u32 s17, s47, s17
	s_nop 0
	v_addc_co_u32_e32 v41, vcc, 0, v37, vcc
	s_mov_b32 s6, 0xc0000
	v_lshl_add_u64 v[0:1], s[16:17], 0, v[34:35]
	v_add_co_u32_e32 v42, vcc, s6, v36
	v_lshl_add_u64 v[44:45], v[0:1], 0, v[156:157]
	s_nop 0
	v_addc_co_u32_e32 v43, vcc, 0, v37, vcc
	v_add_co_u32_e32 v46, vcc, s5, v44
	v_addc_co_u32_e32 v47, vcc, 0, v45, vcc
	s_barrier
	v_lshrrev_b32_e32 v48, 2, v7
	v_lshrrev_b32_e32 v33, 4, v7
	v_sub_u32_e32 v48, 0, v48
	v_sub_u32_e32 v49, 0, v33
	v_xor_b32_e32 v33, v33, v48
	v_lshlrev_b32_e32 v33, 4, v33
	v_lshlrev_b32_e32 v50, 6, v7
	v_xor_b32_e32 v7, v7, v49
	v_lshl_add_u64 v[48:49], v[34:35], 0, s[8:9]
	v_and_b32_e32 v33, 48, v33
	s_movk_i32 s8, 0xe3c0
	v_and_or_b32 v162, v50, s8, v33
	s_movk_i32 s8, 0x13c0
	s_mov_b32 s9, s19
	v_lshlrev_b32_e32 v7, 4, v7
	v_and_or_b32 v163, v50, s8, v33
	s_add_i32 s18, s14, 0x1d00
	v_writelane_b32 v249, s8, 62
	v_and_b32_e32 v7, 48, v7
	v_lshl_or_b32 v164, v32, 6, v7
	v_writelane_b32 v249, s9, 63
	s_lshl_b64 s[8:9], s[18:19], 12
	v_lshl_add_u64 v[32:33], v[34:35], 0, s[8:9]
	v_mov_b32_e32 v0, 0
	v_or_b32_e32 v48, v48, v156
	v_or_b32_e32 v32, v32, v156
	s_mov_b32 s5, 0
	s_mov_b64 s[6:7], 0
	v_mov_b32_e32 v1, v0
	v_mov_b32_e32 v2, v0
	v_mov_b32_e32 v3, v0
	v_mov_b32_e32 v4, v0
	v_mov_b32_e32 v5, v0
	v_mov_b32_e32 v6, v0
	v_lshl_add_u64 v[158:159], s[46:47], 0, v[48:49]
	v_lshl_add_u64 v[160:161], s[46:47], 0, v[32:33]
	v_mov_b32_e32 v7, v0
	v_mov_b32_e32 v32, v0
	v_mov_b32_e32 v33, v0
	v_mov_b32_e32 v34, v0
	v_mov_b32_e32 v35, v0
	v_mov_b32_e32 v36, v0
	v_mov_b32_e32 v37, v0
	v_mov_b32_e32 v38, v0
	v_mov_b32_e32 v39, v0
	s_waitcnt lgkmcnt(0)
	s_barrier
	v_mov_b32_e32 v8, v0
	v_mov_b32_e32 v9, v0
	v_mov_b32_e32 v10, v0
	v_mov_b32_e32 v11, v0
	v_mov_b32_e32 v12, v0
	v_mov_b32_e32 v13, v0
	v_mov_b32_e32 v14, v0
	v_mov_b32_e32 v15, v0
	v_mov_b32_e32 v16, v0
	v_mov_b32_e32 v17, v0
	v_mov_b32_e32 v18, v0
	v_mov_b32_e32 v19, v0
	v_mov_b32_e32 v20, v0
	v_mov_b32_e32 v21, v0
	v_mov_b32_e32 v22, v0
	v_mov_b32_e32 v23, v0
	v_mov_b32_e32 v24, v0
	v_mov_b32_e32 v25, v0
	v_mov_b32_e32 v26, v0
	v_mov_b32_e32 v27, v0
	v_mov_b32_e32 v28, v0
	v_mov_b32_e32 v29, v0
	v_mov_b32_e32 v30, v0
	v_mov_b32_e32 v31, v0
	v_mov_b32_e32 v40, v0
	v_mov_b32_e32 v41, v0
	v_mov_b32_e32 v42, v0
	v_mov_b32_e32 v43, v0
	v_mov_b32_e32 v44, v0
	v_mov_b32_e32 v45, v0
	v_mov_b32_e32 v46, v0
	v_mov_b32_e32 v47, v0
	v_mov_b32_e32 v48, v0
	v_mov_b32_e32 v49, v0
	v_mov_b32_e32 v50, v0
	v_mov_b32_e32 v51, v0
	v_mov_b32_e32 v52, v0
	v_mov_b32_e32 v53, v0
	v_mov_b32_e32 v54, v0
	v_mov_b32_e32 v55, v0
	v_mov_b32_e32 v56, v0
	v_mov_b32_e32 v57, v0
	v_mov_b32_e32 v58, v0
	v_mov_b32_e32 v59, v0
	v_mov_b32_e32 v60, v0
	v_mov_b32_e32 v61, v0
	v_mov_b32_e32 v62, v0
	v_mov_b32_e32 v63, v0
	v_mov_b32_e32 v64, v0
	v_mov_b32_e32 v65, v0
	v_mov_b32_e32 v66, v0
	v_mov_b32_e32 v67, v0
	v_mov_b32_e32 v68, v0
	v_mov_b32_e32 v69, v0
	v_mov_b32_e32 v70, v0
	v_mov_b32_e32 v71, v0
	v_mov_b32_e32 v72, v0
	v_mov_b32_e32 v73, v0
	v_mov_b32_e32 v74, v0
	v_mov_b32_e32 v75, v0
	v_mov_b32_e32 v76, v0
	v_mov_b32_e32 v77, v0
	v_mov_b32_e32 v78, v0
	v_mov_b32_e32 v79, v0
	v_mov_b32_e32 v80, v0
	v_mov_b32_e32 v81, v0
	v_mov_b32_e32 v82, v0
	v_mov_b32_e32 v83, v0
	v_mov_b32_e32 v84, v0
	v_mov_b32_e32 v85, v0
	v_mov_b32_e32 v86, v0
	v_mov_b32_e32 v87, v0
	v_mov_b32_e32 v88, v0
	v_mov_b32_e32 v89, v0
	v_mov_b32_e32 v90, v0
	v_mov_b32_e32 v91, v0
	v_mov_b32_e32 v92, v0
	v_mov_b32_e32 v93, v0
	v_mov_b32_e32 v94, v0
	v_mov_b32_e32 v95, v0
	v_mov_b32_e32 v96, v0
	v_mov_b32_e32 v97, v0
	v_mov_b32_e32 v98, v0
	v_mov_b32_e32 v99, v0
	v_mov_b32_e32 v100, v0
	v_mov_b32_e32 v101, v0
	v_mov_b32_e32 v102, v0
	v_mov_b32_e32 v103, v0
	v_mov_b32_e32 v104, v0
	v_mov_b32_e32 v105, v0
	v_mov_b32_e32 v106, v0
	v_mov_b32_e32 v107, v0
	v_mov_b32_e32 v108, v0
	v_mov_b32_e32 v109, v0
	v_mov_b32_e32 v110, v0
	v_mov_b32_e32 v111, v0
	v_mov_b32_e32 v112, v0
	v_mov_b32_e32 v113, v0
	v_mov_b32_e32 v114, v0
	v_mov_b32_e32 v115, v0
	v_mov_b32_e32 v124, v0
	v_mov_b32_e32 v125, v0
	v_mov_b32_e32 v126, v0
	v_mov_b32_e32 v127, v0
	v_mov_b32_e32 v144, v0
	v_mov_b32_e32 v145, v0
	v_mov_b32_e32 v146, v0
	v_mov_b32_e32 v147, v0
	v_mov_b32_e32 v148, v0
	v_mov_b32_e32 v149, v0
	v_mov_b32_e32 v150, v0
	v_mov_b32_e32 v151, v0
	s_mov_b32 s15, 0xa6d0000
	s_mov_b32 s16, 0xa710000
	v_lshl_add_u64 v[132:133], v[158:159], 0, s[6:7]
	v_add_co_u32_e32 v136, vcc, s15, v132
	s_nop 1
	v_addc_co_u32_e32 v137, vcc, 0, v133, vcc
	v_add_co_u32_e32 v138, vcc, s16, v132
	s_nop 1
	v_addc_co_u32_e32 v139, vcc, 0, v133, vcc
	v_add_co_u32_e32 v174, vcc, s95, v132
	s_nop 1
	v_addc_co_u32_e32 v175, vcc, 0, v133, vcc
	v_add_co_u32_e32 v176, vcc, s74, v132
	v_lshl_add_u64 v[134:135], v[160:161], 0, s[6:7]
	s_nop 1
	v_addc_co_u32_e32 v177, vcc, 0, v133, vcc
	s_mov_b32 s8, 0x50000
	v_add_co_u32_e32 v186, vcc, s8, v134
	s_nop 1
	v_addc_co_u32_e32 v187, vcc, 0, v135, vcc
	s_mov_b32 s8, 0x90000
; DEV f32x4 mfma16(bf16x8 a, bf16x8 b, f32x4 c) { return __builtin_amdgcn_mfma_f32_16x16x32_bf16(a, b, c, 0, 0, 0); }
; DEV void gemm_tile(const u16* __restrict__ A, size_t lda, const u16* __restrict__ Bt, size_t ldb, int K,
;                    u16* sA, u16* sB, f32x4 (&acc)[8][4]) {
;     ...
;   const int nk = K >> 5;
;   const int swz = ((fq ^ ((0 - (fr >> 2)) & 3)) << 3);
;   const u16* sAr = sA + (wr * 128 + fr) * 32 + swz;
;   const u16* sBr = sA + 256 * 32 + (wc * 64 + fr) * 32 + swz;
;   G_LOAD(0)
;   __syncthreads();
;   S_STORE(0)
;   if (nk > 1) G_LOAD(32)
;   __syncthreads();
;   for (int kt = 0; kt < nk; ++kt) {
;     const int st = kt & 1;
;     if (kt + 1 < nk) S_STORE(st ^ 1)
;     if (kt + 2 < nk) G_LOAD((kt + 2) << 5)
;     {
;       const u16* pa = sAr + st * 12288;
;       const u16* pb = sBr + st * 12288;
;       bf16x8 b[4];
; #pragma unroll
;       for (int ni = 0; ni < 4; ++ni) b[ni] = *(const bf16x8*)(pb + ni * 16 * 32);
; #pragma unroll
;       for (int mh = 0; mh < 2; ++mh) {
;         bf16x8 a[4];
; #pragma unroll
;         for (int mi = 0; mi < 4; ++mi) a[mi] = *(const bf16x8*)(pa + (mh * 64 + mi * 16) * 32);
; #pragma unroll
;         for (int mi = 0; mi < 4; ++mi)
; #pragma unroll
;           for (int ni = 0; ni < 4; ++ni) acc[mh * 4 + mi][ni] = mfma16(a[mi], b[ni], acc[mh * 4 + mi][ni]);
;       }
;     }
;     __syncthreads();
;   }
	v_add_co_u32_e32 v188, vcc, s8, v134
	s_nop 1
	v_addc_co_u32_e32 v189, vcc, 0, v135, vcc
	v_lshrrev_b32_e32 v228, 4, v178
	v_sub_u32_e32 v228, 0, v228
	v_and_b32_e32 v228, 3, v228
	v_lshlrev_b32_e32 v228, 4, v228
	v_lshrrev_b32_e32 v229, 6, v178
	v_lshlrev_b32_e32 v229, 10, v229
	v_xor_b32_e32 v136, v136, v228
	v_xor_b32_e32 v138, v138, v228
	v_xor_b32_e32 v174, v174, v228
	v_xor_b32_e32 v176, v176, v228
	v_xor_b32_e32 v186, v186, v228
	v_xor_b32_e32 v188, v188, v228
	v_readfirstlane_b32 s5, v229
	s_nop 1
	s_add_i32 s9, s5, 0x6000
	s_add_i32 m0, s9, 0x0
	s_nop 0
	global_load_lds_dwordx4 v[136:137], off
	v_lshl_add_u64 v[136:137], v[136:137], 0, 64
	s_add_i32 m0, s9, 0x1000
	s_nop 0
	global_load_lds_dwordx4 v[138:139], off
	v_lshl_add_u64 v[138:139], v[138:139], 0, 64
	s_add_i32 m0, s9, 0x2000
	s_nop 0
	global_load_lds_dwordx4 v[174:175], off
	v_lshl_add_u64 v[174:175], v[174:175], 0, 64
	s_add_i32 m0, s9, 0x3000
	s_nop 0
	global_load_lds_dwordx4 v[176:177], off
	v_lshl_add_u64 v[176:177], v[176:177], 0, 64
	s_add_i32 m0, s9, 0x4000
	s_nop 0
	global_load_lds_dwordx4 v[186:187], off
	v_lshl_add_u64 v[186:187], v[186:187], 0, 64
	s_add_i32 m0, s9, 0x5000
	s_nop 0
	global_load_lds_dwordx4 v[188:189], off
	v_lshl_add_u64 v[188:189], v[188:189], 0, 64
	s_add_i32 s9, s5, 0xc000
	s_add_i32 m0, s9, 0x0
	s_nop 0
	global_load_lds_dwordx4 v[136:137], off
	v_lshl_add_u64 v[136:137], v[136:137], 0, 64
	s_add_i32 m0, s9, 0x1000
	s_nop 0
	global_load_lds_dwordx4 v[138:139], off
	v_lshl_add_u64 v[138:139], v[138:139], 0, 64
	s_add_i32 m0, s9, 0x2000
	s_nop 0
	global_load_lds_dwordx4 v[174:175], off
	v_lshl_add_u64 v[174:175], v[174:175], 0, 64
	s_add_i32 m0, s9, 0x3000
	s_nop 0
	global_load_lds_dwordx4 v[176:177], off
	v_lshl_add_u64 v[176:177], v[176:177], 0, 64
	s_add_i32 m0, s9, 0x4000
	s_nop 0
	global_load_lds_dwordx4 v[186:187], off
	v_lshl_add_u64 v[186:187], v[186:187], 0, 64
	s_add_i32 m0, s9, 0x5000
	s_nop 0
	global_load_lds_dwordx4 v[188:189], off
	v_lshl_add_u64 v[188:189], v[188:189], 0, 64
	v_and_b32_e32 v230, 63, v178
	v_lshlrev_b32_e32 v230, 4, v230
	s_mov_b32 s8, 0x6000
	s_mov_b32 s9, s5
	s_waitcnt vmcnt(6)
	s_barrier
.LBB0_414:
	v_add_u32_e32 v229, s8, v163
	v_add_u32_e32 v228, s8, v162
	ds_read_b128 v[116:119], v229 offset:16384
	ds_read_b128 v[166:169], v228
	ds_read_b128 v[128:131], v229 offset:17408
	ds_read_b128 v[140:143], v229 offset:18432
	ds_read_b128 v[120:123], v229 offset:19456
	ds_read_b128 v[152:155], v228 offset:1024
	ds_read_b128 v[170:173], v228 offset:2048
	ds_read_b128 v[132:135], v228 offset:3072
	s_waitcnt lgkmcnt(6)
	v_mfma_f32_16x16x32_bf16 v[148:151], v[166:169], v[116:119], v[148:151]
	s_add_i32 m0, s9, 0x0
	s_waitcnt lgkmcnt(5)
	v_mfma_f32_16x16x32_bf16 v[144:147], v[166:169], v[128:131], v[144:147]
	global_load_lds_dwordx4 v[136:137], off
	v_lshl_add_u64 v[136:137], v[136:137], 0, 64
	global_load_dwordx4 v[244:247], v[136:137], off
	v_lshl_add_u64 v[136:137], v[136:137], 0, 64
	s_waitcnt lgkmcnt(4)
	v_mfma_f32_16x16x32_bf16 v[124:127], v[166:169], v[140:143], v[124:127]
	s_add_i32 m0, s9, 0x1000
	s_waitcnt lgkmcnt(3)
	v_mfma_f32_16x16x32_bf16 v[112:115], v[166:169], v[120:123], v[112:115]
	ds_read_b128 v[232:235], v228 offset:4096
	ds_read_b128 v[236:239], v228 offset:5120
	s_waitcnt lgkmcnt(4)
	v_mfma_f32_16x16x32_bf16 v[108:111], v[152:155], v[116:119], v[108:111]
	global_load_lds_dwordx4 v[138:139], off
	v_lshl_add_u64 v[138:139], v[138:139], 0, 64
	global_load_dwordx4 v[252:255], v[138:139], off
	v_lshl_add_u64 v[138:139], v[138:139], 0, 64
	v_mfma_f32_16x16x32_bf16 v[104:107], v[152:155], v[128:131], v[104:107]
	s_add_i32 m0, s9, 0x2000
	v_mfma_f32_16x16x32_bf16 v[100:103], v[152:155], v[140:143], v[100:103]
	global_load_lds_dwordx4 v[174:175], off
	v_lshl_add_u64 v[174:175], v[174:175], 0, 64
	global_load_dwordx4 v[208:211], v[174:175], off
	v_lshl_add_u64 v[174:175], v[174:175], 0, 64
	v_mfma_f32_16x16x32_bf16 v[96:99], v[152:155], v[120:123], v[96:99]
	s_add_i32 m0, s9, 0x3000
	s_waitcnt lgkmcnt(3)
	v_mfma_f32_16x16x32_bf16 v[92:95], v[170:173], v[116:119], v[92:95]
	global_load_lds_dwordx4 v[176:177], off
	v_lshl_add_u64 v[176:177], v[176:177], 0, 64
	global_load_dwordx4 v[212:215], v[176:177], off
	v_lshl_add_u64 v[176:177], v[176:177], 0, 64
	v_mfma_f32_16x16x32_bf16 v[88:91], v[170:173], v[128:131], v[88:91]
	s_add_i32 m0, s9, 0x4000
	v_mfma_f32_16x16x32_bf16 v[84:87], v[170:173], v[140:143], v[84:87]
	global_load_lds_dwordx4 v[186:187], off
	v_lshl_add_u64 v[186:187], v[186:187], 0, 64
	global_load_dwordx4 v[216:219], v[186:187], off
	v_lshl_add_u64 v[186:187], v[186:187], 0, 64
	v_mfma_f32_16x16x32_bf16 v[80:83], v[170:173], v[120:123], v[80:83]
	ds_read_b128 v[240:243], v228 offset:6144
	ds_read_b128 v[166:169], v228 offset:7168
	s_waitcnt lgkmcnt(4)
	v_mfma_f32_16x16x32_bf16 v[76:79], v[132:135], v[116:119], v[76:79]
	s_add_i32 m0, s9, 0x5000
	v_mfma_f32_16x16x32_bf16 v[72:75], v[132:135], v[128:131], v[72:75]
	global_load_lds_dwordx4 v[188:189], off
	v_lshl_add_u64 v[188:189], v[188:189], 0, 64
	global_load_dwordx4 v[220:223], v[188:189], off
	v_lshl_add_u64 v[188:189], v[188:189], 0, 64
	v_mfma_f32_16x16x32_bf16 v[68:71], v[132:135], v[140:143], v[68:71]
	s_add_i32 s9, s8, s5
	s_add_i32 s8, s8, 0x6000
	v_mfma_f32_16x16x32_bf16 v[64:67], v[132:135], v[120:123], v[64:67]
	s_cmp_eq_u32 s8, 0x12000
	s_cselect_b32 s8, 0, s8
	s_waitcnt lgkmcnt(3)
	v_mfma_f32_16x16x32_bf16 v[60:63], v[232:235], v[116:119], v[60:63]
	s_add_u32 s6, s6, 64
	s_addc_u32 s7, s7, 0
	s_cmpk_lg_i32 s6, 0xf80
	v_mfma_f32_16x16x32_bf16 v[56:59], v[232:235], v[128:131], v[56:59]
	v_mfma_f32_16x16x32_bf16 v[52:55], v[232:235], v[140:143], v[52:55]
	v_mfma_f32_16x16x32_bf16 v[48:51], v[232:235], v[120:123], v[48:51]
	s_waitcnt lgkmcnt(2)
	v_mfma_f32_16x16x32_bf16 v[44:47], v[236:239], v[116:119], v[44:47]
	v_mfma_f32_16x16x32_bf16 v[40:43], v[236:239], v[128:131], v[40:43]
	v_mfma_f32_16x16x32_bf16 v[36:39], v[236:239], v[140:143], v[36:39]
	v_mfma_f32_16x16x32_bf16 v[32:35], v[236:239], v[120:123], v[32:35]
	s_waitcnt lgkmcnt(1)
	v_mfma_f32_16x16x32_bf16 v[28:31], v[240:243], v[116:119], v[28:31]
	v_mfma_f32_16x16x32_bf16 v[24:27], v[240:243], v[128:131], v[24:27]
	v_mfma_f32_16x16x32_bf16 v[20:23], v[240:243], v[140:143], v[20:23]
	v_mfma_f32_16x16x32_bf16 v[16:19], v[240:243], v[120:123], v[16:19]
	s_waitcnt lgkmcnt(0)
	s_waitcnt vmcnt(12)
	s_barrier
; DEV f32x4 mfma16(bf16x8 a, bf16x8 b, f32x4 c) { return __builtin_amdgcn_mfma_f32_16x16x32_bf16(a, b, c, 0, 0, 0); }
; DEV void gemm_tile(const u16* __restrict__ A, size_t lda, const u16* __restrict__ Bt, size_t ldb, int K,
;                    u16* sA, u16* sB, f32x4 (&acc)[8][4]) {
;     ...
;   for (int kt = 0; kt < nk; ++kt) {
;     const int st = kt & 1;
;     if (kt + 1 < nk) S_STORE(st ^ 1)
;     if (kt + 2 < nk) G_LOAD((kt + 2) << 5)
;     {
;       const u16* pa = sAr + st * 12288;
;       const u16* pb = sBr + st * 12288;
;       bf16x8 b[4];
; #pragma unroll
;       for (int ni = 0; ni < 4; ++ni) b[ni] = *(const bf16x8*)(pb + ni * 16 * 32);
; #pragma unroll
;       for (int mh = 0; mh < 2; ++mh) {
;         bf16x8 a[4];
; #pragma unroll
;         for (int mi = 0; mi < 4; ++mi) a[mi] = *(const bf16x8*)(pa + (mh * 64 + mi * 16) * 32);
; #pragma unroll
;         for (int mi = 0; mi < 4; ++mi)
; #pragma unroll
;           for (int ni = 0; ni < 4; ++ni) acc[mh * 4 + mi][ni] = mfma16(a[mi], b[ni], acc[mh * 4 + mi][ni]);
;       }
;     }
;     __syncthreads();
;   }
	v_mfma_f32_16x16x32_bf16 v[12:15], v[166:169], v[116:119], v[12:15]
	v_mfma_f32_16x16x32_bf16 v[8:11], v[166:169], v[128:131], v[8:11]
	v_mfma_f32_16x16x32_bf16 v[4:7], v[166:169], v[140:143], v[4:7]
	v_mfma_f32_16x16x32_bf16 v[0:3], v[166:169], v[120:123], v[0:3]
	v_add_u32_e32 v229, s8, v163
	v_add_u32_e32 v228, s8, v162
	ds_read_b128 v[116:119], v229 offset:16384
	ds_read_b128 v[166:169], v228
	ds_read_b128 v[128:131], v229 offset:17408
	ds_read_b128 v[140:143], v229 offset:18432
	ds_read_b128 v[120:123], v229 offset:19456
	ds_read_b128 v[152:155], v228 offset:1024
	ds_read_b128 v[170:173], v228 offset:2048
	ds_read_b128 v[132:135], v228 offset:3072
	s_waitcnt lgkmcnt(6)
	v_mfma_f32_16x16x32_bf16 v[148:151], v[166:169], v[116:119], v[148:151]
	s_waitcnt vmcnt(0)
	v_add_u32_e32 v231, s9, v230
	s_waitcnt lgkmcnt(5)
	v_mfma_f32_16x16x32_bf16 v[144:147], v[166:169], v[128:131], v[144:147]
	ds_write_b128 v231, v[244:247]
	s_waitcnt lgkmcnt(5)
	v_mfma_f32_16x16x32_bf16 v[124:127], v[166:169], v[140:143], v[124:127]
	ds_write_b128 v231, v[252:255] offset:4096
	s_waitcnt lgkmcnt(5)
	v_mfma_f32_16x16x32_bf16 v[112:115], v[166:169], v[120:123], v[112:115]
	ds_read_b128 v[232:235], v228 offset:4096
	ds_read_b128 v[236:239], v228 offset:5120
	s_waitcnt lgkmcnt(6)
	v_mfma_f32_16x16x32_bf16 v[108:111], v[152:155], v[116:119], v[108:111]
	ds_write_b128 v231, v[208:211] offset:8192
	v_mfma_f32_16x16x32_bf16 v[104:107], v[152:155], v[128:131], v[104:107]
	ds_write_b128 v231, v[212:215] offset:12288
	v_mfma_f32_16x16x32_bf16 v[100:103], v[152:155], v[140:143], v[100:103]
	ds_write_b128 v231, v[216:219] offset:16384
	v_mfma_f32_16x16x32_bf16 v[96:99], v[152:155], v[120:123], v[96:99]
	ds_write_b128 v231, v[220:223] offset:20480
	s_waitcnt lgkmcnt(9)
	v_mfma_f32_16x16x32_bf16 v[92:95], v[170:173], v[116:119], v[92:95]
	s_add_i32 s9, s8, s5
	s_add_i32 s8, s8, 0x6000
	v_mfma_f32_16x16x32_bf16 v[88:91], v[170:173], v[128:131], v[88:91]
	s_cmp_eq_u32 s8, 0x12000
	s_cselect_b32 s8, 0, s8
	v_mfma_f32_16x16x32_bf16 v[84:87], v[170:173], v[140:143], v[84:87]
	s_add_u32 s6, s6, 64
	s_addc_u32 s7, s7, 0
	s_cmpk_lg_i32 s6, 0xf80
	v_mfma_f32_16x16x32_bf16 v[80:83], v[170:173], v[120:123], v[80:83]
	ds_read_b128 v[240:243], v228 offset:6144
	ds_read_b128 v[166:169], v228 offset:7168
	s_waitcnt lgkmcnt(10)
	v_mfma_f32_16x16x32_bf16 v[76:79], v[132:135], v[116:119], v[76:79]
	v_mfma_f32_16x16x32_bf16 v[72:75], v[132:135], v[128:131], v[72:75]
	v_mfma_f32_16x16x32_bf16 v[68:71], v[132:135], v[140:143], v[68:71]
	v_mfma_f32_16x16x32_bf16 v[64:67], v[132:135], v[120:123], v[64:67]
	s_waitcnt lgkmcnt(7)
	v_mfma_f32_16x16x32_bf16 v[60:63], v[232:235], v[116:119], v[60:63]
	v_mfma_f32_16x16x32_bf16 v[56:59], v[232:235], v[128:131], v[56:59]
	v_mfma_f32_16x16x32_bf16 v[52:55], v[232:235], v[140:143], v[52:55]
	v_mfma_f32_16x16x32_bf16 v[48:51], v[232:235], v[120:123], v[48:51]
	s_waitcnt lgkmcnt(6)
	v_mfma_f32_16x16x32_bf16 v[44:47], v[236:239], v[116:119], v[44:47]
	v_mfma_f32_16x16x32_bf16 v[40:43], v[236:239], v[128:131], v[40:43]
	v_mfma_f32_16x16x32_bf16 v[36:39], v[236:239], v[140:143], v[36:39]
	v_mfma_f32_16x16x32_bf16 v[32:35], v[236:239], v[120:123], v[32:35]
	s_waitcnt lgkmcnt(1)
	v_mfma_f32_16x16x32_bf16 v[28:31], v[240:243], v[116:119], v[28:31]
	v_mfma_f32_16x16x32_bf16 v[24:27], v[240:243], v[128:131], v[24:27]
	v_mfma_f32_16x16x32_bf16 v[20:23], v[240:243], v[140:143], v[20:23]
	v_mfma_f32_16x16x32_bf16 v[16:19], v[240:243], v[120:123], v[16:19]
	s_waitcnt lgkmcnt(0)
	s_waitcnt lgkmcnt(0)
	s_barrier
	v_mfma_f32_16x16x32_bf16 v[12:15], v[166:169], v[116:119], v[12:15]
	v_mfma_f32_16x16x32_bf16 v[8:11], v[166:169], v[128:131], v[8:11]
	v_mfma_f32_16x16x32_bf16 v[4:7], v[166:169], v[140:143], v[4:7]
	v_mfma_f32_16x16x32_bf16 v[0:3], v[166:169], v[120:123], v[0:3]
	s_cbranch_scc1 .LBB0_414
	ds_read_b128 v[116:119], v163 offset:16384
	ds_read_b128 v[120:123], v163 offset:17408
	ds_read_b128 v[128:131], v163 offset:18432
	ds_read_b128 v[132:135], v163 offset:19456
	ds_read_b128 v[136:139], v162
	ds_read_b128 v[140:143], v162 offset:1024
	ds_read_b128 v[152:155], v162 offset:2048
	ds_read_b128 v[158:161], v162 offset:3072
	s_movk_i32 s5, 0xff9
	s_waitcnt lgkmcnt(3)
	v_mfma_f32_16x16x32_bf16 v[148:151], v[136:139], v[116:119], v[148:151]
	v_mfma_f32_16x16x32_bf16 v[144:147], v[136:139], v[120:123], v[144:147]
	v_mfma_f32_16x16x32_bf16 v[164:167], v[136:139], v[128:131], v[124:127]
	v_mfma_f32_16x16x32_bf16 v[112:115], v[136:139], v[132:135], v[112:115]
	s_waitcnt lgkmcnt(2)
	v_mfma_f32_16x16x32_bf16 v[108:111], v[140:143], v[116:119], v[108:111]
	v_mfma_f32_16x16x32_bf16 v[104:107], v[140:143], v[120:123], v[104:107]
	v_mfma_f32_16x16x32_bf16 v[100:103], v[140:143], v[128:131], v[100:103]
	v_mfma_f32_16x16x32_bf16 v[96:99], v[140:143], v[132:135], v[96:99]
	s_waitcnt lgkmcnt(1)
	v_mfma_f32_16x16x32_bf16 v[92:95], v[152:155], v[116:119], v[92:95]
	v_mfma_f32_16x16x32_bf16 v[88:91], v[152:155], v[120:123], v[88:91]
	v_mfma_f32_16x16x32_bf16 v[84:87], v[152:155], v[128:131], v[84:87]
	v_mfma_f32_16x16x32_bf16 v[80:83], v[152:155], v[132:135], v[80:83]
	ds_read_b128 v[124:127], v162 offset:4096
	ds_read_b128 v[136:139], v162 offset:5120
	ds_read_b128 v[140:143], v162 offset:6144
	ds_read_b128 v[152:155], v162 offset:7168
	s_waitcnt lgkmcnt(0)
	s_waitcnt vmcnt(0)
	s_barrier
; DEV f32x4 mfma16(bf16x8 a, bf16x8 b, f32x4 c) { return __builtin_amdgcn_mfma_f32_16x16x32_bf16(a, b, c, 0, 0, 0); }
; DEV void gemm_tile(const u16* __restrict__ A, size_t lda, const u16* __restrict__ Bt, size_t ldb, int K,
;                    u16* sA, u16* sB, f32x4 (&acc)[8][4]) {
;     ...
;   for (int kt = 0; kt < nk; ++kt) {
;     const int st = kt & 1;
;     if (kt + 1 < nk) S_STORE(st ^ 1)
;     if (kt + 2 < nk) G_LOAD((kt + 2) << 5)
;     {
;       const u16* pa = sAr + st * 12288;
;       const u16* pb = sBr + st * 12288;
;       bf16x8 b[4];
; #pragma unroll
;       for (int ni = 0; ni < 4; ++ni) b[ni] = *(const bf16x8*)(pb + ni * 16 * 32);
; #pragma unroll
;       for (int mh = 0; mh < 2; ++mh) {
;         bf16x8 a[4];
; #pragma unroll
;         for (int mi = 0; mi < 4; ++mi) a[mi] = *(const bf16x8*)(pa + (mh * 64 + mi * 16) * 32);
; #pragma unroll
;         for (int mi = 0; mi < 4; ++mi)
; #pragma unroll
;           for (int ni = 0; ni < 4; ++ni) acc[mh * 4 + mi][ni] = mfma16(a[mi], b[ni], acc[mh * 4 + mi][ni]);
;       }
;     }
;     __syncthreads();
;   }
; DEV void store_tile_bf16(const f32x4 (&acc)[8][4], u16* __restrict__ OUT, size_t ld, int m0, int n0, int ncols,
;                          unsigned char* smem) {
;     ...
; #pragma unroll
;   for (int mh = 0; mh < 2; ++mh) {
; #pragma unroll
;     for (int mi = 0; mi < 4; ++mi)
; #pragma unroll
;       for (int ni = 0; ni < 4; ++ni)
; #pragma unroll
;         for (int j = 0; j < 4; ++j) st[(mi * 16 + fq * 4 + j) * 72 + ni * 16 + fr] = f2bf(acc[mh * 4 + mi][ni][j]);
	v_mfma_f32_16x16x32_bf16 v[76:79], v[158:161], v[116:119], v[76:79]
	v_mfma_f32_16x16x32_bf16 v[72:75], v[158:161], v[120:123], v[72:75]
	v_mfma_f32_16x16x32_bf16 v[68:71], v[158:161], v[128:131], v[68:71]
	v_mfma_f32_16x16x32_bf16 v[64:67], v[158:161], v[132:135], v[64:67]
	v_mfma_f32_16x16x32_bf16 v[52:55], v[124:127], v[128:131], v[52:55]
	v_mfma_f32_16x16x32_bf16 v[48:51], v[124:127], v[132:135], v[48:51]
	v_mfma_f32_16x16x32_bf16 v[44:47], v[136:139], v[116:119], v[44:47]
	v_mfma_f32_16x16x32_bf16 v[40:43], v[136:139], v[120:123], v[40:43]
	v_mfma_f32_16x16x32_bf16 v[36:39], v[136:139], v[128:131], v[36:39]
	v_mfma_f32_16x16x32_bf16 v[32:35], v[136:139], v[132:135], v[32:35]
	v_mfma_f32_16x16x32_bf16 v[28:31], v[140:143], v[116:119], v[28:31]
	v_mfma_f32_16x16x32_bf16 v[24:27], v[140:143], v[120:123], v[24:27]
	v_mfma_f32_16x16x32_bf16 v[20:23], v[140:143], v[128:131], v[20:23]
	v_mfma_f32_16x16x32_bf16 v[16:19], v[140:143], v[132:135], v[16:19]
	v_mfma_f32_16x16x32_bf16 v[12:15], v[152:155], v[116:119], v[12:15]
	v_mfma_f32_16x16x32_bf16 v[8:11], v[152:155], v[120:123], v[8:11]
	v_mfma_f32_16x16x32_bf16 v[4:7], v[152:155], v[128:131], v[4:7]
	v_mfma_f32_16x16x32_bf16 v[0:3], v[152:155], v[132:135], v[0:3]
	ds_read_b128 v[128:131], v163 offset:40960
	ds_read_b128 v[132:135], v163 offset:41984
	ds_read_b128 v[136:139], v163 offset:43008
	ds_read_b128 v[140:143], v163 offset:44032
	ds_read_b128 v[152:155], v162 offset:24576
	ds_read_b128 v[158:161], v162 offset:25600
	ds_read_b128 v[168:171], v162 offset:26624
	ds_read_b128 v[172:175], v162 offset:27648
	v_mfma_f32_16x16x32_bf16 v[60:63], v[124:127], v[116:119], v[60:63]
	v_mfma_f32_16x16x32_bf16 v[56:59], v[124:127], v[120:123], v[56:59]
	s_waitcnt lgkmcnt(3)
	v_mfma_f32_16x16x32_bf16 v[124:127], v[152:155], v[128:131], v[148:151]
	v_mfma_f32_16x16x32_bf16 v[120:123], v[152:155], v[132:135], v[144:147]
	v_mfma_f32_16x16x32_bf16 v[116:119], v[152:155], v[136:139], v[164:167]
	v_mfma_f32_16x16x32_bf16 v[112:115], v[152:155], v[140:143], v[112:115]
	s_waitcnt lgkmcnt(2)
	v_mfma_f32_16x16x32_bf16 v[108:111], v[158:161], v[128:131], v[108:111]
	v_mfma_f32_16x16x32_bf16 v[104:107], v[158:161], v[132:135], v[104:107]
	v_mfma_f32_16x16x32_bf16 v[100:103], v[158:161], v[136:139], v[100:103]
	v_mfma_f32_16x16x32_bf16 v[96:99], v[158:161], v[140:143], v[96:99]
	ds_read_b128 v[144:147], v162 offset:28672
	ds_read_b128 v[148:151], v162 offset:29696
	ds_read_b128 v[152:155], v162 offset:30720
	ds_read_b128 v[158:161], v162 offset:31744
	s_waitcnt lgkmcnt(0)
	s_barrier
	v_mfma_f32_16x16x32_bf16 v[92:95], v[168:171], v[128:131], v[92:95]
	v_mfma_f32_16x16x32_bf16 v[76:79], v[172:175], v[128:131], v[76:79]
	v_mfma_f32_16x16x32_bf16 v[60:63], v[144:147], v[128:131], v[60:63]
	v_mfma_f32_16x16x32_bf16 v[44:47], v[148:151], v[128:131], v[44:47]
	v_mfma_f32_16x16x32_bf16 v[28:31], v[152:155], v[128:131], v[28:31]
	v_mfma_f32_16x16x32_bf16 v[12:15], v[158:161], v[128:131], v[12:15]
	v_mov_b32_e32 v129, v178
	s_nop 0
	v_lshrrev_b32_e32 v128, 6, v129
	v_mfma_f32_16x16x32_bf16 v[88:91], v[168:171], v[132:135], v[88:91]
	v_mul_lo_u32 v131, v128, s75
	v_lshrrev_b32_e32 v128, 2, v129
	v_and_b32_e32 v130, 15, v129
	v_mfma_f32_16x16x32_bf16 v[72:75], v[172:175], v[132:135], v[72:75]
	v_lshl_or_b32 v130, v130, 1, v131
	v_mfma_f32_16x16x32_bf16 v[56:59], v[144:147], v[132:135], v[56:59]
	v_mfma_f32_16x16x32_bf16 v[40:43], v[148:151], v[132:135], v[40:43]
	v_mfma_f32_16x16x32_bf16 v[24:27], v[152:155], v[132:135], v[24:27]
	v_mfma_f32_16x16x32_bf16 v[8:11], v[158:161], v[132:135], v[8:11]
	v_lshlrev_b32_e32 v133, 3, v129
	v_and_b32_e32 v132, 12, v128
	v_and_b32_e32 v128, 64, v129
	v_and_b32_e32 v133, 56, v133
	v_or3_b32 v128, v128, s14, v133
	v_lshl_or_b32 v131, v133, 1, v131
	v_bfe_u32 v133, v129, 3, 3
	v_and_b32_e32 v129, 0xffffff80, v129
	v_add_u32_e32 v134, s4, v129
	v_bfe_u32 v135, v124, 16, 1
	s_movk_i32 s4, 0x90
	v_add3_u32 v135, v124, v135, s71
	v_mad_u32_u24 v124, v132, s4, v130
	v_bfe_u32 v130, v125, 16, 1
	v_add3_u32 v125, v125, v130, s71
	ds_write_b16_d16_hi v124, v125 offset:144
	v_bfe_u32 v125, v126, 16, 1
	v_add3_u32 v125, v126, v125, s71
	ds_write_b16_d16_hi v124, v125 offset:288
	v_bfe_u32 v125, v127, 16, 1
	v_add3_u32 v125, v127, v125, s71
	ds_write_b16_d16_hi v124, v125 offset:432
	v_bfe_u32 v125, v120, 16, 1
	v_add3_u32 v120, v120, v125, s71
	ds_write_b16_d16_hi v124, v120 offset:32
	v_bfe_u32 v120, v121, 16, 1
	v_add3_u32 v120, v121, v120, s71
	ds_write_b16_d16_hi v124, v120 offset:176
	v_bfe_u32 v120, v122, 16, 1
	v_add3_u32 v120, v122, v120, s71
	ds_write_b16_d16_hi v124, v120 offset:320
	v_bfe_u32 v120, v123, 16, 1
	v_add3_u32 v120, v123, v120, s71
	ds_write_b16_d16_hi v124, v120 offset:464
	v_bfe_u32 v120, v116, 16, 1
	v_add3_u32 v116, v116, v120, s71
	ds_write_b16_d16_hi v124, v116 offset:64
	v_bfe_u32 v116, v117, 16, 1
	v_add3_u32 v116, v117, v116, s71
	ds_write_b16_d16_hi v124, v116 offset:208
	v_bfe_u32 v116, v118, 16, 1
	v_add3_u32 v116, v118, v116, s71
	ds_write_b16_d16_hi v124, v116 offset:352
	v_bfe_u32 v116, v119, 16, 1
	v_add3_u32 v116, v119, v116, s71
	ds_write_b16_d16_hi v124, v116 offset:496
	v_bfe_u32 v116, v112, 16, 1
	v_add3_u32 v112, v112, v116, s71
	ds_write_b16_d16_hi v124, v112 offset:96
	v_bfe_u32 v112, v113, 16, 1
	v_add3_u32 v112, v113, v112, s71
	ds_write_b16_d16_hi v124, v112 offset:240
	v_bfe_u32 v112, v114, 16, 1
	v_add3_u32 v112, v114, v112, s71
	ds_write_b16_d16_hi v124, v112 offset:384
	v_bfe_u32 v112, v115, 16, 1
	v_add3_u32 v112, v115, v112, s71
	ds_write_b16_d16_hi v124, v112 offset:528
	v_bfe_u32 v112, v108, 16, 1
	v_add3_u32 v108, v108, v112, s71
; DEV void store_tile_bf16(const f32x4 (&acc)[8][4], u16* __restrict__ OUT, size_t ld, int m0, int n0, int ncols,
;                          unsigned char* smem) {
;     ...
; #pragma unroll
;   for (int mh = 0; mh < 2; ++mh) {
; #pragma unroll
;     for (int mi = 0; mi < 4; ++mi)
; #pragma unroll
;       for (int ni = 0; ni < 4; ++ni)
; #pragma unroll
;         for (int j = 0; j < 4; ++j) st[(mi * 16 + fq * 4 + j) * 72 + ni * 16 + fr] = f2bf(acc[mh * 4 + mi][ni][j]);
	ds_write_b16_d16_hi v124, v108 offset:2304
	v_bfe_u32 v108, v109, 16, 1
	v_add3_u32 v108, v109, v108, s71
	ds_write_b16_d16_hi v124, v108 offset:2448
	v_bfe_u32 v108, v110, 16, 1
	v_add3_u32 v108, v110, v108, s71
	ds_write_b16_d16_hi v124, v108 offset:2592
	v_bfe_u32 v108, v111, 16, 1
	v_add3_u32 v108, v111, v108, s71
	ds_write_b16_d16_hi v124, v108 offset:2736
	v_bfe_u32 v108, v104, 16, 1
	v_add3_u32 v104, v104, v108, s71
	ds_write_b16_d16_hi v124, v104 offset:2336
	v_bfe_u32 v104, v105, 16, 1
	v_add3_u32 v104, v105, v104, s71
	ds_write_b16_d16_hi v124, v104 offset:2480
	v_bfe_u32 v104, v106, 16, 1
	v_add3_u32 v104, v106, v104, s71
	ds_write_b16_d16_hi v124, v104 offset:2624
	v_bfe_u32 v104, v107, 16, 1
	v_add3_u32 v104, v107, v104, s71
	ds_write_b16_d16_hi v124, v104 offset:2768
	v_bfe_u32 v104, v100, 16, 1
	v_add3_u32 v100, v100, v104, s71
	ds_write_b16_d16_hi v124, v100 offset:2368
	v_bfe_u32 v100, v101, 16, 1
	v_add3_u32 v100, v101, v100, s71
	ds_write_b16_d16_hi v124, v100 offset:2512
	v_bfe_u32 v100, v102, 16, 1
	v_add3_u32 v100, v102, v100, s71
	ds_write_b16_d16_hi v124, v100 offset:2656
	v_bfe_u32 v100, v103, 16, 1
	v_add3_u32 v100, v103, v100, s71
	ds_write_b16_d16_hi v124, v100 offset:2800
	v_bfe_u32 v100, v96, 16, 1
	v_add3_u32 v96, v96, v100, s71
	ds_write_b16_d16_hi v124, v96 offset:2400
	v_bfe_u32 v96, v97, 16, 1
	v_add3_u32 v96, v97, v96, s71
	ds_write_b16_d16_hi v124, v96 offset:2544
	v_bfe_u32 v96, v98, 16, 1
	v_add3_u32 v96, v98, v96, s71
	ds_write_b16_d16_hi v124, v96 offset:2688
	v_bfe_u32 v96, v99, 16, 1
	v_add3_u32 v96, v99, v96, s71
	ds_write_b16_d16_hi v124, v96 offset:2832
	v_bfe_u32 v96, v92, 16, 1
	v_add3_u32 v92, v92, v96, s71
	ds_write_b16_d16_hi v124, v92 offset:4608
	v_bfe_u32 v92, v93, 16, 1
	v_add3_u32 v92, v93, v92, s71
	ds_write_b16_d16_hi v124, v92 offset:4752
	v_bfe_u32 v92, v94, 16, 1
	v_add3_u32 v92, v94, v92, s71
	ds_write_b16_d16_hi v124, v92 offset:4896
	v_bfe_u32 v92, v95, 16, 1
	v_add3_u32 v92, v95, v92, s71
	ds_write_b16_d16_hi v124, v92 offset:5040
	v_bfe_u32 v92, v88, 16, 1
	v_add3_u32 v88, v88, v92, s71
	ds_write_b16_d16_hi v124, v88 offset:4640
	v_bfe_u32 v88, v89, 16, 1
	v_add3_u32 v88, v89, v88, s71
	v_mfma_f32_16x16x32_bf16 v[84:87], v[168:171], v[136:139], v[84:87]
	ds_write_b16_d16_hi v124, v88 offset:4784
	v_bfe_u32 v88, v90, 16, 1
	v_add3_u32 v88, v90, v88, s71
	ds_write_b16_d16_hi v124, v88 offset:4928
	v_bfe_u32 v88, v91, 16, 1
	v_add3_u32 v88, v91, v88, s71
	ds_write_b16_d16_hi v124, v88 offset:5072
	s_nop 0
	v_bfe_u32 v88, v84, 16, 1
	v_add3_u32 v84, v84, v88, s71
	ds_write_b16_d16_hi v124, v84 offset:4672
	v_bfe_u32 v84, v85, 16, 1
	v_add3_u32 v84, v85, v84, s71
	v_mfma_f32_16x16x32_bf16 v[80:83], v[168:171], v[140:143], v[80:83]
	ds_write_b16_d16_hi v124, v84 offset:4816
	v_bfe_u32 v84, v86, 16, 1
	v_add3_u32 v84, v86, v84, s71
	ds_write_b16_d16_hi v124, v84 offset:4960
	v_bfe_u32 v84, v87, 16, 1
	v_add3_u32 v84, v87, v84, s71
	ds_write_b16_d16_hi v124, v84 offset:5104
	s_nop 0
	v_bfe_u32 v84, v80, 16, 1
	v_add3_u32 v80, v80, v84, s71
	ds_write_b16_d16_hi v124, v80 offset:4704
	v_bfe_u32 v80, v81, 16, 1
	v_add3_u32 v80, v81, v80, s71
	ds_write_b16_d16_hi v124, v80 offset:4848
	v_bfe_u32 v80, v82, 16, 1
	v_add3_u32 v80, v82, v80, s71
	ds_write_b16_d16_hi v124, v80 offset:4992
	v_bfe_u32 v80, v83, 16, 1
	v_add3_u32 v80, v83, v80, s71
	ds_write_b16_d16_hi v124, v80 offset:5136
	v_bfe_u32 v80, v76, 16, 1
	v_add3_u32 v76, v76, v80, s71
	ds_write_b16_d16_hi v124, v76 offset:6912
	v_bfe_u32 v76, v77, 16, 1
	v_add3_u32 v76, v77, v76, s71
	ds_write_b16_d16_hi v124, v76 offset:7056
	v_bfe_u32 v76, v78, 16, 1
	v_add3_u32 v76, v78, v76, s71
	ds_write_b16_d16_hi v124, v76 offset:7200
	v_bfe_u32 v76, v79, 16, 1
	v_add3_u32 v76, v79, v76, s71
	ds_write_b16_d16_hi v124, v76 offset:7344
	v_bfe_u32 v76, v72, 16, 1
	v_add3_u32 v72, v72, v76, s71
	ds_write_b16_d16_hi v124, v72 offset:6944
	v_bfe_u32 v72, v73, 16, 1
	v_add3_u32 v72, v73, v72, s71
	v_mfma_f32_16x16x32_bf16 v[68:71], v[172:175], v[136:139], v[68:71]
	ds_write_b16_d16_hi v124, v72 offset:7088
	v_bfe_u32 v72, v74, 16, 1
	v_add3_u32 v72, v74, v72, s71
	ds_write_b16_d16_hi v124, v72 offset:7232
	v_bfe_u32 v72, v75, 16, 1
	v_add3_u32 v72, v75, v72, s71
	ds_write_b16_d16_hi v124, v72 offset:7376
	s_nop 0
	v_bfe_u32 v72, v68, 16, 1
	v_add3_u32 v68, v68, v72, s71
	ds_write_b16_d16_hi v124, v68 offset:6976
	v_bfe_u32 v68, v69, 16, 1
	v_add3_u32 v68, v69, v68, s71
	v_mfma_f32_16x16x32_bf16 v[64:67], v[172:175], v[140:143], v[64:67]
	ds_write_b16_d16_hi v124, v68 offset:7120
	v_bfe_u32 v68, v70, 16, 1
	v_add3_u32 v68, v70, v68, s71
	ds_write_b16_d16_hi v124, v68 offset:7264
	v_bfe_u32 v68, v71, 16, 1
	v_add3_u32 v68, v71, v68, s71
	ds_write_b16_d16_hi v124, v68 offset:7408
	s_nop 0
	v_bfe_u32 v68, v64, 16, 1
	v_add3_u32 v64, v64, v68, s71
	ds_write_b16_d16_hi v124, v64 offset:7008
	v_bfe_u32 v64, v65, 16, 1
	v_add3_u32 v64, v65, v64, s71
	ds_write_b16_d16_hi v124, v64 offset:7152
	v_bfe_u32 v64, v66, 16, 1
	v_mfma_f32_16x16x32_bf16 v[52:55], v[144:147], v[136:139], v[52:55]
	v_add3_u32 v64, v66, v64, s71
	ds_write_b16_d16_hi v124, v64 offset:7296
	v_bfe_u32 v64, v67, 16, 1
	v_mfma_f32_16x16x32_bf16 v[48:51], v[144:147], v[140:143], v[48:51]
	v_ashrrev_i32_e32 v129, 31, v128
	v_add3_u32 v64, v67, v64, s71
	v_cmp_gt_i32_e32 vcc, s5, v128
	v_mfma_f32_16x16x32_bf16 v[36:39], v[148:151], v[136:139], v[36:39]
	v_lshl_add_u64 v[128:129], v[128:129], 1, s[68:69]
	ds_write_b16_d16_hi v124, v64 offset:7440
	v_mad_u32_u24 v66, v133, s4, v131
	v_mfma_f32_16x16x32_bf16 v[32:35], v[148:151], v[140:143], v[32:35]
	v_or_b32_e32 v64, v134, v133
	ds_write_b16_d16_hi v124, v135
	v_mfma_f32_16x16x32_bf16 v[20:23], v[152:155], v[136:139], v[20:23]
	v_mfma_f32_16x16x32_bf16 v[16:19], v[152:155], v[140:143], v[16:19]
	v_mfma_f32_16x16x32_bf16 v[4:7], v[158:161], v[136:139], v[4:7]
	v_mfma_f32_16x16x32_bf16 v[0:3], v[158:161], v[140:143], v[0:3]
	s_and_saveexec_b64 s[4:5], vcc
	s_cbranch_execz .LBB0_417
; DEV void store_tile_bf16(const f32x4 (&acc)[8][4], u16* __restrict__ OUT, size_t ld, int m0, int n0, int ncols,
;                          unsigned char* smem) {
;     ...
;     const int chunk = lane & 7;
;     const int c0 = n0 + wc * 64 + chunk * 8;
; #pragma unroll
;     for (int itr = 0; itr < 8; ++itr) {
;       const int rl = (lane >> 3) + 8 * itr;
;       const u32x4 v = *(const u32x4*)(st + rl * 72 + chunk * 8);
;       if (c0 + 8 <= ncols) *(u32x4*)(OUT + (size_t)(m0 + wr * 128 + mh * 64 + rl) * ld + c0) = v;
;     }
	ds_read_b128 v[68:71], v66
	v_ashrrev_i32_e32 v65, 31, v64
	v_lshlrev_b64 v[72:73], 13, v[64:65]
	v_lshl_add_u64 v[72:73], v[128:129], 0, v[72:73]
	s_waitcnt lgkmcnt(0)
	global_store_dwordx4 v[72:73], v[68:71], off
	ds_read_b128 v[68:71], v66 offset:1152
	v_or_b32_e32 v72, 8, v64
	v_ashrrev_i32_e32 v73, 31, v72
	v_lshlrev_b64 v[72:73], 13, v[72:73]
	v_lshl_add_u64 v[72:73], v[128:129], 0, v[72:73]
	s_waitcnt lgkmcnt(0)
	global_store_dwordx4 v[72:73], v[68:71], off
	ds_read_b128 v[68:71], v66 offset:2304
	v_or_b32_e32 v72, 16, v64
	v_ashrrev_i32_e32 v73, 31, v72
	v_lshlrev_b64 v[72:73], 13, v[72:73]
	v_lshl_add_u64 v[72:73], v[128:129], 0, v[72:73]
	s_waitcnt lgkmcnt(0)
	global_store_dwordx4 v[72:73], v[68:71], off
	ds_read_b128 v[68:71], v66 offset:3456
	v_or_b32_e32 v72, 24, v64
	v_ashrrev_i32_e32 v73, 31, v72
	v_lshlrev_b64 v[72:73], 13, v[72:73]
	v_lshl_add_u64 v[72:73], v[128:129], 0, v[72:73]
	s_waitcnt lgkmcnt(0)
	global_store_dwordx4 v[72:73], v[68:71], off
	ds_read_b128 v[68:71], v66 offset:4608
	v_or_b32_e32 v72, 32, v64
	v_ashrrev_i32_e32 v73, 31, v72
	v_lshlrev_b64 v[72:73], 13, v[72:73]
	v_lshl_add_u64 v[72:73], v[128:129], 0, v[72:73]
	s_waitcnt lgkmcnt(0)
	global_store_dwordx4 v[72:73], v[68:71], off
	ds_read_b128 v[68:71], v66 offset:5760
	v_or_b32_e32 v72, 40, v64
	v_ashrrev_i32_e32 v73, 31, v72
	v_lshlrev_b64 v[72:73], 13, v[72:73]
	v_lshl_add_u64 v[72:73], v[128:129], 0, v[72:73]
	s_waitcnt lgkmcnt(0)
	global_store_dwordx4 v[72:73], v[68:71], off
	ds_read_b128 v[68:71], v66 offset:6912
	v_or_b32_e32 v72, 48, v64
	v_ashrrev_i32_e32 v73, 31, v72
	v_lshlrev_b64 v[72:73], 13, v[72:73]
	v_lshl_add_u64 v[72:73], v[128:129], 0, v[72:73]
	s_waitcnt lgkmcnt(0)
	global_store_dwordx4 v[72:73], v[68:71], off
	ds_read_b128 v[68:71], v66 offset:8064
	v_or_b32_e32 v72, 56, v64
	v_ashrrev_i32_e32 v73, 31, v72
	v_lshlrev_b64 v[72:73], 13, v[72:73]
	v_lshl_add_u64 v[72:73], v[128:129], 0, v[72:73]
	s_waitcnt lgkmcnt(0)
	global_store_dwordx4 v[72:73], v[68:71], off
